# k17 plus: 60 GEMM LDS-DMA tile loads use SGPR base + 32-bit VGPR offset instead of a 64-bit VALU add
# baseline (speedup 1.0000x reference)
; #define PG8_STAGE(bufoff, gbase, voff) do { _Pragma("unroll") for (int _i = 0; _i < 2; ++_i) \
;         __builtin_amdgcn_global_load_lds((const unsigned*)((const char*)(gbase) + (voff)[_i]), (LAS unsigned*)(lds + (bufoff) + ldsw + _i * 8192), 16, 0, 0); } while (0)
; #define PG8_WAIT_V(n) asm volatile("s_waitcnt vmcnt(" #n ")" ::: "memory")
; #define PG8_BAR __builtin_amdgcn_s_barrier()
; template <class Epi, class Sched, bool ALIGN_EPI = true, bool SP2 = true>
; __device__ __forceinline__ void gemm_phase(LAS unsigned char* lds, const Gemm g, const Sched& S, const Epi& E) {
;     ...
;     const int aoff = lds_byte(wr * 64 + fr, fq * 8), boff = lds_byte(wc * 32 + fr, fq * 8);
;     ...
;     Unit cur, nxt; int ui = 0;
;     if (!S.next(0, cur)) return;
;     f32x4 acc[2][2][4][2];
; #pragma unroll
;     for (int a = 0; a < 2; ++a)
; #pragma unroll
;         for (int b = 0; b < 2; ++b)
; #pragma unroll
;             for (int m = 0; m < 4; ++m)
; #pragma unroll
;                 for (int n = 0; n < 2; ++n) acc[a][b][m][n] = (f32x4){0.f, 0.f, 0.f, 0.f};
;     bf16x8 At[4][2], B0[2][2], B1[2][2];
;     const char* cA = (const char*)g.A + (size_t)cur.pm * tstepA; const char* cB = (const char*)g.Bt + (size_t)cur.pn * tstepB;
;     if constexpr (SP2) {
;         PG8_STAGE(PG8_SB(0, 0), cB, voffB); PG8_STAGE(PG8_SB(0, 1), cB + hstepB, voffB); PG8_STAGE(PG8_SA(0, 0), cA, voffA); PG8_STAGE(PG8_SA(0, 1), cA + hstepA, voffA);
;         if (wr == 1) PG8_BAR;
;         PG8_WAIT_V(2); PG8_BAR;
;         PG8_STAGE(PG8_SB(1, 0), cB + kstep, voffB); PG8_STAGE(PG8_SA(1, 0), cA + kstep, voffA); PG8_STAGE(PG8_SB(1, 1), cB + hstepB + kstep, voffB);
;         PG8_WAIT_V(6); PG8_BAR;
.LBB0_199:
	s_lshl_b32 s54, -1, s52
	s_not_b32 s49, s54
	s_add_u32 s20, s20, 0x17e00000
	s_addc_u32 s21, s21, 0
	s_lshl_b32 s0, s0, 5
	s_and_b32 s47, s0, 0x60
	s_add_i32 m0, s64, 0x18000
	v_lshl_add_u64 v[8:9], v[8:9], 0, s[12:13]
	s_lshl_b32 s50, s2, 6
	s_lshl_b32 s2, s2, 13
	s_lshl_b32 s14, s47, 7
	s_waitcnt vmcnt(2)
	s_barrier
	global_load_lds_dwordx4 v[8:9], off
	v_lshl_add_u64 v[6:7], v[6:7], 0, s[12:13]
	s_add_i32 m0, s64, 0x1a000
	s_add_i32 s16, s64, 0x8000
	s_add_i32 s17, s64, 0xa000
	global_load_lds_dwordx4 v[6:7], off
	v_lshl_add_u64 v[2:3], v[2:3], 0, s[12:13]
	s_mov_b32 m0, s16
	s_add_u32 s8, s42, 0x40080
	global_load_lds_dwordx4 v[2:3], off
	v_lshl_add_u64 v[2:3], v[4:5], 0, s[12:13]
	s_mov_b32 m0, s17
	s_addc_u32 s9, s43, 0
	global_load_lds_dwordx4 v[2:3], off
	s_add_i32 m0, s64, 0x1c000
	s_nop 0
	global_load_lds_dwordx4 v0, s[8:9]
	v_lshl_add_u64 v[2:3], s[8:9], 0, v[130:131]
	s_add_i32 m0, s64, 0x1e000
	s_movk_i32 s8, 0x3c0
	global_load_lds_dwordx4 v[2:3], off
	v_and_b32_e32 v2, 48, v10
	v_lshlrev_b32_e32 v3, 6, v10
	v_and_or_b32 v2, v3, s8, v2
	v_lshlrev_b32_e32 v3, 2, v10
	v_and_b32_e32 v3, 32, v3
	v_bitop3_b32 v4, v2, s2, v3 bitop3:0xde
	v_bitop3_b32 v141, s14, v2, v3 bitop3:0xf6
	v_lshlrev_b32_e32 v2, 14, v15
	v_and_b32_e32 v2, 0xffff8000, v2
	v_lshl_add_u32 v2, v14, 11, v2
	v_and_b32_e32 v3, 1, v15
	v_lshl_or_b32 v2, v3, 6, v2
	v_lshl_add_u32 v136, v16, 1, v2
	v_lshlrev_b32_e32 v2, 14, v11
	v_and_b32_e32 v2, 0xffff8000, v2
	s_waitcnt vmcnt(6)
	v_lshl_add_u32 v2, v12, 11, v2
	v_and_b32_e32 v3, 1, v11
	s_cmpk_lt_u32 s1, 0x100
	v_lshl_or_b32 v2, v3, 6, v2
	s_sext_i32_i16 s0, s10
	s_cselect_b64 s[22:23], -1, 0
	s_ashr_i32 s10, s38, 31
	v_mov_b32_e32 v137, v1
	v_lshl_add_u32 v138, v13, 1, v2
	v_mov_b32_e32 v139, v1
	s_mov_b32 s14, 0
	v_add_u32_e32 v146, 0, v4
	s_barrier
	s_branch .LBB0_202

; #define PG8_STAGE(bufoff, gbase, voff) do { _Pragma("unroll") for (int _i = 0; _i < 2; ++_i) \
;         __builtin_amdgcn_global_load_lds((const unsigned*)((const char*)(gbase) + (voff)[_i]), (LAS unsigned*)(lds + (bufoff) + ldsw + _i * 8192), 16, 0, 0); } while (0)
; #define PG8_LDA(dst, b, h) do { _Pragma("unroll") for (int m = 0; m < 4; ++m) _Pragma("unroll") for (int k = 0; k < 2; ++k) dst[m][k] = *(const LAS bf16x8*)(lds + PG8_SA(b, h) + aoff + m * 2048 + k * 1024); } while (0)
; #define PG8_LDB(dst, b, h) do { _Pragma("unroll") for (int n = 0; n < 2; ++n) _Pragma("unroll") for (int k = 0; k < 2; ++k) dst[n][k] = *(const LAS bf16x8*)(lds + PG8_SB(b, h) + boff + n * 2048 + k * 1024); } while (0)
; #define PG8_MMA(ai, bj, At, Bt) do { __builtin_amdgcn_s_setprio(1); _Pragma("unroll") for (int m = 0; m < 4; ++m) _Pragma("unroll") for (int n = 0; n < 2; ++n) _Pragma("unroll") for (int k = 0; k < 2; ++k) \
;         acc[ai][bj][m][n] = __builtin_amdgcn_mfma_f32_16x16x32_bf16(Bt[n][k], At[m][k], acc[ai][bj][m][n], 0, 0, 0); __builtin_amdgcn_s_setprio(0); } while (0)
; #define PG8_WAIT_V(n) asm volatile("s_waitcnt vmcnt(" #n ")" ::: "memory")
; #define PG8_WAIT_L(n) asm volatile("s_waitcnt lgkmcnt(" #n ")" ::: "memory")
; #define PG8_BAR __builtin_amdgcn_s_barrier()
; #define PG8_SCHED __builtin_amdgcn_sched_barrier(0)
; template <class Epi, class Sched, bool ALIGN_EPI = true, bool SP2 = true>
; __device__ __forceinline__ void gemm_phase(LAS unsigned char* lds, const Gemm g, const Sched& S, const Epi& E) {
;     ...
;             PG8_LDB(B0, 0, 0); PG8_LDB(B1, 0, 1); PG8_SCHED; PG8_LDA(At, 0, 0); PG8_STAGE(PG8_SA(1, 1), a1 + hstepA, voffA);
;             PG8_WAIT_V(8); PG8_WAIT_L(0); PG8_BAR; PG8_MMA(0, 0, At, B0); PG8_MMA(0, 1, At, B1); PG8_BAR; PG8_SCHED;
;             PG8_LDA(At, 0, 1); PG8_STAGE(PG8_SB(0, 0), b2, voffB); PG8_STAGE(PG8_SB(0, 1), b2 + hstepB, voffB); PG8_STAGE(PG8_SA(0, 0), a2, voffA);
;             PG8_WAIT_V(8); PG8_WAIT_L(0); PG8_BAR; PG8_MMA(1, 0, At, B0); PG8_MMA(1, 1, At, B1); PG8_BAR; PG8_SCHED;
.LBB0_205:
	s_add_u32 s35, s36, 0xfffc0080
	s_addc_u32 s42, s37, -1
	s_add_i32 s58, 0, 0x10000
	s_cmp_eq_u32 s27, 12
	s_cselect_b32 s45, s1, s42
	s_cselect_b32 s44, s2, s35
	v_add_u32_e32 v140, s58, v141
	s_cselect_b32 s43, s8, s25
	s_cselect_b32 s42, s9, s15
	s_add_i32 s35, 0, 0x14000
	ds_read_b128 v[142:145], v140
	ds_read_b128 v[148:151], v140 offset:1024
	ds_read_b128 v[152:155], v140 offset:2048
	ds_read_b128 v[156:159], v140 offset:3072
	v_add_u32_e32 v140, s35, v141
	ds_read_b128 v[160:163], v140
	ds_read_b128 v[164:167], v140 offset:1024
	ds_read_b128 v[168:171], v140 offset:2048
	ds_read_b128 v[172:175], v140 offset:3072
	s_add_i32 m0, s64, 0xc000
	ds_read_b128 v[176:179], v146
	ds_read_b128 v[180:183], v146 offset:1024
	ds_read_b128 v[184:187], v146 offset:2048
	ds_read_b128 v[188:191], v146 offset:3072
	ds_read_b128 v[196:199], v146 offset:4096
	ds_read_b128 v[200:203], v146 offset:5120
	ds_read_b128 v[204:207], v146 offset:6144
	ds_read_b128 v[208:211], v146 offset:7168
	global_load_lds_dwordx4 v136, s[36:37]
	s_add_i32 m0, s64, 0xe000
	s_nop 0
	global_load_lds_dwordx4 v138, s[36:37]
	s_waitcnt vmcnt(8)
	s_waitcnt lgkmcnt(0)
	s_barrier
	s_setprio 1
	s_waitcnt lgkmcnt(0)
	v_mfma_f32_16x16x32_bf16 v[126:129], v[142:145], v[176:179], v[126:129]
	v_mfma_f32_16x16x32_bf16 v[122:125], v[152:155], v[176:179], v[122:125]
	v_mfma_f32_16x16x32_bf16 v[110:113], v[142:145], v[184:187], v[110:113]
	v_mfma_f32_16x16x32_bf16 v[106:109], v[152:155], v[184:187], v[106:109]
	v_mfma_f32_16x16x32_bf16 v[94:97], v[142:145], v[196:199], v[94:97]
	v_mfma_f32_16x16x32_bf16 v[90:93], v[152:155], v[196:199], v[90:93]
	v_mfma_f32_16x16x32_bf16 v[78:81], v[142:145], v[204:207], v[78:81]
	v_mfma_f32_16x16x32_bf16 v[74:77], v[152:155], v[204:207], v[74:77]
	v_mfma_f32_16x16x32_bf16 v[126:129], v[148:151], v[180:183], v[126:129]
	v_mfma_f32_16x16x32_bf16 v[122:125], v[156:159], v[180:183], v[122:125]
	v_mfma_f32_16x16x32_bf16 v[110:113], v[148:151], v[188:191], v[110:113]
	v_mfma_f32_16x16x32_bf16 v[106:109], v[156:159], v[188:191], v[106:109]
	v_mfma_f32_16x16x32_bf16 v[94:97], v[148:151], v[200:203], v[94:97]
	v_mfma_f32_16x16x32_bf16 v[90:93], v[156:159], v[200:203], v[90:93]
	v_mfma_f32_16x16x32_bf16 v[78:81], v[148:151], v[208:211], v[78:81]
	v_mfma_f32_16x16x32_bf16 v[74:77], v[156:159], v[208:211], v[74:77]
	s_setprio 0
	s_setprio 1
	v_mfma_f32_16x16x32_bf16 v[118:121], v[160:163], v[176:179], v[118:121]
	v_mfma_f32_16x16x32_bf16 v[114:117], v[168:171], v[176:179], v[114:117]
	v_mfma_f32_16x16x32_bf16 v[102:105], v[160:163], v[184:187], v[102:105]
	v_mfma_f32_16x16x32_bf16 v[98:101], v[168:171], v[184:187], v[98:101]
	v_mfma_f32_16x16x32_bf16 v[86:89], v[160:163], v[196:199], v[86:89]
	v_mfma_f32_16x16x32_bf16 v[82:85], v[168:171], v[196:199], v[82:85]
	v_mfma_f32_16x16x32_bf16 v[70:73], v[160:163], v[204:207], v[70:73]
	v_mfma_f32_16x16x32_bf16 v[66:69], v[168:171], v[204:207], v[66:69]
	v_mfma_f32_16x16x32_bf16 v[118:121], v[164:167], v[180:183], v[118:121]
	v_mfma_f32_16x16x32_bf16 v[114:117], v[172:175], v[180:183], v[114:117]
	v_mfma_f32_16x16x32_bf16 v[102:105], v[164:167], v[188:191], v[102:105]
	v_mfma_f32_16x16x32_bf16 v[98:101], v[172:175], v[188:191], v[98:101]
	v_mfma_f32_16x16x32_bf16 v[86:89], v[164:167], v[200:203], v[86:89]
	v_mfma_f32_16x16x32_bf16 v[82:85], v[172:175], v[200:203], v[82:85]
	v_mfma_f32_16x16x32_bf16 v[70:73], v[164:167], v[208:211], v[70:73]
	v_mfma_f32_16x16x32_bf16 v[66:69], v[172:175], v[208:211], v[66:69]
	s_setprio 0
	s_barrier
	s_add_i32 s58, s58, s62
	v_lshl_add_u64 v[212:213], s[42:43], 0, v[0:1]
	s_mov_b32 m0, s58
	ds_read_b128 v[176:179], v146 offset:16384
	ds_read_b128 v[180:183], v146 offset:17408
	ds_read_b128 v[184:187], v146 offset:18432
	ds_read_b128 v[188:191], v146 offset:19456
	ds_read_b128 v[196:199], v146 offset:20480
	ds_read_b128 v[200:203], v146 offset:21504
	ds_read_b128 v[204:207], v146 offset:22528
	ds_read_b128 v[208:211], v146 offset:23552
	global_load_lds_dwordx4 v[212:213], off
	s_add_i32 m0, s58, 0x2000
	s_add_u32 s58, s42, 0x40000
	v_lshl_add_u64 v[214:215], s[42:43], 0, v[130:131]
	s_addc_u32 s59, s43, 0
	s_add_i32 s35, s35, s62
	global_load_lds_dwordx4 v[214:215], off
	s_mov_b32 m0, s35
	v_lshl_add_u64 v[222:223], s[44:45], 0, v[132:133]
	global_load_lds_dwordx4 v0, s[58:59]
	s_add_i32 m0, s35, 0x2000
	s_nop 0
	global_load_lds_dwordx4 v130, s[58:59]
	v_lshl_add_u64 v[220:221], s[44:45], 0, v[134:135]
	s_mov_b32 m0, s64
	s_nop 0
	global_load_lds_dwordx4 v[220:221], off
	s_mov_b32 m0, s65
	s_nop 0
	global_load_lds_dwordx4 v[222:223], off
	s_waitcnt vmcnt(8)
	s_waitcnt lgkmcnt(0)
	s_barrier
; #define PG8_STAGE(bufoff, gbase, voff) do { _Pragma("unroll") for (int _i = 0; _i < 2; ++_i) \
;         __builtin_amdgcn_global_load_lds((const unsigned*)((const char*)(gbase) + (voff)[_i]), (LAS unsigned*)(lds + (bufoff) + ldsw + _i * 8192), 16, 0, 0); } while (0)
; #define PG8_LDA(dst, b, h) do { _Pragma("unroll") for (int m = 0; m < 4; ++m) _Pragma("unroll") for (int k = 0; k < 2; ++k) dst[m][k] = *(const LAS bf16x8*)(lds + PG8_SA(b, h) + aoff + m * 2048 + k * 1024); } while (0)
; #define PG8_LDB(dst, b, h) do { _Pragma("unroll") for (int n = 0; n < 2; ++n) _Pragma("unroll") for (int k = 0; k < 2; ++k) dst[n][k] = *(const LAS bf16x8*)(lds + PG8_SB(b, h) + boff + n * 2048 + k * 1024); } while (0)
; #define PG8_MMA(ai, bj, At, Bt) do { __builtin_amdgcn_s_setprio(1); _Pragma("unroll") for (int m = 0; m < 4; ++m) _Pragma("unroll") for (int n = 0; n < 2; ++n) _Pragma("unroll") for (int k = 0; k < 2; ++k) \
;         acc[ai][bj][m][n] = __builtin_amdgcn_mfma_f32_16x16x32_bf16(Bt[n][k], At[m][k], acc[ai][bj][m][n], 0, 0, 0); __builtin_amdgcn_s_setprio(0); } while (0)
; #define PG8_WAIT_V(n) asm volatile("s_waitcnt vmcnt(" #n ")" ::: "memory")
; #define PG8_WAIT_L(n) asm volatile("s_waitcnt lgkmcnt(" #n ")" ::: "memory")
; #define PG8_BAR __builtin_amdgcn_s_barrier()
; #define PG8_SCHED __builtin_amdgcn_sched_barrier(0)
; template <class Epi, class Sched, bool ALIGN_EPI = true, bool SP2 = true>
; __device__ __forceinline__ void gemm_phase(LAS unsigned char* lds, const Gemm g, const Sched& S, const Epi& E) {
;     ...
;             PG8_WAIT_V(8); PG8_WAIT_L(0); PG8_BAR; PG8_MMA(1, 0, At, B0); PG8_MMA(1, 1, At, B1); PG8_BAR; PG8_SCHED;
;             PG8_LDB(B0, 1, 0); PG8_LDB(B1, 1, 1); PG8_SCHED; PG8_LDA(At, 1, 0); PG8_STAGE(PG8_SA(0, 1), a2 + hstepA, voffA);
;             PG8_WAIT_V(8); PG8_WAIT_L(0); PG8_BAR; PG8_MMA(0, 0, At, B0); PG8_MMA(0, 1, At, B1); PG8_BAR; PG8_SCHED;
	s_setprio 1
	s_waitcnt lgkmcnt(0)
	v_mfma_f32_16x16x32_bf16 v[62:65], v[142:145], v[176:179], v[62:65]
	v_mfma_f32_16x16x32_bf16 v[58:61], v[152:155], v[176:179], v[58:61]
	v_mfma_f32_16x16x32_bf16 v[46:49], v[142:145], v[184:187], v[46:49]
	v_mfma_f32_16x16x32_bf16 v[42:45], v[152:155], v[184:187], v[42:45]
	v_mfma_f32_16x16x32_bf16 v[30:33], v[142:145], v[196:199], v[30:33]
	v_mfma_f32_16x16x32_bf16 v[26:29], v[152:155], v[196:199], v[26:29]
	v_mfma_f32_16x16x32_bf16 v[14:17], v[142:145], v[204:207], v[14:17]
	v_mfma_f32_16x16x32_bf16 v[10:13], v[152:155], v[204:207], v[10:13]
	v_mfma_f32_16x16x32_bf16 v[62:65], v[148:151], v[180:183], v[62:65]
	v_mfma_f32_16x16x32_bf16 v[58:61], v[156:159], v[180:183], v[58:61]
	v_mfma_f32_16x16x32_bf16 v[46:49], v[148:151], v[188:191], v[46:49]
	v_mfma_f32_16x16x32_bf16 v[42:45], v[156:159], v[188:191], v[42:45]
	v_mfma_f32_16x16x32_bf16 v[30:33], v[148:151], v[200:203], v[30:33]
	v_mfma_f32_16x16x32_bf16 v[26:29], v[156:159], v[200:203], v[26:29]
	v_mfma_f32_16x16x32_bf16 v[14:17], v[148:151], v[208:211], v[14:17]
	v_mfma_f32_16x16x32_bf16 v[10:13], v[156:159], v[208:211], v[10:13]
	s_setprio 0
	s_setprio 1
	v_mfma_f32_16x16x32_bf16 v[54:57], v[160:163], v[176:179], v[54:57]
	v_mfma_f32_16x16x32_bf16 v[50:53], v[168:171], v[176:179], v[50:53]
	v_mfma_f32_16x16x32_bf16 v[38:41], v[160:163], v[184:187], v[38:41]
	v_mfma_f32_16x16x32_bf16 v[34:37], v[168:171], v[184:187], v[34:37]
	v_mfma_f32_16x16x32_bf16 v[22:25], v[160:163], v[196:199], v[22:25]
	v_mfma_f32_16x16x32_bf16 v[18:21], v[168:171], v[196:199], v[18:21]
	v_mfma_f32_16x16x32_bf16 v[6:9], v[160:163], v[204:207], v[6:9]
	v_mfma_f32_16x16x32_bf16 v[2:5], v[168:171], v[204:207], v[2:5]
	v_mfma_f32_16x16x32_bf16 v[54:57], v[164:167], v[180:183], v[54:57]
	v_mfma_f32_16x16x32_bf16 v[50:53], v[172:175], v[180:183], v[50:53]
	v_mfma_f32_16x16x32_bf16 v[38:41], v[164:167], v[188:191], v[38:41]
	v_mfma_f32_16x16x32_bf16 v[34:37], v[172:175], v[188:191], v[34:37]
	v_mfma_f32_16x16x32_bf16 v[22:25], v[164:167], v[200:203], v[22:25]
	v_mfma_f32_16x16x32_bf16 v[18:21], v[172:175], v[200:203], v[18:21]
	v_mfma_f32_16x16x32_bf16 v[6:9], v[164:167], v[208:211], v[6:9]
	v_mfma_f32_16x16x32_bf16 v[2:5], v[172:175], v[208:211], v[2:5]
	s_setprio 0
	s_barrier
	s_add_i32 s35, 0, 0x18000
	v_add_u32_e32 v140, s35, v141
	s_add_i32 s58, 0, 0x1c000
	ds_read_b128 v[142:145], v140
	ds_read_b128 v[148:151], v140 offset:1024
	ds_read_b128 v[152:155], v140 offset:2048
	ds_read_b128 v[156:159], v140 offset:3072
	v_add_u32_e32 v140, s58, v141
	ds_read_b128 v[160:163], v140
	ds_read_b128 v[164:167], v140 offset:1024
	ds_read_b128 v[168:171], v140 offset:2048
	ds_read_b128 v[172:175], v140 offset:3072
	s_add_u32 s44, s44, 0x40000
	s_addc_u32 s45, s45, 0
	s_mov_b32 m0, s46
	ds_read_b128 v[176:179], v146 offset:32768
	ds_read_b128 v[180:183], v146 offset:33792
	ds_read_b128 v[184:187], v146 offset:34816
	ds_read_b128 v[188:191], v146 offset:35840
	ds_read_b128 v[196:199], v146 offset:36864
	ds_read_b128 v[200:203], v146 offset:37888
	ds_read_b128 v[204:207], v146 offset:38912
	ds_read_b128 v[208:211], v146 offset:39936
	global_load_lds_dwordx4 v134, s[44:45]
	v_lshl_add_u64 v[224:225], s[44:45], 0, v[132:133]
	s_mov_b32 m0, s51
	s_nop 0
	global_load_lds_dwordx4 v[224:225], off
	s_waitcnt vmcnt(8)
	s_waitcnt lgkmcnt(0)
	s_barrier
	s_setprio 1
	s_waitcnt lgkmcnt(0)
	v_mfma_f32_16x16x32_bf16 v[126:129], v[142:145], v[176:179], v[126:129]
	v_mfma_f32_16x16x32_bf16 v[122:125], v[152:155], v[176:179], v[122:125]
	v_mfma_f32_16x16x32_bf16 v[110:113], v[142:145], v[184:187], v[110:113]
	v_mfma_f32_16x16x32_bf16 v[106:109], v[152:155], v[184:187], v[106:109]
	v_mfma_f32_16x16x32_bf16 v[94:97], v[142:145], v[196:199], v[94:97]
	v_mfma_f32_16x16x32_bf16 v[90:93], v[152:155], v[196:199], v[90:93]
	v_mfma_f32_16x16x32_bf16 v[78:81], v[142:145], v[204:207], v[78:81]
	v_mfma_f32_16x16x32_bf16 v[74:77], v[152:155], v[204:207], v[74:77]
	v_mfma_f32_16x16x32_bf16 v[126:129], v[148:151], v[180:183], v[126:129]
	v_mfma_f32_16x16x32_bf16 v[122:125], v[156:159], v[180:183], v[122:125]
	v_mfma_f32_16x16x32_bf16 v[110:113], v[148:151], v[188:191], v[110:113]
	v_mfma_f32_16x16x32_bf16 v[106:109], v[156:159], v[188:191], v[106:109]
	v_mfma_f32_16x16x32_bf16 v[94:97], v[148:151], v[200:203], v[94:97]
	v_mfma_f32_16x16x32_bf16 v[90:93], v[156:159], v[200:203], v[90:93]
	v_mfma_f32_16x16x32_bf16 v[78:81], v[148:151], v[208:211], v[78:81]
	v_mfma_f32_16x16x32_bf16 v[74:77], v[156:159], v[208:211], v[74:77]
	s_setprio 0
	s_setprio 1
	v_mfma_f32_16x16x32_bf16 v[118:121], v[160:163], v[176:179], v[118:121]
	v_mfma_f32_16x16x32_bf16 v[114:117], v[168:171], v[176:179], v[114:117]
	v_mfma_f32_16x16x32_bf16 v[102:105], v[160:163], v[184:187], v[102:105]
	v_mfma_f32_16x16x32_bf16 v[98:101], v[168:171], v[184:187], v[98:101]
	v_mfma_f32_16x16x32_bf16 v[86:89], v[160:163], v[196:199], v[86:89]
	v_mfma_f32_16x16x32_bf16 v[82:85], v[168:171], v[196:199], v[82:85]
	v_mfma_f32_16x16x32_bf16 v[70:73], v[160:163], v[204:207], v[70:73]
	v_mfma_f32_16x16x32_bf16 v[66:69], v[168:171], v[204:207], v[66:69]
	v_mfma_f32_16x16x32_bf16 v[118:121], v[164:167], v[180:183], v[118:121]
	v_mfma_f32_16x16x32_bf16 v[114:117], v[172:175], v[180:183], v[114:117]
	v_mfma_f32_16x16x32_bf16 v[102:105], v[164:167], v[188:191], v[102:105]
	v_mfma_f32_16x16x32_bf16 v[98:101], v[172:175], v[188:191], v[98:101]
	v_mfma_f32_16x16x32_bf16 v[86:89], v[164:167], v[200:203], v[86:89]
	v_mfma_f32_16x16x32_bf16 v[82:85], v[172:175], v[200:203], v[82:85]
	v_mfma_f32_16x16x32_bf16 v[70:73], v[164:167], v[208:211], v[70:73]
	v_mfma_f32_16x16x32_bf16 v[66:69], v[172:175], v[208:211], v[66:69]
	s_setprio 0
	s_barrier
; #define PG8_STAGE(bufoff, gbase, voff) do { _Pragma("unroll") for (int _i = 0; _i < 2; ++_i) \
;         __builtin_amdgcn_global_load_lds((const unsigned*)((const char*)(gbase) + (voff)[_i]), (LAS unsigned*)(lds + (bufoff) + ldsw + _i * 8192), 16, 0, 0); } while (0)
; #define PG8_LDA(dst, b, h) do { _Pragma("unroll") for (int m = 0; m < 4; ++m) _Pragma("unroll") for (int k = 0; k < 2; ++k) dst[m][k] = *(const LAS bf16x8*)(lds + PG8_SA(b, h) + aoff + m * 2048 + k * 1024); } while (0)
; #define PG8_MMA(ai, bj, At, Bt) do { __builtin_amdgcn_s_setprio(1); _Pragma("unroll") for (int m = 0; m < 4; ++m) _Pragma("unroll") for (int n = 0; n < 2; ++n) _Pragma("unroll") for (int k = 0; k < 2; ++k) \
;         acc[ai][bj][m][n] = __builtin_amdgcn_mfma_f32_16x16x32_bf16(Bt[n][k], At[m][k], acc[ai][bj][m][n], 0, 0, 0); __builtin_amdgcn_s_setprio(0); } while (0)
; #define PG8_WAIT_V(n) asm volatile("s_waitcnt vmcnt(" #n ")" ::: "memory")
; #define PG8_WAIT_L(n) asm volatile("s_waitcnt lgkmcnt(" #n ")" ::: "memory")
; #define PG8_BAR __builtin_amdgcn_s_barrier()
; #define PG8_SCHED __builtin_amdgcn_sched_barrier(0)
; template <class Epi, class Sched, bool ALIGN_EPI = true, bool SP2 = true>
; __device__ __forceinline__ void gemm_phase(LAS unsigned char* lds, const Gemm g, const Sched& S, const Epi& E) {
;     ...
;             PG8_WAIT_V(8); PG8_WAIT_L(0); PG8_BAR; PG8_MMA(0, 0, At, B0); PG8_MMA(0, 1, At, B1); PG8_BAR; PG8_SCHED;
;             PG8_LDA(At, 1, 1); PG8_STAGE(PG8_SB(1, 0), b3, voffB); PG8_STAGE(PG8_SB(1, 1), b3 + hstepB, voffB); PG8_STAGE(PG8_SA(1, 0), a3, voffA);
;             PG8_WAIT_V(8); PG8_WAIT_L(0); PG8_BAR; PG8_MMA(1, 0, At, B0); PG8_MMA(1, 1, At, B1); PG8_BAR; PG8_SCHED;
;         }
;         if constexpr (ALIGN_EPI) { if (wr == 0) PG8_BAR; }
	s_add_i32 s35, s35, s62
	v_lshl_add_u64 v[212:213], v[212:213], 0, s[12:13]
	s_mov_b32 m0, s35
	ds_read_b128 v[176:179], v146 offset:49152
	ds_read_b128 v[180:183], v146 offset:50176
	ds_read_b128 v[184:187], v146 offset:51200
	ds_read_b128 v[188:191], v146 offset:52224
	ds_read_b128 v[196:199], v146 offset:53248
	ds_read_b128 v[200:203], v146 offset:54272
	ds_read_b128 v[204:207], v146 offset:55296
	ds_read_b128 v[208:211], v146 offset:56320
	global_load_lds_dwordx4 v[212:213], off
	s_add_i32 m0, s35, 0x2000
	s_add_u32 s42, s42, 0x40080
	v_lshl_add_u64 v[212:213], v[214:215], 0, s[12:13]
	s_addc_u32 s43, s43, 0
	s_add_i32 s35, s58, s62
	global_load_lds_dwordx4 v[212:213], off
	s_mov_b32 m0, s35
	s_nop 0
	global_load_lds_dwordx4 v0, s[42:43]
	v_lshl_add_u64 v[212:213], s[42:43], 0, v[130:131]
	s_add_i32 m0, s35, 0x2000
	s_nop 0
	global_load_lds_dwordx4 v[212:213], off
	v_lshl_add_u64 v[212:213], v[220:221], 0, s[12:13]
	s_mov_b32 m0, s16
	s_nop 0
	global_load_lds_dwordx4 v[212:213], off
	v_lshl_add_u64 v[212:213], v[222:223], 0, s[12:13]
	s_mov_b32 m0, s17
	s_nop 0
	global_load_lds_dwordx4 v[212:213], off
	s_waitcnt vmcnt(8)
	s_waitcnt lgkmcnt(0)
	s_barrier
	s_setprio 1
	s_waitcnt lgkmcnt(0)
	v_mfma_f32_16x16x32_bf16 v[62:65], v[142:145], v[176:179], v[62:65]
	v_mfma_f32_16x16x32_bf16 v[58:61], v[152:155], v[176:179], v[58:61]
	v_mfma_f32_16x16x32_bf16 v[46:49], v[142:145], v[184:187], v[46:49]
	v_mfma_f32_16x16x32_bf16 v[42:45], v[152:155], v[184:187], v[42:45]
	v_mfma_f32_16x16x32_bf16 v[30:33], v[142:145], v[196:199], v[30:33]
	v_mfma_f32_16x16x32_bf16 v[26:29], v[152:155], v[196:199], v[26:29]
	v_mfma_f32_16x16x32_bf16 v[14:17], v[142:145], v[204:207], v[14:17]
	v_mfma_f32_16x16x32_bf16 v[10:13], v[152:155], v[204:207], v[10:13]
	v_mfma_f32_16x16x32_bf16 v[62:65], v[148:151], v[180:183], v[62:65]
	v_mfma_f32_16x16x32_bf16 v[58:61], v[156:159], v[180:183], v[58:61]
	v_mfma_f32_16x16x32_bf16 v[46:49], v[148:151], v[188:191], v[46:49]
	v_mfma_f32_16x16x32_bf16 v[42:45], v[156:159], v[188:191], v[42:45]
	v_mfma_f32_16x16x32_bf16 v[30:33], v[148:151], v[200:203], v[30:33]
	v_mfma_f32_16x16x32_bf16 v[26:29], v[156:159], v[200:203], v[26:29]
	v_mfma_f32_16x16x32_bf16 v[14:17], v[148:151], v[208:211], v[14:17]
	v_mfma_f32_16x16x32_bf16 v[10:13], v[156:159], v[208:211], v[10:13]
	s_setprio 0
	s_setprio 1
	v_mfma_f32_16x16x32_bf16 v[54:57], v[160:163], v[176:179], v[54:57]
	v_mfma_f32_16x16x32_bf16 v[50:53], v[168:171], v[176:179], v[50:53]
	v_mfma_f32_16x16x32_bf16 v[38:41], v[160:163], v[184:187], v[38:41]
	v_mfma_f32_16x16x32_bf16 v[34:37], v[168:171], v[184:187], v[34:37]
	v_mfma_f32_16x16x32_bf16 v[22:25], v[160:163], v[196:199], v[22:25]
	v_mfma_f32_16x16x32_bf16 v[18:21], v[168:171], v[196:199], v[18:21]
	v_mfma_f32_16x16x32_bf16 v[6:9], v[160:163], v[204:207], v[6:9]
	v_mfma_f32_16x16x32_bf16 v[2:5], v[168:171], v[204:207], v[2:5]
	v_mfma_f32_16x16x32_bf16 v[54:57], v[164:167], v[180:183], v[54:57]
	v_mfma_f32_16x16x32_bf16 v[50:53], v[172:175], v[180:183], v[50:53]
	v_mfma_f32_16x16x32_bf16 v[38:41], v[164:167], v[188:191], v[38:41]
	v_mfma_f32_16x16x32_bf16 v[34:37], v[172:175], v[188:191], v[34:37]
	v_mfma_f32_16x16x32_bf16 v[22:25], v[164:167], v[200:203], v[22:25]
	v_mfma_f32_16x16x32_bf16 v[18:21], v[172:175], v[200:203], v[18:21]
	v_mfma_f32_16x16x32_bf16 v[6:9], v[164:167], v[208:211], v[6:9]
	v_mfma_f32_16x16x32_bf16 v[2:5], v[172:175], v[208:211], v[2:5]
	s_setprio 0
	s_barrier
	s_add_i32 s27, s27, 2
	s_add_u32 s36, s36, 0x100
	s_addc_u32 s37, s37, 0
	s_add_u32 s15, s15, 0x100
	s_addc_u32 s25, s25, 0
	s_cmp_gt_u32 s27, 13
	s_cbranch_scc0 .LBB0_205
	s_and_b64 vcc, exec, s[22:23]
	s_cbranch_vccz .LBB0_208
	s_barrier

; #define PG8_STAGE(bufoff, gbase, voff) do { _Pragma("unroll") for (int _i = 0; _i < 2; ++_i) \
;         __builtin_amdgcn_global_load_lds((const unsigned*)((const char*)(gbase) + (voff)[_i]), (LAS unsigned*)(lds + (bufoff) + ldsw + _i * 8192), 16, 0, 0); } while (0)
; #define PG8_WAIT_V(n) asm volatile("s_waitcnt vmcnt(" #n ")" ::: "memory")
; #define PG8_BAR __builtin_amdgcn_s_barrier()
; template <class Epi, class Sched, bool ALIGN_EPI = true, bool SP2 = true>
; __device__ __forceinline__ void gemm_phase(LAS unsigned char* lds, const Gemm g, const Sched& S, const Epi& E) {
;     ...
;     const int aoff = lds_byte(wr * 64 + fr, fq * 8), boff = lds_byte(wc * 32 + fr, fq * 8);
;     ...
;     Unit cur, nxt; int ui = 0;
;     if (!S.next(0, cur)) return;
;     f32x4 acc[2][2][4][2];
; #pragma unroll
;     for (int a = 0; a < 2; ++a)
; #pragma unroll
;         for (int b = 0; b < 2; ++b)
; #pragma unroll
;             for (int m = 0; m < 4; ++m)
; #pragma unroll
;                 for (int n = 0; n < 2; ++n) acc[a][b][m][n] = (f32x4){0.f, 0.f, 0.f, 0.f};
;     bf16x8 At[4][2], B0[2][2], B1[2][2];
;     const char* cA = (const char*)g.A + (size_t)cur.pm * tstepA; const char* cB = (const char*)g.Bt + (size_t)cur.pn * tstepB;
;     if constexpr (SP2) {
;         PG8_STAGE(PG8_SB(0, 0), cB, voffB); PG8_STAGE(PG8_SB(0, 1), cB + hstepB, voffB); PG8_STAGE(PG8_SA(0, 0), cA, voffA); PG8_STAGE(PG8_SA(0, 1), cA + hstepA, voffA);
;         if (wr == 1) PG8_BAR;
;         PG8_WAIT_V(2); PG8_BAR;
;         PG8_STAGE(PG8_SB(1, 0), cB + kstep, voffB); PG8_STAGE(PG8_SA(1, 0), cA + kstep, voffA); PG8_STAGE(PG8_SB(1, 1), cB + hstepB + kstep, voffB);
;         PG8_WAIT_V(6); PG8_BAR;
.LBB0_452:
	s_add_u32 s34, s34, 0xde00000
	s_sext_i32_i8 s17, s10
	s_addc_u32 s35, s35, 0
	s_lshl_b32 s9, s23, 6
	v_and_b32_e32 v15, 48, v14
	s_lshl_b32 s10, s23, 13
	v_lshlrev_b32_e32 v20, 6, v14
	s_movk_i32 s23, 0x3c0
	v_lshlrev_b32_e32 v14, 2, v14
	v_and_or_b32 v15, v20, s23, v15
	v_and_b32_e32 v14, 32, v14
	v_bitop3_b32 v20, v15, s10, v14 bitop3:0xde
	s_lshl_b32 s10, s22, 5
	s_and_b32 s10, s10, 0x60
	s_add_i32 m0, s53, 0x18000
	v_lshl_add_u64 v[6:7], v[6:7], 0, s[14:15]
	s_lshl_b32 s22, s10, 7
	s_waitcnt vmcnt(2)
	s_barrier
	global_load_lds_dwordx4 v[6:7], off
	v_lshl_add_u64 v[4:5], v[4:5], 0, s[14:15]
	s_add_i32 m0, s53, 0x1a000
	s_add_i32 s54, s53, 0x8000
	s_add_i32 s55, s53, 0xa000
	v_bitop3_b32 v144, s22, v15, v14 bitop3:0xf6
	global_load_lds_dwordx4 v[4:5], off
	v_lshl_add_u64 v[0:1], v[0:1], 0, s[14:15]
	s_mov_b32 m0, s54
	s_add_u32 s22, s18, 0x40080
	global_load_lds_dwordx4 v[0:1], off
	v_lshl_add_u64 v[0:1], v[2:3], 0, s[14:15]
	s_mov_b32 m0, s55
	s_addc_u32 s23, s19, 0
	global_load_lds_dwordx4 v[0:1], off
	s_add_i32 m0, s53, 0x1c000
	s_nop 0
	global_load_lds_dwordx4 v18, s[22:23]
	s_add_i32 m0, s53, 0x1e000
	s_cmpk_lt_u32 s2, 0x100
	global_load_lds_dwordx4 v16, s[22:23]
	v_lshlrev_b32_e32 v0, 14, v12
	v_and_b32_e32 v0, 0xffff8000, v0
	v_lshl_add_u32 v0, v11, 11, v0
	v_and_b32_e32 v1, 1, v12
	v_lshl_or_b32 v0, v1, 6, v0
	v_lshl_add_u32 v136, v13, 1, v0
	v_lshlrev_b32_e32 v0, 14, v8
	v_and_b32_e32 v0, 0xffff8000, v0
	s_waitcnt vmcnt(6)
	v_lshl_add_u32 v0, v9, 11, v0
	v_and_b32_e32 v1, 1, v8
	v_lshl_or_b32 v0, v1, 6, v0
	s_cselect_b64 s[36:37], -1, 0
	s_ashr_i32 s56, s25, 31
	v_mov_b32_e32 v137, v19
	v_lshl_add_u32 v138, v10, 1, v0
	v_mov_b32_e32 v139, v19
	s_mov_b32 s57, 0
	v_add_u32_e32 v145, 0, v20
	s_barrier
	s_waitcnt vmcnt(0)
	s_branch .LBB0_455

; #define PG8_STAGE(bufoff, gbase, voff) do { _Pragma("unroll") for (int _i = 0; _i < 2; ++_i) \
;         __builtin_amdgcn_global_load_lds((const unsigned*)((const char*)(gbase) + (voff)[_i]), (LAS unsigned*)(lds + (bufoff) + ldsw + _i * 8192), 16, 0, 0); } while (0)
; #define PG8_LDA(dst, b, h) do { _Pragma("unroll") for (int m = 0; m < 4; ++m) _Pragma("unroll") for (int k = 0; k < 2; ++k) dst[m][k] = *(const LAS bf16x8*)(lds + PG8_SA(b, h) + aoff + m * 2048 + k * 1024); } while (0)
; #define PG8_LDB(dst, b, h) do { _Pragma("unroll") for (int n = 0; n < 2; ++n) _Pragma("unroll") for (int k = 0; k < 2; ++k) dst[n][k] = *(const LAS bf16x8*)(lds + PG8_SB(b, h) + boff + n * 2048 + k * 1024); } while (0)
; #define PG8_MMA(ai, bj, At, Bt) do { __builtin_amdgcn_s_setprio(1); _Pragma("unroll") for (int m = 0; m < 4; ++m) _Pragma("unroll") for (int n = 0; n < 2; ++n) _Pragma("unroll") for (int k = 0; k < 2; ++k) \
;         acc[ai][bj][m][n] = __builtin_amdgcn_mfma_f32_16x16x32_bf16(Bt[n][k], At[m][k], acc[ai][bj][m][n], 0, 0, 0); __builtin_amdgcn_s_setprio(0); } while (0)
; #define PG8_WAIT_V(n) asm volatile("s_waitcnt vmcnt(" #n ")" ::: "memory")
; #define PG8_WAIT_L(n) asm volatile("s_waitcnt lgkmcnt(" #n ")" ::: "memory")
; #define PG8_BAR __builtin_amdgcn_s_barrier()
; #define PG8_SCHED __builtin_amdgcn_sched_barrier(0)
; template <class Epi, class Sched, bool ALIGN_EPI = true, bool SP2 = true>
; __device__ __forceinline__ void gemm_phase(LAS unsigned char* lds, const Gemm g, const Sched& S, const Epi& E) {
;     ...
;             PG8_LDB(B0, 0, 0); PG8_LDB(B1, 0, 1); PG8_SCHED; PG8_LDA(At, 0, 0); PG8_STAGE(PG8_SA(1, 1), a1 + hstepA, voffA);
;             PG8_WAIT_V(8); PG8_WAIT_L(0); PG8_BAR; PG8_MMA(0, 0, At, B0); PG8_MMA(0, 1, At, B1); PG8_BAR; PG8_SCHED;
;             PG8_LDA(At, 0, 1); PG8_STAGE(PG8_SB(0, 0), b2, voffB); PG8_STAGE(PG8_SB(0, 1), b2 + hstepB, voffB); PG8_STAGE(PG8_SA(0, 0), a2, voffA);
;             PG8_WAIT_V(8); PG8_WAIT_L(0); PG8_BAR; PG8_MMA(1, 0, At, B0); PG8_MMA(1, 1, At, B1); PG8_BAR; PG8_SCHED;
.LBB0_458:
	s_add_u32 s18, s50, 0xfffc0080
	s_addc_u32 s19, s51, -1
	s_add_i32 s58, 0, 0x10000
	s_cmp_eq_u32 s60, 12
	s_cselect_b32 s21, s22, s19
	s_cselect_b32 s20, s23, s18
	v_add_u32_e32 v146, s58, v144
	s_cselect_b32 s19, s2, s45
	s_cselect_b32 s18, s43, s30
	s_add_i32 s61, 0, 0x14000
	ds_read_b128 v[140:143], v146
	ds_read_b128 v[164:167], v146 offset:1024
	ds_read_b128 v[168:171], v146 offset:2048
	ds_read_b128 v[172:175], v146 offset:3072
	v_add_u32_e32 v146, s61, v144
	ds_read_b128 v[198:201], v146
	ds_read_b128 v[202:205], v146 offset:1024
	ds_read_b128 v[206:209], v146 offset:2048
	ds_read_b128 v[210:213], v146 offset:3072
	s_add_i32 m0, s53, 0xc000
	ds_read_b128 v[218:221], v145
	ds_read_b128 v[222:225], v145 offset:1024
	ds_read_b128 v[226:229], v145 offset:2048
	ds_read_b128 v[230:233], v145 offset:3072
	ds_read_b128 v[234:237], v145 offset:4096
	ds_read_b128 v[238:241], v145 offset:5120
	ds_read_b128 v[242:245], v145 offset:6144
	ds_read_b128 v[246:249], v145 offset:7168
	global_load_lds_dwordx4 v136, s[50:51]
	s_add_i32 m0, s53, 0xe000
	s_nop 0
	global_load_lds_dwordx4 v138, s[50:51]
	s_waitcnt vmcnt(8)
	s_waitcnt lgkmcnt(0)
	s_barrier
	s_setprio 1
	s_waitcnt lgkmcnt(0)
	v_mfma_f32_16x16x32_bf16 v[128:131], v[140:143], v[218:221], v[128:131]
	v_mfma_f32_16x16x32_bf16 v[124:127], v[168:171], v[218:221], v[124:127]
	v_mfma_f32_16x16x32_bf16 v[120:123], v[140:143], v[226:229], v[120:123]
	v_mfma_f32_16x16x32_bf16 v[112:115], v[168:171], v[226:229], v[112:115]
	v_mfma_f32_16x16x32_bf16 v[104:107], v[140:143], v[234:237], v[104:107]
	v_mfma_f32_16x16x32_bf16 v[96:99], v[168:171], v[234:237], v[96:99]
	v_mfma_f32_16x16x32_bf16 v[88:91], v[140:143], v[242:245], v[88:91]
	v_mfma_f32_16x16x32_bf16 v[80:83], v[168:171], v[242:245], v[80:83]
	v_mfma_f32_16x16x32_bf16 v[128:131], v[164:167], v[222:225], v[128:131]
	v_mfma_f32_16x16x32_bf16 v[124:127], v[172:175], v[222:225], v[124:127]
	v_mfma_f32_16x16x32_bf16 v[120:123], v[164:167], v[230:233], v[120:123]
	v_mfma_f32_16x16x32_bf16 v[112:115], v[172:175], v[230:233], v[112:115]
	v_mfma_f32_16x16x32_bf16 v[104:107], v[164:167], v[238:241], v[104:107]
	v_mfma_f32_16x16x32_bf16 v[96:99], v[172:175], v[238:241], v[96:99]
	v_mfma_f32_16x16x32_bf16 v[88:91], v[164:167], v[246:249], v[88:91]
	v_mfma_f32_16x16x32_bf16 v[80:83], v[172:175], v[246:249], v[80:83]
	s_setprio 0
	s_setprio 1
	v_mfma_f32_16x16x32_bf16 v[116:119], v[198:201], v[218:221], v[116:119]
	v_mfma_f32_16x16x32_bf16 v[108:111], v[206:209], v[218:221], v[108:111]
	v_mfma_f32_16x16x32_bf16 v[100:103], v[198:201], v[226:229], v[100:103]
	v_mfma_f32_16x16x32_bf16 v[92:95], v[206:209], v[226:229], v[92:95]
	v_mfma_f32_16x16x32_bf16 v[84:87], v[198:201], v[234:237], v[84:87]
	v_mfma_f32_16x16x32_bf16 v[76:79], v[206:209], v[234:237], v[76:79]
	v_mfma_f32_16x16x32_bf16 v[72:75], v[198:201], v[242:245], v[72:75]
	v_mfma_f32_16x16x32_bf16 v[68:71], v[206:209], v[242:245], v[68:71]
	v_mfma_f32_16x16x32_bf16 v[116:119], v[202:205], v[222:225], v[116:119]
	v_mfma_f32_16x16x32_bf16 v[108:111], v[210:213], v[222:225], v[108:111]
	v_mfma_f32_16x16x32_bf16 v[100:103], v[202:205], v[230:233], v[100:103]
	v_mfma_f32_16x16x32_bf16 v[92:95], v[210:213], v[230:233], v[92:95]
	v_mfma_f32_16x16x32_bf16 v[84:87], v[202:205], v[238:241], v[84:87]
	v_mfma_f32_16x16x32_bf16 v[76:79], v[210:213], v[238:241], v[76:79]
	v_mfma_f32_16x16x32_bf16 v[72:75], v[202:205], v[246:249], v[72:75]
	v_mfma_f32_16x16x32_bf16 v[68:71], v[210:213], v[246:249], v[68:71]
	s_setprio 0
	s_barrier
	s_add_i32 s58, s58, s39
	v_lshl_add_u64 v[146:147], s[18:19], 0, v[18:19]
	s_mov_b32 m0, s58
	ds_read_b128 v[218:221], v145 offset:16384
	ds_read_b128 v[222:225], v145 offset:17408
	ds_read_b128 v[226:229], v145 offset:18432
	ds_read_b128 v[230:233], v145 offset:19456
	ds_read_b128 v[234:237], v145 offset:20480
	ds_read_b128 v[238:241], v145 offset:21504
	ds_read_b128 v[242:245], v145 offset:22528
	ds_read_b128 v[246:249], v145 offset:23552
	global_load_lds_dwordx4 v[146:147], off
	s_add_i32 m0, s58, 0x2000
	s_add_u32 s58, s18, 0x40000
	v_lshl_add_u64 v[148:149], s[18:19], 0, v[16:17]
	s_addc_u32 s59, s19, 0
	s_add_i32 s61, s61, s39
	global_load_lds_dwordx4 v[148:149], off
	s_mov_b32 m0, s61
	v_lshl_add_u64 v[152:153], s[20:21], 0, v[132:133]
	global_load_lds_dwordx4 v18, s[58:59]
	s_add_i32 m0, s61, 0x2000
	s_nop 0
	global_load_lds_dwordx4 v16, s[58:59]
	v_lshl_add_u64 v[150:151], s[20:21], 0, v[134:135]
	s_mov_b32 m0, s53
	s_nop 0
	global_load_lds_dwordx4 v[150:151], off
	s_mov_b32 m0, s0
	s_nop 0
	global_load_lds_dwordx4 v[152:153], off
	s_waitcnt vmcnt(8)
	s_waitcnt lgkmcnt(0)
	s_barrier
; #define PG8_STAGE(bufoff, gbase, voff) do { _Pragma("unroll") for (int _i = 0; _i < 2; ++_i) \
;         __builtin_amdgcn_global_load_lds((const unsigned*)((const char*)(gbase) + (voff)[_i]), (LAS unsigned*)(lds + (bufoff) + ldsw + _i * 8192), 16, 0, 0); } while (0)
; #define PG8_LDA(dst, b, h) do { _Pragma("unroll") for (int m = 0; m < 4; ++m) _Pragma("unroll") for (int k = 0; k < 2; ++k) dst[m][k] = *(const LAS bf16x8*)(lds + PG8_SA(b, h) + aoff + m * 2048 + k * 1024); } while (0)
; #define PG8_LDB(dst, b, h) do { _Pragma("unroll") for (int n = 0; n < 2; ++n) _Pragma("unroll") for (int k = 0; k < 2; ++k) dst[n][k] = *(const LAS bf16x8*)(lds + PG8_SB(b, h) + boff + n * 2048 + k * 1024); } while (0)
; #define PG8_MMA(ai, bj, At, Bt) do { __builtin_amdgcn_s_setprio(1); _Pragma("unroll") for (int m = 0; m < 4; ++m) _Pragma("unroll") for (int n = 0; n < 2; ++n) _Pragma("unroll") for (int k = 0; k < 2; ++k) \
;         acc[ai][bj][m][n] = __builtin_amdgcn_mfma_f32_16x16x32_bf16(Bt[n][k], At[m][k], acc[ai][bj][m][n], 0, 0, 0); __builtin_amdgcn_s_setprio(0); } while (0)
; #define PG8_WAIT_V(n) asm volatile("s_waitcnt vmcnt(" #n ")" ::: "memory")
; #define PG8_WAIT_L(n) asm volatile("s_waitcnt lgkmcnt(" #n ")" ::: "memory")
; #define PG8_BAR __builtin_amdgcn_s_barrier()
; #define PG8_SCHED __builtin_amdgcn_sched_barrier(0)
; template <class Epi, class Sched, bool ALIGN_EPI = true, bool SP2 = true>
; __device__ __forceinline__ void gemm_phase(LAS unsigned char* lds, const Gemm g, const Sched& S, const Epi& E) {
;     ...
;             PG8_WAIT_V(8); PG8_WAIT_L(0); PG8_BAR; PG8_MMA(1, 0, At, B0); PG8_MMA(1, 1, At, B1); PG8_BAR; PG8_SCHED;
;             PG8_LDB(B0, 1, 0); PG8_LDB(B1, 1, 1); PG8_SCHED; PG8_LDA(At, 1, 0); PG8_STAGE(PG8_SA(0, 1), a2 + hstepA, voffA);
;             PG8_WAIT_V(8); PG8_WAIT_L(0); PG8_BAR; PG8_MMA(0, 0, At, B0); PG8_MMA(0, 1, At, B1); PG8_BAR; PG8_SCHED;
	s_setprio 1
	s_waitcnt lgkmcnt(0)
	v_mfma_f32_16x16x32_bf16 v[64:67], v[140:143], v[218:221], v[64:67]
	v_mfma_f32_16x16x32_bf16 v[60:63], v[168:171], v[218:221], v[60:63]
	v_mfma_f32_16x16x32_bf16 v[56:59], v[140:143], v[226:229], v[56:59]
	v_mfma_f32_16x16x32_bf16 v[48:51], v[168:171], v[226:229], v[48:51]
	v_mfma_f32_16x16x32_bf16 v[40:43], v[140:143], v[234:237], v[40:43]
	v_mfma_f32_16x16x32_bf16 v[32:35], v[168:171], v[234:237], v[32:35]
	v_mfma_f32_16x16x32_bf16 v[24:27], v[140:143], v[242:245], v[24:27]
	v_mfma_f32_16x16x32_bf16 v[12:15], v[168:171], v[242:245], v[12:15]
	v_mfma_f32_16x16x32_bf16 v[64:67], v[164:167], v[222:225], v[64:67]
	v_mfma_f32_16x16x32_bf16 v[60:63], v[172:175], v[222:225], v[60:63]
	v_mfma_f32_16x16x32_bf16 v[56:59], v[164:167], v[230:233], v[56:59]
	v_mfma_f32_16x16x32_bf16 v[48:51], v[172:175], v[230:233], v[48:51]
	v_mfma_f32_16x16x32_bf16 v[40:43], v[164:167], v[238:241], v[40:43]
	v_mfma_f32_16x16x32_bf16 v[32:35], v[172:175], v[238:241], v[32:35]
	v_mfma_f32_16x16x32_bf16 v[24:27], v[164:167], v[246:249], v[24:27]
	v_mfma_f32_16x16x32_bf16 v[12:15], v[172:175], v[246:249], v[12:15]
	s_setprio 0
	s_setprio 1
	v_mfma_f32_16x16x32_bf16 v[52:55], v[198:201], v[218:221], v[52:55]
	v_mfma_f32_16x16x32_bf16 v[44:47], v[206:209], v[218:221], v[44:47]
	v_mfma_f32_16x16x32_bf16 v[36:39], v[198:201], v[226:229], v[36:39]
	v_mfma_f32_16x16x32_bf16 v[28:31], v[206:209], v[226:229], v[28:31]
	v_mfma_f32_16x16x32_bf16 v[20:23], v[198:201], v[234:237], v[20:23]
	v_mfma_f32_16x16x32_bf16 v[8:11], v[206:209], v[234:237], v[8:11]
	v_mfma_f32_16x16x32_bf16 v[4:7], v[198:201], v[242:245], v[4:7]
	v_mfma_f32_16x16x32_bf16 v[0:3], v[206:209], v[242:245], v[0:3]
	v_mfma_f32_16x16x32_bf16 v[52:55], v[202:205], v[222:225], v[52:55]
	v_mfma_f32_16x16x32_bf16 v[44:47], v[210:213], v[222:225], v[44:47]
	v_mfma_f32_16x16x32_bf16 v[36:39], v[202:205], v[230:233], v[36:39]
	v_mfma_f32_16x16x32_bf16 v[28:31], v[210:213], v[230:233], v[28:31]
	v_mfma_f32_16x16x32_bf16 v[20:23], v[202:205], v[238:241], v[20:23]
	v_mfma_f32_16x16x32_bf16 v[8:11], v[210:213], v[238:241], v[8:11]
	v_mfma_f32_16x16x32_bf16 v[4:7], v[202:205], v[246:249], v[4:7]
	v_mfma_f32_16x16x32_bf16 v[0:3], v[210:213], v[246:249], v[0:3]
	s_setprio 0
	s_barrier
	s_add_i32 s58, 0, 0x18000
	v_add_u32_e32 v154, s58, v144
	s_add_i32 s59, 0, 0x1c000
	ds_read_b128 v[140:143], v154
	ds_read_b128 v[164:167], v154 offset:1024
	ds_read_b128 v[168:171], v154 offset:2048
	ds_read_b128 v[172:175], v154 offset:3072
	v_add_u32_e32 v154, s59, v144
	ds_read_b128 v[198:201], v154
	ds_read_b128 v[202:205], v154 offset:1024
	ds_read_b128 v[206:209], v154 offset:2048
	ds_read_b128 v[210:213], v154 offset:3072
	s_add_u32 s20, s20, 0x40000
	s_addc_u32 s21, s21, 0
	s_mov_b32 m0, s1
	ds_read_b128 v[218:221], v145 offset:32768
	ds_read_b128 v[222:225], v145 offset:33792
	ds_read_b128 v[226:229], v145 offset:34816
	ds_read_b128 v[230:233], v145 offset:35840
	ds_read_b128 v[234:237], v145 offset:36864
	ds_read_b128 v[238:241], v145 offset:37888
	ds_read_b128 v[242:245], v145 offset:38912
	ds_read_b128 v[246:249], v145 offset:39936
	global_load_lds_dwordx4 v134, s[20:21]
	v_lshl_add_u64 v[154:155], s[20:21], 0, v[132:133]
	s_mov_b32 m0, s8
	s_nop 0
	global_load_lds_dwordx4 v[154:155], off
	s_waitcnt vmcnt(8)
	s_waitcnt lgkmcnt(0)
	s_barrier
	s_setprio 1
	s_waitcnt lgkmcnt(0)
	v_mfma_f32_16x16x32_bf16 v[128:131], v[140:143], v[218:221], v[128:131]
	v_mfma_f32_16x16x32_bf16 v[124:127], v[168:171], v[218:221], v[124:127]
	v_mfma_f32_16x16x32_bf16 v[120:123], v[140:143], v[226:229], v[120:123]
	v_mfma_f32_16x16x32_bf16 v[112:115], v[168:171], v[226:229], v[112:115]
	v_mfma_f32_16x16x32_bf16 v[104:107], v[140:143], v[234:237], v[104:107]
	v_mfma_f32_16x16x32_bf16 v[96:99], v[168:171], v[234:237], v[96:99]
	v_mfma_f32_16x16x32_bf16 v[88:91], v[140:143], v[242:245], v[88:91]
	v_mfma_f32_16x16x32_bf16 v[80:83], v[168:171], v[242:245], v[80:83]
	v_mfma_f32_16x16x32_bf16 v[128:131], v[164:167], v[222:225], v[128:131]
	v_mfma_f32_16x16x32_bf16 v[124:127], v[172:175], v[222:225], v[124:127]
	v_mfma_f32_16x16x32_bf16 v[120:123], v[164:167], v[230:233], v[120:123]
	v_mfma_f32_16x16x32_bf16 v[112:115], v[172:175], v[230:233], v[112:115]
	v_mfma_f32_16x16x32_bf16 v[104:107], v[164:167], v[238:241], v[104:107]
	v_mfma_f32_16x16x32_bf16 v[96:99], v[172:175], v[238:241], v[96:99]
	v_mfma_f32_16x16x32_bf16 v[88:91], v[164:167], v[246:249], v[88:91]
	v_mfma_f32_16x16x32_bf16 v[80:83], v[172:175], v[246:249], v[80:83]
	s_setprio 0
	s_setprio 1
	v_mfma_f32_16x16x32_bf16 v[116:119], v[198:201], v[218:221], v[116:119]
	v_mfma_f32_16x16x32_bf16 v[108:111], v[206:209], v[218:221], v[108:111]
	v_mfma_f32_16x16x32_bf16 v[100:103], v[198:201], v[226:229], v[100:103]
	v_mfma_f32_16x16x32_bf16 v[92:95], v[206:209], v[226:229], v[92:95]
	v_mfma_f32_16x16x32_bf16 v[84:87], v[198:201], v[234:237], v[84:87]
	v_mfma_f32_16x16x32_bf16 v[76:79], v[206:209], v[234:237], v[76:79]
	v_mfma_f32_16x16x32_bf16 v[72:75], v[198:201], v[242:245], v[72:75]
	v_mfma_f32_16x16x32_bf16 v[68:71], v[206:209], v[242:245], v[68:71]
	v_mfma_f32_16x16x32_bf16 v[116:119], v[202:205], v[222:225], v[116:119]
	v_mfma_f32_16x16x32_bf16 v[108:111], v[210:213], v[222:225], v[108:111]
	v_mfma_f32_16x16x32_bf16 v[100:103], v[202:205], v[230:233], v[100:103]
	v_mfma_f32_16x16x32_bf16 v[92:95], v[210:213], v[230:233], v[92:95]
	v_mfma_f32_16x16x32_bf16 v[84:87], v[202:205], v[238:241], v[84:87]
	v_mfma_f32_16x16x32_bf16 v[76:79], v[210:213], v[238:241], v[76:79]
	v_mfma_f32_16x16x32_bf16 v[72:75], v[202:205], v[246:249], v[72:75]
	v_mfma_f32_16x16x32_bf16 v[68:71], v[210:213], v[246:249], v[68:71]
	s_setprio 0
	s_barrier
; #define PG8_STAGE(bufoff, gbase, voff) do { _Pragma("unroll") for (int _i = 0; _i < 2; ++_i) \
;         __builtin_amdgcn_global_load_lds((const unsigned*)((const char*)(gbase) + (voff)[_i]), (LAS unsigned*)(lds + (bufoff) + ldsw + _i * 8192), 16, 0, 0); } while (0)
; #define PG8_LDA(dst, b, h) do { _Pragma("unroll") for (int m = 0; m < 4; ++m) _Pragma("unroll") for (int k = 0; k < 2; ++k) dst[m][k] = *(const LAS bf16x8*)(lds + PG8_SA(b, h) + aoff + m * 2048 + k * 1024); } while (0)
; #define PG8_MMA(ai, bj, At, Bt) do { __builtin_amdgcn_s_setprio(1); _Pragma("unroll") for (int m = 0; m < 4; ++m) _Pragma("unroll") for (int n = 0; n < 2; ++n) _Pragma("unroll") for (int k = 0; k < 2; ++k) \
;         acc[ai][bj][m][n] = __builtin_amdgcn_mfma_f32_16x16x32_bf16(Bt[n][k], At[m][k], acc[ai][bj][m][n], 0, 0, 0); __builtin_amdgcn_s_setprio(0); } while (0)
; #define PG8_WAIT_V(n) asm volatile("s_waitcnt vmcnt(" #n ")" ::: "memory")
; #define PG8_WAIT_L(n) asm volatile("s_waitcnt lgkmcnt(" #n ")" ::: "memory")
; #define PG8_BAR __builtin_amdgcn_s_barrier()
; #define PG8_SCHED __builtin_amdgcn_sched_barrier(0)
; template <class Epi, class Sched, bool ALIGN_EPI = true, bool SP2 = true>
; __device__ __forceinline__ void gemm_phase(LAS unsigned char* lds, const Gemm g, const Sched& S, const Epi& E) {
;     ...
;             PG8_WAIT_V(8); PG8_WAIT_L(0); PG8_BAR; PG8_MMA(0, 0, At, B0); PG8_MMA(0, 1, At, B1); PG8_BAR; PG8_SCHED;
;             PG8_LDA(At, 1, 1); PG8_STAGE(PG8_SB(1, 0), b3, voffB); PG8_STAGE(PG8_SB(1, 1), b3 + hstepB, voffB); PG8_STAGE(PG8_SA(1, 0), a3, voffA);
;             PG8_WAIT_V(8); PG8_WAIT_L(0); PG8_BAR; PG8_MMA(1, 0, At, B0); PG8_MMA(1, 1, At, B1); PG8_BAR; PG8_SCHED;
;         }
;         if constexpr (ALIGN_EPI) { if (wr == 0) PG8_BAR; }
	s_add_i32 s20, s58, s39
	v_lshl_add_u64 v[146:147], v[146:147], 0, s[14:15]
	s_mov_b32 m0, s20
	ds_read_b128 v[218:221], v145 offset:49152
	ds_read_b128 v[222:225], v145 offset:50176
	ds_read_b128 v[226:229], v145 offset:51200
	ds_read_b128 v[230:233], v145 offset:52224
	ds_read_b128 v[234:237], v145 offset:53248
	ds_read_b128 v[238:241], v145 offset:54272
	ds_read_b128 v[242:245], v145 offset:55296
	ds_read_b128 v[246:249], v145 offset:56320
	global_load_lds_dwordx4 v[146:147], off
	s_add_i32 m0, s20, 0x2000
	s_add_u32 s18, s18, 0x40080
	v_lshl_add_u64 v[146:147], v[148:149], 0, s[14:15]
	s_addc_u32 s19, s19, 0
	s_add_i32 s20, s59, s39
	global_load_lds_dwordx4 v[146:147], off
	s_mov_b32 m0, s20
	s_nop 0
	global_load_lds_dwordx4 v18, s[18:19]
	v_lshl_add_u64 v[146:147], s[18:19], 0, v[16:17]
	s_add_i32 m0, s20, 0x2000
	s_nop 0
	global_load_lds_dwordx4 v[146:147], off
	v_lshl_add_u64 v[146:147], v[150:151], 0, s[14:15]
	s_mov_b32 m0, s54
	s_nop 0
	global_load_lds_dwordx4 v[146:147], off
	v_lshl_add_u64 v[146:147], v[152:153], 0, s[14:15]
	s_mov_b32 m0, s55
	s_nop 0
	global_load_lds_dwordx4 v[146:147], off
	s_waitcnt vmcnt(8)
	s_waitcnt lgkmcnt(0)
	s_barrier
	s_setprio 1
	s_waitcnt lgkmcnt(0)
	v_mfma_f32_16x16x32_bf16 v[64:67], v[140:143], v[218:221], v[64:67]
	v_mfma_f32_16x16x32_bf16 v[60:63], v[168:171], v[218:221], v[60:63]
	v_mfma_f32_16x16x32_bf16 v[56:59], v[140:143], v[226:229], v[56:59]
	v_mfma_f32_16x16x32_bf16 v[48:51], v[168:171], v[226:229], v[48:51]
	v_mfma_f32_16x16x32_bf16 v[40:43], v[140:143], v[234:237], v[40:43]
	v_mfma_f32_16x16x32_bf16 v[32:35], v[168:171], v[234:237], v[32:35]
	v_mfma_f32_16x16x32_bf16 v[24:27], v[140:143], v[242:245], v[24:27]
	v_mfma_f32_16x16x32_bf16 v[12:15], v[168:171], v[242:245], v[12:15]
	v_mfma_f32_16x16x32_bf16 v[64:67], v[164:167], v[222:225], v[64:67]
	v_mfma_f32_16x16x32_bf16 v[60:63], v[172:175], v[222:225], v[60:63]
	v_mfma_f32_16x16x32_bf16 v[56:59], v[164:167], v[230:233], v[56:59]
	v_mfma_f32_16x16x32_bf16 v[48:51], v[172:175], v[230:233], v[48:51]
	v_mfma_f32_16x16x32_bf16 v[40:43], v[164:167], v[238:241], v[40:43]
	v_mfma_f32_16x16x32_bf16 v[32:35], v[172:175], v[238:241], v[32:35]
	v_mfma_f32_16x16x32_bf16 v[24:27], v[164:167], v[246:249], v[24:27]
	v_mfma_f32_16x16x32_bf16 v[12:15], v[172:175], v[246:249], v[12:15]
	s_setprio 0
	s_setprio 1
	v_mfma_f32_16x16x32_bf16 v[52:55], v[198:201], v[218:221], v[52:55]
	v_mfma_f32_16x16x32_bf16 v[44:47], v[206:209], v[218:221], v[44:47]
	v_mfma_f32_16x16x32_bf16 v[36:39], v[198:201], v[226:229], v[36:39]
	v_mfma_f32_16x16x32_bf16 v[28:31], v[206:209], v[226:229], v[28:31]
	v_mfma_f32_16x16x32_bf16 v[20:23], v[198:201], v[234:237], v[20:23]
	v_mfma_f32_16x16x32_bf16 v[8:11], v[206:209], v[234:237], v[8:11]
	v_mfma_f32_16x16x32_bf16 v[4:7], v[198:201], v[242:245], v[4:7]
	v_mfma_f32_16x16x32_bf16 v[0:3], v[206:209], v[242:245], v[0:3]
	v_mfma_f32_16x16x32_bf16 v[52:55], v[202:205], v[222:225], v[52:55]
	v_mfma_f32_16x16x32_bf16 v[44:47], v[210:213], v[222:225], v[44:47]
	v_mfma_f32_16x16x32_bf16 v[36:39], v[202:205], v[230:233], v[36:39]
	v_mfma_f32_16x16x32_bf16 v[28:31], v[210:213], v[230:233], v[28:31]
	v_mfma_f32_16x16x32_bf16 v[20:23], v[202:205], v[238:241], v[20:23]
	v_mfma_f32_16x16x32_bf16 v[8:11], v[210:213], v[238:241], v[8:11]
	v_mfma_f32_16x16x32_bf16 v[4:7], v[202:205], v[246:249], v[4:7]
	v_mfma_f32_16x16x32_bf16 v[0:3], v[210:213], v[246:249], v[0:3]
	s_setprio 0
	s_barrier
	s_add_i32 s60, s60, 2
	s_add_u32 s50, s50, 0x100
	s_addc_u32 s51, s51, 0
	s_add_u32 s30, s30, 0x100
	s_addc_u32 s45, s45, 0
	s_cmp_gt_u32 s60, 13
	s_cbranch_scc0 .LBB0_458
	s_and_b64 vcc, exec, s[36:37]
	s_cbranch_vccz .LBB0_461
	s_barrier

; #define PG8_STAGE(bufoff, gbase, voff) do { _Pragma("unroll") for (int _i = 0; _i < 2; ++_i) \
;         __builtin_amdgcn_global_load_lds((const unsigned*)((const char*)(gbase) + (voff)[_i]), (LAS unsigned*)(lds + (bufoff) + ldsw + _i * 8192), 16, 0, 0); } while (0)
; #define PG8_WAIT_V(n) asm volatile("s_waitcnt vmcnt(" #n ")" ::: "memory")
; #define PG8_BAR __builtin_amdgcn_s_barrier()
; template <class Epi, class Sched, bool ALIGN_EPI = true, bool SP2 = true>
; __device__ __forceinline__ void gemm_phase(LAS unsigned char* lds, const Gemm g, const Sched& S, const Epi& E) {
;     ...
;     const int aoff = lds_byte(wr * 64 + fr, fq * 8), boff = lds_byte(wc * 32 + fr, fq * 8);
;     ...
;     Unit cur, nxt; int ui = 0;
;     if (!S.next(0, cur)) return;
;     f32x4 acc[2][2][4][2];
; #pragma unroll
;     for (int a = 0; a < 2; ++a)
; #pragma unroll
;         for (int b = 0; b < 2; ++b)
; #pragma unroll
;             for (int m = 0; m < 4; ++m)
; #pragma unroll
;                 for (int n = 0; n < 2; ++n) acc[a][b][m][n] = (f32x4){0.f, 0.f, 0.f, 0.f};
;     bf16x8 At[4][2], B0[2][2], B1[2][2];
;     const char* cA = (const char*)g.A + (size_t)cur.pm * tstepA; const char* cB = (const char*)g.Bt + (size_t)cur.pn * tstepB;
;     if constexpr (SP2) {
;         PG8_STAGE(PG8_SB(0, 0), cB, voffB); PG8_STAGE(PG8_SB(0, 1), cB + hstepB, voffB); PG8_STAGE(PG8_SA(0, 0), cA, voffA); PG8_STAGE(PG8_SA(0, 1), cA + hstepA, voffA);
;         if (wr == 1) PG8_BAR;
;         PG8_WAIT_V(2); PG8_BAR;
;         PG8_STAGE(PG8_SB(1, 0), cB + kstep, voffB); PG8_STAGE(PG8_SA(1, 0), cA + kstep, voffA); PG8_STAGE(PG8_SB(1, 1), cB + hstepB + kstep, voffB);
;         PG8_WAIT_V(6); PG8_BAR;
.LBB0_618:
	s_add_u32 s12, s48, 0x17e00000
	s_addc_u32 s13, s49, 0
	s_add_u32 s50, s48, 0x140000
	s_addc_u32 s51, s49, 0
	s_add_u32 s54, s48, 0x80000
	v_and_b32_e32 v9, 48, v8
	v_lshlrev_b32_e32 v10, 6, v8
	s_movk_i32 s25, 0x3c0
	v_lshlrev_b32_e32 v8, 2, v8
	s_addc_u32 s55, s49, 0
	s_lshl_b32 s38, s8, 6
	s_lshl_b32 s8, s8, 13
	v_and_or_b32 v9, v10, s25, v9
	v_and_b32_e32 v8, 32, v8
	v_bitop3_b32 v10, v9, s8, v8 bitop3:0xde
	s_lshl_b32 s8, s9, 5
	s_and_b32 s39, s8, 0x60
	s_add_i32 m0, s22, 0x18000
	v_lshl_add_u64 v[6:7], v[6:7], 0, s[14:15]
	s_lshl_b32 s8, s39, 7
	s_waitcnt vmcnt(2)
	s_barrier
	global_load_lds_dwordx4 v[6:7], off
	v_lshl_add_u64 v[4:5], v[4:5], 0, s[14:15]
	s_add_i32 m0, s22, 0x1a000
	s_add_i32 s52, s22, 0x8000
	s_add_i32 s53, s22, 0xa000
	v_bitop3_b32 v166, s8, v9, v8 bitop3:0xf6
	global_load_lds_dwordx4 v[4:5], off
	v_lshl_add_u64 v[0:1], v[0:1], 0, s[14:15]
	s_mov_b32 m0, s52
	s_add_u32 s8, s44, 0x18080
	global_load_lds_dwordx4 v[0:1], off
	v_lshl_add_u64 v[0:1], v[2:3], 0, s[14:15]
	s_mov_b32 m0, s53
	s_addc_u32 s9, s45, 0
	global_load_lds_dwordx4 v[0:1], off
	s_add_i32 m0, s22, 0x1c000
	s_nop 0
	global_load_lds_dwordx4 v132, s[8:9]
	s_add_i32 m0, s22, 0x1e000
	s_cmpk_lt_u32 s2, 0x100
	global_load_lds_dwordx4 v136, s[8:9]
	s_waitcnt vmcnt(6)
	s_cselect_b64 s[62:63], -1, 0
	s_ashr_i32 s28, s26, 31
	s_ashr_i32 s2, s40, 31
	s_add_u32 s36, s26, s40
	v_add_u32_e32 v167, 0, v10
	s_addc_u32 s37, s28, s2
	s_barrier
	s_branch .LBB0_621

; #define PG8_STAGE(bufoff, gbase, voff) do { _Pragma("unroll") for (int _i = 0; _i < 2; ++_i) \
;         __builtin_amdgcn_global_load_lds((const unsigned*)((const char*)(gbase) + (voff)[_i]), (LAS unsigned*)(lds + (bufoff) + ldsw + _i * 8192), 16, 0, 0); } while (0)
; #define PG8_LDA(dst, b, h) do { _Pragma("unroll") for (int m = 0; m < 4; ++m) _Pragma("unroll") for (int k = 0; k < 2; ++k) dst[m][k] = *(const LAS bf16x8*)(lds + PG8_SA(b, h) + aoff + m * 2048 + k * 1024); } while (0)
; #define PG8_LDB(dst, b, h) do { _Pragma("unroll") for (int n = 0; n < 2; ++n) _Pragma("unroll") for (int k = 0; k < 2; ++k) dst[n][k] = *(const LAS bf16x8*)(lds + PG8_SB(b, h) + boff + n * 2048 + k * 1024); } while (0)
; #define PG8_MMA(ai, bj, At, Bt) do { __builtin_amdgcn_s_setprio(1); _Pragma("unroll") for (int m = 0; m < 4; ++m) _Pragma("unroll") for (int n = 0; n < 2; ++n) _Pragma("unroll") for (int k = 0; k < 2; ++k) \
;         acc[ai][bj][m][n] = __builtin_amdgcn_mfma_f32_16x16x32_bf16(Bt[n][k], At[m][k], acc[ai][bj][m][n], 0, 0, 0); __builtin_amdgcn_s_setprio(0); } while (0)
; #define PG8_WAIT_V(n) asm volatile("s_waitcnt vmcnt(" #n ")" ::: "memory")
; #define PG8_WAIT_L(n) asm volatile("s_waitcnt lgkmcnt(" #n ")" ::: "memory")
; #define PG8_BAR __builtin_amdgcn_s_barrier()
; #define PG8_SCHED __builtin_amdgcn_sched_barrier(0)
; template <class Epi, class Sched, bool ALIGN_EPI = true, bool SP2 = true>
; __device__ __forceinline__ void gemm_phase(LAS unsigned char* lds, const Gemm g, const Sched& S, const Epi& E) {
;     ...
;             PG8_LDB(B0, 0, 0); PG8_LDB(B1, 0, 1); PG8_SCHED; PG8_LDA(At, 0, 0); PG8_STAGE(PG8_SA(1, 1), a1 + hstepA, voffA);
;             PG8_WAIT_V(8); PG8_WAIT_L(0); PG8_BAR; PG8_MMA(0, 0, At, B0); PG8_MMA(0, 1, At, B1); PG8_BAR; PG8_SCHED;
;             PG8_LDA(At, 0, 1); PG8_STAGE(PG8_SB(0, 0), b2, voffB); PG8_STAGE(PG8_SB(0, 1), b2 + hstepB, voffB); PG8_STAGE(PG8_SA(0, 0), a2, voffA);
;             PG8_WAIT_V(8); PG8_WAIT_L(0); PG8_BAR; PG8_MMA(1, 0, At, B0); PG8_MMA(1, 1, At, B1); PG8_BAR; PG8_SCHED;
.LBB0_627:
	s_add_i32 s42, 0, 0x10000
	s_add_i32 s30, 0, 0x14000
	v_add_u32_e32 v8, s42, v166
	v_add_u32_e32 v9, s30, v166
	ds_read_b128 v[10:13], v8
	ds_read_b128 v[20:23], v8 offset:1024
	ds_read_b128 v[24:27], v8 offset:2048
	ds_read_b128 v[28:31], v8 offset:3072
	ds_read_b128 v[32:35], v9
	ds_read_b128 v[36:39], v9 offset:1024
	ds_read_b128 v[40:43], v9 offset:2048
	ds_read_b128 v[44:47], v9 offset:3072
	s_add_u32 s8, s16, 0x30080
	s_addc_u32 s9, s17, 0
	s_add_i32 s58, s22, 0xc000
	s_mov_b32 m0, s58
	s_add_i32 s2, s22, 0xe000
	ds_read_b128 v[0:3], v167
	ds_read_b128 v[4:7], v167 offset:1024
	ds_read_b128 v[48:51], v167 offset:2048
	ds_read_b128 v[52:55], v167 offset:3072
	ds_read_b128 v[56:59], v167 offset:4096
	ds_read_b128 v[60:63], v167 offset:5120
	ds_read_b128 v[64:67], v167 offset:6144
	s_waitcnt vmcnt(0)
	ds_read_b128 v[68:71], v167 offset:7168
	global_load_lds_dwordx4 v16, s[8:9]
	v_lshl_add_u64 v[14:15], s[8:9], 0, v[134:135]
	s_mov_b32 m0, s2
	s_nop 0
	global_load_lds_dwordx4 v[14:15], off
	s_waitcnt vmcnt(8)
	s_waitcnt lgkmcnt(0)
	s_barrier
	s_setprio 1
	s_waitcnt lgkmcnt(0)
	v_mfma_f32_16x16x32_bf16 v[72:75], v[10:13], v[0:3], 0
	v_mfma_f32_16x16x32_bf16 v[76:79], v[24:27], v[0:3], 0
	v_mfma_f32_16x16x32_bf16 v[80:83], v[10:13], v[48:51], 0
	v_mfma_f32_16x16x32_bf16 v[84:87], v[24:27], v[48:51], 0
	v_mfma_f32_16x16x32_bf16 v[88:91], v[10:13], v[56:59], 0
	v_mfma_f32_16x16x32_bf16 v[92:95], v[24:27], v[56:59], 0
	v_mfma_f32_16x16x32_bf16 v[96:99], v[10:13], v[64:67], 0
	v_mfma_f32_16x16x32_bf16 v[100:103], v[24:27], v[64:67], 0
	v_mfma_f32_16x16x32_bf16 v[72:75], v[20:23], v[4:7], v[72:75]
	v_mfma_f32_16x16x32_bf16 v[76:79], v[28:31], v[4:7], v[76:79]
	v_mfma_f32_16x16x32_bf16 v[80:83], v[20:23], v[52:55], v[80:83]
	v_mfma_f32_16x16x32_bf16 v[84:87], v[28:31], v[52:55], v[84:87]
	v_mfma_f32_16x16x32_bf16 v[88:91], v[20:23], v[60:63], v[88:91]
	v_mfma_f32_16x16x32_bf16 v[92:95], v[28:31], v[60:63], v[92:95]
	v_mfma_f32_16x16x32_bf16 v[96:99], v[20:23], v[68:71], v[96:99]
	v_mfma_f32_16x16x32_bf16 v[100:103], v[28:31], v[68:71], v[100:103]
	s_setprio 0
	s_setprio 1
	v_mfma_f32_16x16x32_bf16 v[104:107], v[32:35], v[0:3], 0
	v_mfma_f32_16x16x32_bf16 v[0:3], v[40:43], v[0:3], 0
	v_mfma_f32_16x16x32_bf16 v[108:111], v[44:47], v[4:7], v[0:3]
	v_mfma_f32_16x16x32_bf16 v[0:3], v[32:35], v[48:51], 0
	v_mfma_f32_16x16x32_bf16 v[112:115], v[36:39], v[52:55], v[0:3]
	v_mfma_f32_16x16x32_bf16 v[0:3], v[40:43], v[48:51], 0
	v_mfma_f32_16x16x32_bf16 v[48:51], v[44:47], v[52:55], v[0:3]
	v_mfma_f32_16x16x32_bf16 v[0:3], v[32:35], v[56:59], 0
	v_mfma_f32_16x16x32_bf16 v[52:55], v[36:39], v[60:63], v[0:3]
	v_mfma_f32_16x16x32_bf16 v[0:3], v[40:43], v[56:59], 0
	v_mfma_f32_16x16x32_bf16 v[56:59], v[44:47], v[60:63], v[0:3]
	v_mfma_f32_16x16x32_bf16 v[0:3], v[32:35], v[64:67], 0
	v_mfma_f32_16x16x32_bf16 v[60:63], v[36:39], v[68:71], v[0:3]
	v_mfma_f32_16x16x32_bf16 v[0:3], v[40:43], v[64:67], 0
	v_mfma_f32_16x16x32_bf16 v[104:107], v[36:39], v[4:7], v[104:107]
	v_mfma_f32_16x16x32_bf16 v[64:67], v[44:47], v[68:71], v[0:3]
	s_setprio 0
	s_barrier
	s_nop 3
	v_lshl_add_u64 v[0:1], s[44:45], 0, v[132:133]
	s_mov_b64 s[64:65], 0x100
	s_add_i32 s42, s42, s21
	v_lshl_add_u64 v[2:3], v[0:1], 0, s[64:65]
	s_mov_b32 m0, s42
	s_add_i32 s8, s42, 0x2000
	ds_read_b128 v[68:71], v167 offset:16384
	ds_read_b128 v[116:119], v167 offset:17408
	ds_read_b128 v[120:123], v167 offset:18432
	s_waitcnt vmcnt(0)
	ds_read_b128 v[124:127], v167 offset:19456
	ds_read_b128 v[128:131], v167 offset:20480
	ds_read_b128 v[138:141], v167 offset:21504
	ds_read_b128 v[142:145], v167 offset:22528
	ds_read_b128 v[168:171], v167 offset:23552
	global_load_lds_dwordx4 v[2:3], off
	v_lshl_add_u64 v[2:3], s[44:45], 0, v[136:137]
	s_add_u32 s60, s44, 0x18100
	v_lshl_add_u64 v[4:5], v[2:3], 0, s[64:65]
	s_mov_b32 m0, s8
	s_addc_u32 s61, s45, 0
	s_add_i32 s9, s30, s21
	global_load_lds_dwordx4 v[4:5], off
	s_mov_b32 m0, s9
	s_add_i32 s30, s9, 0x2000
	global_load_lds_dwordx4 v132, s[60:61]
	s_mov_b32 m0, s30
	s_nop 0
	global_load_lds_dwordx4 v136, s[60:61]
	v_lshl_add_u64 v[4:5], s[16:17], 0, v[16:17]
	v_lshl_add_u64 v[6:7], v[4:5], 0, s[64:65]
	s_mov_b32 m0, s22
	s_nop 0
	global_load_lds_dwordx4 v[6:7], off
	v_lshl_add_u64 v[6:7], s[16:17], 0, v[134:135]
	v_lshl_add_u64 v[14:15], v[6:7], 0, s[64:65]
	s_mov_b32 m0, s23
	s_nop 0
	global_load_lds_dwordx4 v[14:15], off
	s_waitcnt vmcnt(8)
	s_waitcnt lgkmcnt(0)
	s_barrier
	s_setprio 1
	s_waitcnt lgkmcnt(0)
	v_mfma_f32_16x16x32_bf16 v[172:175], v[10:13], v[68:71], 0
	v_mfma_f32_16x16x32_bf16 v[202:205], v[10:13], v[120:123], 0
	v_mfma_f32_16x16x32_bf16 v[210:213], v[10:13], v[128:131], 0
	v_mfma_f32_16x16x32_bf16 v[10:13], v[10:13], v[142:145], 0
	v_mfma_f32_16x16x32_bf16 v[172:175], v[20:23], v[116:119], v[172:175]
	v_mfma_f32_16x16x32_bf16 v[202:205], v[20:23], v[124:127], v[202:205]
	v_mfma_f32_16x16x32_bf16 v[210:213], v[20:23], v[138:141], v[210:213]
	v_mfma_f32_16x16x32_bf16 v[12:15], v[20:23], v[168:171], v[10:13]
	v_mfma_f32_16x16x32_bf16 v[20:23], v[24:27], v[142:145], 0
	v_mfma_f32_16x16x32_bf16 v[198:201], v[24:27], v[68:71], 0
	v_mfma_f32_16x16x32_bf16 v[206:209], v[24:27], v[120:123], 0
	v_mfma_f32_16x16x32_bf16 v[218:221], v[24:27], v[128:131], 0
	v_mfma_f32_16x16x32_bf16 v[20:23], v[28:31], v[168:171], v[20:23]
	v_mfma_f32_16x16x32_bf16 v[198:201], v[28:31], v[116:119], v[198:201]
	v_mfma_f32_16x16x32_bf16 v[206:209], v[28:31], v[124:127], v[206:209]
	v_mfma_f32_16x16x32_bf16 v[218:221], v[28:31], v[138:141], v[218:221]
	s_setprio 0
	s_setprio 1
	v_mfma_f32_16x16x32_bf16 v[24:27], v[32:35], v[68:71], 0
	v_mfma_f32_16x16x32_bf16 v[28:31], v[40:43], v[68:71], 0
	v_mfma_f32_16x16x32_bf16 v[24:27], v[36:39], v[116:119], v[24:27]
	v_mfma_f32_16x16x32_bf16 v[28:31], v[44:47], v[116:119], v[28:31]
	v_mfma_f32_16x16x32_bf16 v[68:71], v[32:35], v[120:123], 0
	v_mfma_f32_16x16x32_bf16 v[116:119], v[40:43], v[120:123], 0
	v_mfma_f32_16x16x32_bf16 v[120:123], v[32:35], v[128:131], 0
	v_mfma_f32_16x16x32_bf16 v[32:35], v[32:35], v[142:145], 0
	v_mfma_f32_16x16x32_bf16 v[68:71], v[36:39], v[124:127], v[68:71]
	v_mfma_f32_16x16x32_bf16 v[116:119], v[44:47], v[124:127], v[116:119]
	v_mfma_f32_16x16x32_bf16 v[120:123], v[36:39], v[138:141], v[120:123]
	v_mfma_f32_16x16x32_bf16 v[124:127], v[40:43], v[128:131], 0
	v_mfma_f32_16x16x32_bf16 v[32:35], v[36:39], v[168:171], v[32:35]
	v_mfma_f32_16x16x32_bf16 v[36:39], v[40:43], v[142:145], 0
	v_mfma_f32_16x16x32_bf16 v[124:127], v[44:47], v[138:141], v[124:127]
	v_mfma_f32_16x16x32_bf16 v[36:39], v[44:47], v[168:171], v[36:39]
	s_setprio 0
	s_barrier
; #define PG8_STAGE(bufoff, gbase, voff) do { _Pragma("unroll") for (int _i = 0; _i < 2; ++_i) \
;         __builtin_amdgcn_global_load_lds((const unsigned*)((const char*)(gbase) + (voff)[_i]), (LAS unsigned*)(lds + (bufoff) + ldsw + _i * 8192), 16, 0, 0); } while (0)
; #define PG8_LDA(dst, b, h) do { _Pragma("unroll") for (int m = 0; m < 4; ++m) _Pragma("unroll") for (int k = 0; k < 2; ++k) dst[m][k] = *(const LAS bf16x8*)(lds + PG8_SA(b, h) + aoff + m * 2048 + k * 1024); } while (0)
; #define PG8_LDB(dst, b, h) do { _Pragma("unroll") for (int n = 0; n < 2; ++n) _Pragma("unroll") for (int k = 0; k < 2; ++k) dst[n][k] = *(const LAS bf16x8*)(lds + PG8_SB(b, h) + boff + n * 2048 + k * 1024); } while (0)
; #define PG8_MMA(ai, bj, At, Bt) do { __builtin_amdgcn_s_setprio(1); _Pragma("unroll") for (int m = 0; m < 4; ++m) _Pragma("unroll") for (int n = 0; n < 2; ++n) _Pragma("unroll") for (int k = 0; k < 2; ++k) \
;         acc[ai][bj][m][n] = __builtin_amdgcn_mfma_f32_16x16x32_bf16(Bt[n][k], At[m][k], acc[ai][bj][m][n], 0, 0, 0); __builtin_amdgcn_s_setprio(0); } while (0)
; #define PG8_WAIT_V(n) asm volatile("s_waitcnt vmcnt(" #n ")" ::: "memory")
; #define PG8_WAIT_L(n) asm volatile("s_waitcnt lgkmcnt(" #n ")" ::: "memory")
; #define PG8_BAR __builtin_amdgcn_s_barrier()
; #define PG8_SCHED __builtin_amdgcn_sched_barrier(0)
; template <class Epi, class Sched, bool ALIGN_EPI = true, bool SP2 = true>
; __device__ __forceinline__ void gemm_phase(LAS unsigned char* lds, const Gemm g, const Sched& S, const Epi& E) {
;     ...
;             PG8_LDB(B0, 1, 0); PG8_LDB(B1, 1, 1); PG8_SCHED; PG8_LDA(At, 1, 0); PG8_STAGE(PG8_SA(0, 1), a2 + hstepA, voffA);
;             PG8_WAIT_V(8); PG8_WAIT_L(0); PG8_BAR; PG8_MMA(0, 0, At, B0); PG8_MMA(0, 1, At, B1); PG8_BAR; PG8_SCHED;
;             PG8_LDA(At, 1, 1); PG8_STAGE(PG8_SB(1, 0), b3, voffB); PG8_STAGE(PG8_SB(1, 1), b3 + hstepB, voffB); PG8_STAGE(PG8_SA(1, 0), a3, voffA);
;             PG8_WAIT_V(8); PG8_WAIT_L(0); PG8_BAR; PG8_MMA(1, 0, At, B0); PG8_MMA(1, 1, At, B1); PG8_BAR; PG8_SCHED;
	s_add_i32 s43, 0, 0x18000
	s_add_i32 s57, 0, 0x1c000
	v_add_u32_e32 v10, s43, v166
	v_add_u32_e32 v11, s57, v166
	ds_read_b128 v[40:43], v10
	ds_read_b128 v[44:47], v10 offset:1024
	ds_read_b128 v[128:131], v10 offset:2048
	ds_read_b128 v[138:141], v10 offset:3072
	ds_read_b128 v[142:145], v11
	ds_read_b128 v[168:171], v11 offset:1024
	ds_read_b128 v[222:225], v11 offset:2048
	ds_read_b128 v[226:229], v11 offset:3072
	s_add_u32 s60, s16, 0x30100
	s_addc_u32 s61, s17, 0
	s_mov_b32 m0, s24
	ds_read_b128 v[230:233], v167 offset:32768
	ds_read_b128 v[234:237], v167 offset:33792
	ds_read_b128 v[238:241], v167 offset:34816
	ds_read_b128 v[242:245], v167 offset:35840
	ds_read_b128 v[246:249], v167 offset:36864
	ds_read_b128 v[250:253], v167 offset:37888
	ds_read_b128 v[146:149], v167 offset:38912
	ds_read_b128 v[150:153], v167 offset:39936
	global_load_lds_dwordx4 v16, s[60:61]
	v_lshl_add_u64 v[154:155], s[60:61], 0, v[134:135]
	s_mov_b32 m0, s31
	s_nop 0
	global_load_lds_dwordx4 v[154:155], off
	s_waitcnt vmcnt(8)
	s_waitcnt lgkmcnt(0)
	s_barrier
	s_setprio 1
	s_waitcnt lgkmcnt(0)
	v_mfma_f32_16x16x32_bf16 v[72:75], v[40:43], v[230:233], v[72:75]
	v_mfma_f32_16x16x32_bf16 v[76:79], v[128:131], v[230:233], v[76:79]
	v_mfma_f32_16x16x32_bf16 v[80:83], v[40:43], v[238:241], v[80:83]
	v_mfma_f32_16x16x32_bf16 v[84:87], v[128:131], v[238:241], v[84:87]
	v_mfma_f32_16x16x32_bf16 v[88:91], v[40:43], v[246:249], v[88:91]
	v_mfma_f32_16x16x32_bf16 v[92:95], v[128:131], v[246:249], v[92:95]
	v_mfma_f32_16x16x32_bf16 v[96:99], v[40:43], v[146:149], v[96:99]
	v_mfma_f32_16x16x32_bf16 v[100:103], v[128:131], v[146:149], v[100:103]
	v_mfma_f32_16x16x32_bf16 v[72:75], v[44:47], v[234:237], v[72:75]
	v_mfma_f32_16x16x32_bf16 v[76:79], v[138:141], v[234:237], v[76:79]
	v_mfma_f32_16x16x32_bf16 v[80:83], v[44:47], v[242:245], v[80:83]
	v_mfma_f32_16x16x32_bf16 v[84:87], v[138:141], v[242:245], v[84:87]
	v_mfma_f32_16x16x32_bf16 v[88:91], v[44:47], v[250:253], v[88:91]
	v_mfma_f32_16x16x32_bf16 v[92:95], v[138:141], v[250:253], v[92:95]
	v_mfma_f32_16x16x32_bf16 v[96:99], v[44:47], v[150:153], v[96:99]
	v_mfma_f32_16x16x32_bf16 v[100:103], v[138:141], v[150:153], v[100:103]
	s_setprio 0
	s_setprio 1
	v_mfma_f32_16x16x32_bf16 v[104:107], v[142:145], v[230:233], v[104:107]
	v_mfma_f32_16x16x32_bf16 v[108:111], v[222:225], v[230:233], v[108:111]
	v_mfma_f32_16x16x32_bf16 v[112:115], v[142:145], v[238:241], v[112:115]
	v_mfma_f32_16x16x32_bf16 v[48:51], v[222:225], v[238:241], v[48:51]
	v_mfma_f32_16x16x32_bf16 v[52:55], v[142:145], v[246:249], v[52:55]
	v_mfma_f32_16x16x32_bf16 v[56:59], v[222:225], v[246:249], v[56:59]
	v_mfma_f32_16x16x32_bf16 v[60:63], v[142:145], v[146:149], v[60:63]
	v_mfma_f32_16x16x32_bf16 v[64:67], v[222:225], v[146:149], v[64:67]
	v_mfma_f32_16x16x32_bf16 v[104:107], v[168:171], v[234:237], v[104:107]
	v_mfma_f32_16x16x32_bf16 v[108:111], v[226:229], v[234:237], v[108:111]
	v_mfma_f32_16x16x32_bf16 v[112:115], v[168:171], v[242:245], v[112:115]
	v_mfma_f32_16x16x32_bf16 v[48:51], v[226:229], v[242:245], v[48:51]
	v_mfma_f32_16x16x32_bf16 v[52:55], v[168:171], v[250:253], v[52:55]
	v_mfma_f32_16x16x32_bf16 v[56:59], v[226:229], v[250:253], v[56:59]
	v_mfma_f32_16x16x32_bf16 v[60:63], v[168:171], v[150:153], v[60:63]
	v_mfma_f32_16x16x32_bf16 v[64:67], v[226:229], v[150:153], v[64:67]
	s_setprio 0
	s_barrier
	s_add_i32 s61, s43, s21
	s_mov_b64 vcc, 0x180
	s_add_i32 s43, s61, 0x2000
	v_lshl_add_u64 v[154:155], v[0:1], 0, vcc
	s_mov_b32 m0, s61
	s_add_u32 s64, s44, 0x18180
	ds_read_b128 v[146:149], v167 offset:49152
	ds_read_b128 v[150:153], v167 offset:50176
	ds_read_b128 v[230:233], v167 offset:51200
	ds_read_b128 v[234:237], v167 offset:52224
	ds_read_b128 v[238:241], v167 offset:53248
	ds_read_b128 v[242:245], v167 offset:54272
	ds_read_b128 v[246:249], v167 offset:55296
	ds_read_b128 v[250:253], v167 offset:56320
	global_load_lds_dwordx4 v[154:155], off
	v_lshl_add_u64 v[154:155], v[2:3], 0, vcc
	s_mov_b32 m0, s43
	s_addc_u32 s65, s45, 0
	s_add_i32 s57, s57, s21
	global_load_lds_dwordx4 v[154:155], off
	s_mov_b32 m0, s57
	s_add_i32 s59, s57, 0x2000
	global_load_lds_dwordx4 v132, s[64:65]
	v_lshl_add_u64 v[154:155], s[64:65], 0, v[136:137]
	s_mov_b32 m0, s59
	s_nop 0
	global_load_lds_dwordx4 v[154:155], off
	v_lshl_add_u64 v[154:155], v[4:5], 0, vcc
	s_mov_b32 m0, s52
	s_nop 0
	global_load_lds_dwordx4 v[154:155], off
	v_lshl_add_u64 v[154:155], v[6:7], 0, vcc
	s_mov_b32 m0, s53
	s_nop 0
	global_load_lds_dwordx4 v[154:155], off
	s_waitcnt vmcnt(8)
	s_waitcnt lgkmcnt(0)
	s_barrier
; #define PG8_STAGE(bufoff, gbase, voff) do { _Pragma("unroll") for (int _i = 0; _i < 2; ++_i) \
;         __builtin_amdgcn_global_load_lds((const unsigned*)((const char*)(gbase) + (voff)[_i]), (LAS unsigned*)(lds + (bufoff) + ldsw + _i * 8192), 16, 0, 0); } while (0)
; #define PG8_LDA(dst, b, h) do { _Pragma("unroll") for (int m = 0; m < 4; ++m) _Pragma("unroll") for (int k = 0; k < 2; ++k) dst[m][k] = *(const LAS bf16x8*)(lds + PG8_SA(b, h) + aoff + m * 2048 + k * 1024); } while (0)
; #define PG8_LDB(dst, b, h) do { _Pragma("unroll") for (int n = 0; n < 2; ++n) _Pragma("unroll") for (int k = 0; k < 2; ++k) dst[n][k] = *(const LAS bf16x8*)(lds + PG8_SB(b, h) + boff + n * 2048 + k * 1024); } while (0)
; #define PG8_MMA(ai, bj, At, Bt) do { __builtin_amdgcn_s_setprio(1); _Pragma("unroll") for (int m = 0; m < 4; ++m) _Pragma("unroll") for (int n = 0; n < 2; ++n) _Pragma("unroll") for (int k = 0; k < 2; ++k) \
;         acc[ai][bj][m][n] = __builtin_amdgcn_mfma_f32_16x16x32_bf16(Bt[n][k], At[m][k], acc[ai][bj][m][n], 0, 0, 0); __builtin_amdgcn_s_setprio(0); } while (0)
; #define PG8_WAIT_V(n) asm volatile("s_waitcnt vmcnt(" #n ")" ::: "memory")
; template <class Epi, class Sched, bool ALIGN_EPI = true, bool SP2 = true>
; __device__ __forceinline__ void gemm_phase(LAS unsigned char* lds, const Gemm g, const Sched& S, const Epi& E) {
;     ...
;             PG8_LDB(B0, 0, 0); PG8_LDB(B1, 0, 1); PG8_SCHED; PG8_LDA(At, 0, 0); PG8_STAGE(PG8_SA(1, 1), a1 + hstepA, voffA);
;             PG8_WAIT_V(8); PG8_WAIT_L(0); PG8_BAR; PG8_MMA(0, 0, At, B0); PG8_MMA(0, 1, At, B1); PG8_BAR; PG8_SCHED;
;             PG8_LDA(At, 0, 1); PG8_STAGE(PG8_SB(0, 0), b2, voffB); PG8_STAGE(PG8_SB(0, 1), b2 + hstepB, voffB); PG8_STAGE(PG8_SA(0, 0), a2, voffA);
;             PG8_WAIT_V(8); PG8_WAIT_L(0); PG8_BAR; PG8_MMA(1, 0, At, B0); PG8_MMA(1, 1, At, B1); PG8_BAR; PG8_SCHED;
;             PG8_LDB(B0, 1, 0); PG8_LDB(B1, 1, 1); PG8_SCHED; PG8_LDA(At, 1, 0); PG8_STAGE(PG8_SA(0, 1), a2 + hstepA, voffA);
;             PG8_WAIT_V(8); PG8_WAIT_L(0); PG8_BAR; PG8_MMA(0, 0, At, B0); PG8_MMA(0, 1, At, B1); PG8_BAR; PG8_SCHED;
;             PG8_LDA(At, 1, 1); PG8_STAGE(PG8_SB(1, 0), b3, voffB); PG8_STAGE(PG8_SB(1, 1), b3 + hstepB, voffB); PG8_STAGE(PG8_SA(1, 0), a3, voffA);
;             PG8_WAIT_V(8); PG8_WAIT_L(0); PG8_BAR; PG8_MMA(1, 0, At, B0); PG8_MMA(1, 1, At, B1); PG8_BAR; PG8_SCHED;
	s_setprio 1
	s_waitcnt lgkmcnt(0)
	v_mfma_f32_16x16x32_bf16 v[12:15], v[40:43], v[246:249], v[12:15]
	v_mfma_f32_16x16x32_bf16 v[20:23], v[128:131], v[246:249], v[20:23]
	v_mfma_f32_16x16x32_bf16 v[172:175], v[40:43], v[146:149], v[172:175]
	v_mfma_f32_16x16x32_bf16 v[198:201], v[128:131], v[146:149], v[198:201]
	v_mfma_f32_16x16x32_bf16 v[202:205], v[40:43], v[230:233], v[202:205]
	v_mfma_f32_16x16x32_bf16 v[206:209], v[128:131], v[230:233], v[206:209]
	v_mfma_f32_16x16x32_bf16 v[210:213], v[40:43], v[238:241], v[210:213]
	v_mfma_f32_16x16x32_bf16 v[218:221], v[128:131], v[238:241], v[218:221]
	v_mfma_f32_16x16x32_bf16 v[12:15], v[44:47], v[250:253], v[12:15]
	v_mfma_f32_16x16x32_bf16 v[20:23], v[138:141], v[250:253], v[20:23]
	v_mfma_f32_16x16x32_bf16 v[172:175], v[44:47], v[150:153], v[172:175]
	v_mfma_f32_16x16x32_bf16 v[198:201], v[138:141], v[150:153], v[198:201]
	v_mfma_f32_16x16x32_bf16 v[202:205], v[44:47], v[234:237], v[202:205]
	v_mfma_f32_16x16x32_bf16 v[206:209], v[138:141], v[234:237], v[206:209]
	v_mfma_f32_16x16x32_bf16 v[210:213], v[44:47], v[242:245], v[210:213]
	v_mfma_f32_16x16x32_bf16 v[218:221], v[138:141], v[242:245], v[218:221]
	s_setprio 0
	s_setprio 1
	v_mfma_f32_16x16x32_bf16 v[24:27], v[142:145], v[146:149], v[24:27]
	v_mfma_f32_16x16x32_bf16 v[28:31], v[222:225], v[146:149], v[28:31]
	v_mfma_f32_16x16x32_bf16 v[40:43], v[142:145], v[230:233], v[68:71]
	v_mfma_f32_16x16x32_bf16 v[44:47], v[222:225], v[230:233], v[116:119]
	v_mfma_f32_16x16x32_bf16 v[68:71], v[142:145], v[238:241], v[120:123]
	v_mfma_f32_16x16x32_bf16 v[116:119], v[222:225], v[238:241], v[124:127]
	v_mfma_f32_16x16x32_bf16 v[32:35], v[142:145], v[246:249], v[32:35]
	v_mfma_f32_16x16x32_bf16 v[36:39], v[222:225], v[246:249], v[36:39]
	v_mfma_f32_16x16x32_bf16 v[24:27], v[168:171], v[150:153], v[24:27]
	v_mfma_f32_16x16x32_bf16 v[28:31], v[226:229], v[150:153], v[28:31]
	v_mfma_f32_16x16x32_bf16 v[40:43], v[168:171], v[234:237], v[40:43]
	v_mfma_f32_16x16x32_bf16 v[44:47], v[226:229], v[234:237], v[44:47]
	v_mfma_f32_16x16x32_bf16 v[68:71], v[168:171], v[242:245], v[68:71]
	v_mfma_f32_16x16x32_bf16 v[116:119], v[226:229], v[242:245], v[116:119]
	v_mfma_f32_16x16x32_bf16 v[32:35], v[168:171], v[250:253], v[32:35]
	v_mfma_f32_16x16x32_bf16 v[36:39], v[226:229], v[250:253], v[36:39]
	s_setprio 0
	s_barrier
	ds_read_b128 v[120:123], v8
	ds_read_b128 v[124:127], v8 offset:1024
	ds_read_b128 v[128:131], v8 offset:2048
	ds_read_b128 v[138:141], v8 offset:3072
	ds_read_b128 v[142:145], v9
	ds_read_b128 v[146:149], v9 offset:1024
	ds_read_b128 v[150:153], v9 offset:2048
	ds_read_b128 v[168:171], v9 offset:3072
	s_add_u32 s64, s16, 0x30180
	s_addc_u32 s65, s17, 0
	s_mov_b32 m0, s58
	ds_read_b128 v[222:225], v167
	ds_read_b128 v[226:229], v167 offset:1024
	ds_read_b128 v[230:233], v167 offset:2048
	ds_read_b128 v[234:237], v167 offset:3072
	ds_read_b128 v[238:241], v167 offset:4096
	ds_read_b128 v[242:245], v167 offset:5120
	ds_read_b128 v[246:249], v167 offset:6144
	ds_read_b128 v[250:253], v167 offset:7168
	global_load_lds_dwordx4 v16, s[64:65]
	v_lshl_add_u64 v[154:155], s[64:65], 0, v[134:135]
	s_mov_b32 m0, s2
	s_nop 0
	global_load_lds_dwordx4 v[154:155], off
	s_waitcnt vmcnt(8)
	s_waitcnt lgkmcnt(0)
	s_barrier
	s_setprio 1
	s_waitcnt lgkmcnt(0)
	v_mfma_f32_16x16x32_bf16 v[72:75], v[120:123], v[222:225], v[72:75]
	v_mfma_f32_16x16x32_bf16 v[76:79], v[128:131], v[222:225], v[76:79]
	v_mfma_f32_16x16x32_bf16 v[80:83], v[120:123], v[230:233], v[80:83]
	v_mfma_f32_16x16x32_bf16 v[84:87], v[128:131], v[230:233], v[84:87]
	v_mfma_f32_16x16x32_bf16 v[88:91], v[120:123], v[238:241], v[88:91]
	v_mfma_f32_16x16x32_bf16 v[92:95], v[128:131], v[238:241], v[92:95]
	v_mfma_f32_16x16x32_bf16 v[96:99], v[120:123], v[246:249], v[96:99]
	v_mfma_f32_16x16x32_bf16 v[100:103], v[128:131], v[246:249], v[100:103]
	v_mfma_f32_16x16x32_bf16 v[72:75], v[124:127], v[226:229], v[72:75]
	v_mfma_f32_16x16x32_bf16 v[76:79], v[138:141], v[226:229], v[76:79]
	v_mfma_f32_16x16x32_bf16 v[80:83], v[124:127], v[234:237], v[80:83]
	v_mfma_f32_16x16x32_bf16 v[84:87], v[138:141], v[234:237], v[84:87]
	v_mfma_f32_16x16x32_bf16 v[88:91], v[124:127], v[242:245], v[88:91]
	v_mfma_f32_16x16x32_bf16 v[92:95], v[138:141], v[242:245], v[92:95]
	v_mfma_f32_16x16x32_bf16 v[96:99], v[124:127], v[250:253], v[96:99]
	v_mfma_f32_16x16x32_bf16 v[100:103], v[138:141], v[250:253], v[100:103]
	s_setprio 0
	s_setprio 1
	v_mfma_f32_16x16x32_bf16 v[104:107], v[142:145], v[222:225], v[104:107]
	v_mfma_f32_16x16x32_bf16 v[108:111], v[150:153], v[222:225], v[108:111]
	v_mfma_f32_16x16x32_bf16 v[112:115], v[142:145], v[230:233], v[112:115]
	v_mfma_f32_16x16x32_bf16 v[48:51], v[150:153], v[230:233], v[48:51]
	v_mfma_f32_16x16x32_bf16 v[52:55], v[142:145], v[238:241], v[52:55]
	v_mfma_f32_16x16x32_bf16 v[56:59], v[150:153], v[238:241], v[56:59]
	v_mfma_f32_16x16x32_bf16 v[60:63], v[142:145], v[246:249], v[60:63]
	v_mfma_f32_16x16x32_bf16 v[64:67], v[150:153], v[246:249], v[64:67]
	v_mfma_f32_16x16x32_bf16 v[104:107], v[146:149], v[226:229], v[104:107]
	v_mfma_f32_16x16x32_bf16 v[108:111], v[168:171], v[226:229], v[108:111]
	v_mfma_f32_16x16x32_bf16 v[112:115], v[146:149], v[234:237], v[112:115]
	v_mfma_f32_16x16x32_bf16 v[48:51], v[168:171], v[234:237], v[48:51]
	v_mfma_f32_16x16x32_bf16 v[52:55], v[146:149], v[242:245], v[52:55]
	v_mfma_f32_16x16x32_bf16 v[56:59], v[168:171], v[242:245], v[56:59]
	v_mfma_f32_16x16x32_bf16 v[60:63], v[146:149], v[250:253], v[60:63]
	v_mfma_f32_16x16x32_bf16 v[64:67], v[168:171], v[250:253], v[64:67]
	s_setprio 0
	s_barrier
; #define PG8_STAGE(bufoff, gbase, voff) do { _Pragma("unroll") for (int _i = 0; _i < 2; ++_i) \
;         __builtin_amdgcn_global_load_lds((const unsigned*)((const char*)(gbase) + (voff)[_i]), (LAS unsigned*)(lds + (bufoff) + ldsw + _i * 8192), 16, 0, 0); } while (0)
; #define PG8_LDA(dst, b, h) do { _Pragma("unroll") for (int m = 0; m < 4; ++m) _Pragma("unroll") for (int k = 0; k < 2; ++k) dst[m][k] = *(const LAS bf16x8*)(lds + PG8_SA(b, h) + aoff + m * 2048 + k * 1024); } while (0)
; #define PG8_LDB(dst, b, h) do { _Pragma("unroll") for (int n = 0; n < 2; ++n) _Pragma("unroll") for (int k = 0; k < 2; ++k) dst[n][k] = *(const LAS bf16x8*)(lds + PG8_SB(b, h) + boff + n * 2048 + k * 1024); } while (0)
; #define PG8_MMA(ai, bj, At, Bt) do { __builtin_amdgcn_s_setprio(1); _Pragma("unroll") for (int m = 0; m < 4; ++m) _Pragma("unroll") for (int n = 0; n < 2; ++n) _Pragma("unroll") for (int k = 0; k < 2; ++k) \
;         acc[ai][bj][m][n] = __builtin_amdgcn_mfma_f32_16x16x32_bf16(Bt[n][k], At[m][k], acc[ai][bj][m][n], 0, 0, 0); __builtin_amdgcn_s_setprio(0); } while (0)
; #define PG8_WAIT_V(n) asm volatile("s_waitcnt vmcnt(" #n ")" ::: "memory")
; #define PG8_WAIT_L(n) asm volatile("s_waitcnt lgkmcnt(" #n ")" ::: "memory")
; #define PG8_BAR __builtin_amdgcn_s_barrier()
; #define PG8_SCHED __builtin_amdgcn_sched_barrier(0)
; template <class Epi, class Sched, bool ALIGN_EPI = true, bool SP2 = true>
; __device__ __forceinline__ void gemm_phase(LAS unsigned char* lds, const Gemm g, const Sched& S, const Epi& E) {
;     ...
;             PG8_LDA(At, 0, 1); PG8_STAGE(PG8_SB(0, 0), b2, voffB); PG8_STAGE(PG8_SB(0, 1), b2 + hstepB, voffB); PG8_STAGE(PG8_SA(0, 0), a2, voffA);
;             PG8_WAIT_V(8); PG8_WAIT_L(0); PG8_BAR; PG8_MMA(1, 0, At, B0); PG8_MMA(1, 1, At, B1); PG8_BAR; PG8_SCHED;
;             PG8_LDB(B0, 1, 0); PG8_LDB(B1, 1, 1); PG8_SCHED; PG8_LDA(At, 1, 0); PG8_STAGE(PG8_SA(0, 1), a2 + hstepA, voffA);
;             PG8_WAIT_V(8); PG8_WAIT_L(0); PG8_BAR; PG8_MMA(0, 0, At, B0); PG8_MMA(0, 1, At, B1); PG8_BAR; PG8_SCHED;
	s_mov_b64 vcc, 0x200
	s_mov_b32 m0, s42
	v_lshl_add_u64 v[154:155], v[0:1], 0, vcc
	s_add_u32 s64, s44, 0x18200
	ds_read_b128 v[222:225], v167 offset:16384
	ds_read_b128 v[226:229], v167 offset:17408
	ds_read_b128 v[230:233], v167 offset:18432
	ds_read_b128 v[234:237], v167 offset:19456
	ds_read_b128 v[238:241], v167 offset:20480
	ds_read_b128 v[242:245], v167 offset:21504
	ds_read_b128 v[246:249], v167 offset:22528
	ds_read_b128 v[250:253], v167 offset:23552
	global_load_lds_dwordx4 v[154:155], off
	v_lshl_add_u64 v[154:155], v[2:3], 0, vcc
	s_mov_b32 m0, s8
	s_addc_u32 s65, s45, 0
	global_load_lds_dwordx4 v[154:155], off
	s_mov_b32 m0, s9
	s_nop 0
	global_load_lds_dwordx4 v132, s[64:65]
	v_lshl_add_u64 v[154:155], s[64:65], 0, v[136:137]
	s_mov_b32 m0, s30
	s_nop 0
	global_load_lds_dwordx4 v[154:155], off
	v_lshl_add_u64 v[154:155], v[4:5], 0, vcc
	s_mov_b32 m0, s22
	s_nop 0
	global_load_lds_dwordx4 v[154:155], off
	v_lshl_add_u64 v[154:155], v[6:7], 0, vcc
	s_mov_b32 m0, s23
	s_nop 0
	global_load_lds_dwordx4 v[154:155], off
	s_waitcnt vmcnt(8)
	s_waitcnt lgkmcnt(0)
	s_barrier
	s_setprio 1
	s_waitcnt lgkmcnt(0)
	v_mfma_f32_16x16x32_bf16 v[12:15], v[120:123], v[246:249], v[12:15]
	v_mfma_f32_16x16x32_bf16 v[20:23], v[128:131], v[246:249], v[20:23]
	v_mfma_f32_16x16x32_bf16 v[172:175], v[120:123], v[222:225], v[172:175]
	v_mfma_f32_16x16x32_bf16 v[198:201], v[128:131], v[222:225], v[198:201]
	v_mfma_f32_16x16x32_bf16 v[202:205], v[120:123], v[230:233], v[202:205]
	v_mfma_f32_16x16x32_bf16 v[206:209], v[128:131], v[230:233], v[206:209]
	v_mfma_f32_16x16x32_bf16 v[210:213], v[120:123], v[238:241], v[210:213]
	v_mfma_f32_16x16x32_bf16 v[218:221], v[128:131], v[238:241], v[218:221]
	v_mfma_f32_16x16x32_bf16 v[12:15], v[124:127], v[250:253], v[12:15]
	v_mfma_f32_16x16x32_bf16 v[20:23], v[138:141], v[250:253], v[20:23]
	v_mfma_f32_16x16x32_bf16 v[172:175], v[124:127], v[226:229], v[172:175]
	v_mfma_f32_16x16x32_bf16 v[198:201], v[138:141], v[226:229], v[198:201]
	v_mfma_f32_16x16x32_bf16 v[202:205], v[124:127], v[234:237], v[202:205]
	v_mfma_f32_16x16x32_bf16 v[206:209], v[138:141], v[234:237], v[206:209]
	v_mfma_f32_16x16x32_bf16 v[210:213], v[124:127], v[242:245], v[210:213]
	v_mfma_f32_16x16x32_bf16 v[218:221], v[138:141], v[242:245], v[218:221]
	s_setprio 0
	s_setprio 1
	v_mfma_f32_16x16x32_bf16 v[24:27], v[142:145], v[222:225], v[24:27]
	v_mfma_f32_16x16x32_bf16 v[28:31], v[150:153], v[222:225], v[28:31]
	v_mfma_f32_16x16x32_bf16 v[40:43], v[142:145], v[230:233], v[40:43]
	v_mfma_f32_16x16x32_bf16 v[44:47], v[150:153], v[230:233], v[44:47]
	v_mfma_f32_16x16x32_bf16 v[68:71], v[142:145], v[238:241], v[68:71]
	v_mfma_f32_16x16x32_bf16 v[116:119], v[150:153], v[238:241], v[116:119]
	v_mfma_f32_16x16x32_bf16 v[32:35], v[142:145], v[246:249], v[32:35]
	v_mfma_f32_16x16x32_bf16 v[36:39], v[150:153], v[246:249], v[36:39]
	v_mfma_f32_16x16x32_bf16 v[24:27], v[146:149], v[226:229], v[24:27]
	v_mfma_f32_16x16x32_bf16 v[28:31], v[168:171], v[226:229], v[28:31]
	v_mfma_f32_16x16x32_bf16 v[40:43], v[146:149], v[234:237], v[40:43]
	v_mfma_f32_16x16x32_bf16 v[44:47], v[168:171], v[234:237], v[44:47]
	v_mfma_f32_16x16x32_bf16 v[68:71], v[146:149], v[242:245], v[68:71]
	v_mfma_f32_16x16x32_bf16 v[116:119], v[168:171], v[242:245], v[116:119]
	v_mfma_f32_16x16x32_bf16 v[32:35], v[146:149], v[250:253], v[32:35]
	v_mfma_f32_16x16x32_bf16 v[36:39], v[168:171], v[250:253], v[36:39]
	s_setprio 0
	s_barrier
	ds_read_b128 v[120:123], v10
	ds_read_b128 v[124:127], v10 offset:1024
	ds_read_b128 v[128:131], v10 offset:2048
	ds_read_b128 v[138:141], v10 offset:3072
	ds_read_b128 v[142:145], v11
	ds_read_b128 v[146:149], v11 offset:1024
	ds_read_b128 v[150:153], v11 offset:2048
	ds_read_b128 v[168:171], v11 offset:3072
	s_add_u32 s64, s16, 0x30200
	s_addc_u32 s65, s17, 0
	s_mov_b32 m0, s24
	ds_read_b128 v[222:225], v167 offset:32768
	ds_read_b128 v[226:229], v167 offset:33792
	ds_read_b128 v[230:233], v167 offset:34816
	ds_read_b128 v[234:237], v167 offset:35840
	ds_read_b128 v[238:241], v167 offset:36864
	ds_read_b128 v[242:245], v167 offset:37888
	ds_read_b128 v[246:249], v167 offset:38912
	ds_read_b128 v[250:253], v167 offset:39936
	global_load_lds_dwordx4 v16, s[64:65]
	s_mov_b32 m0, s31
	s_nop 0
	global_load_lds_dwordx4 v134, s[64:65]
	s_waitcnt vmcnt(8)
	s_waitcnt lgkmcnt(0)
	s_barrier
	s_setprio 1
	s_waitcnt lgkmcnt(0)
	v_mfma_f32_16x16x32_bf16 v[72:75], v[120:123], v[222:225], v[72:75]
	v_mfma_f32_16x16x32_bf16 v[76:79], v[128:131], v[222:225], v[76:79]
	v_mfma_f32_16x16x32_bf16 v[80:83], v[120:123], v[230:233], v[80:83]
	v_mfma_f32_16x16x32_bf16 v[84:87], v[128:131], v[230:233], v[84:87]
	v_mfma_f32_16x16x32_bf16 v[88:91], v[120:123], v[238:241], v[88:91]
	v_mfma_f32_16x16x32_bf16 v[92:95], v[128:131], v[238:241], v[92:95]
	v_mfma_f32_16x16x32_bf16 v[96:99], v[120:123], v[246:249], v[96:99]
	v_mfma_f32_16x16x32_bf16 v[100:103], v[128:131], v[246:249], v[100:103]
	v_mfma_f32_16x16x32_bf16 v[72:75], v[124:127], v[226:229], v[72:75]
	v_mfma_f32_16x16x32_bf16 v[76:79], v[138:141], v[226:229], v[76:79]
	v_mfma_f32_16x16x32_bf16 v[80:83], v[124:127], v[234:237], v[80:83]
	v_mfma_f32_16x16x32_bf16 v[84:87], v[138:141], v[234:237], v[84:87]
	v_mfma_f32_16x16x32_bf16 v[88:91], v[124:127], v[242:245], v[88:91]
	v_mfma_f32_16x16x32_bf16 v[92:95], v[138:141], v[242:245], v[92:95]
	v_mfma_f32_16x16x32_bf16 v[96:99], v[124:127], v[250:253], v[96:99]
	v_mfma_f32_16x16x32_bf16 v[100:103], v[138:141], v[250:253], v[100:103]
	s_setprio 0
	s_setprio 1
	v_mfma_f32_16x16x32_bf16 v[104:107], v[142:145], v[222:225], v[104:107]
	v_mfma_f32_16x16x32_bf16 v[108:111], v[150:153], v[222:225], v[108:111]
	v_mfma_f32_16x16x32_bf16 v[112:115], v[142:145], v[230:233], v[112:115]
	v_mfma_f32_16x16x32_bf16 v[48:51], v[150:153], v[230:233], v[48:51]
	v_mfma_f32_16x16x32_bf16 v[52:55], v[142:145], v[238:241], v[52:55]
	v_mfma_f32_16x16x32_bf16 v[56:59], v[150:153], v[238:241], v[56:59]
	v_mfma_f32_16x16x32_bf16 v[60:63], v[142:145], v[246:249], v[60:63]
	v_mfma_f32_16x16x32_bf16 v[64:67], v[150:153], v[246:249], v[64:67]
	v_mfma_f32_16x16x32_bf16 v[104:107], v[146:149], v[226:229], v[104:107]
	v_mfma_f32_16x16x32_bf16 v[108:111], v[168:171], v[226:229], v[108:111]
	v_mfma_f32_16x16x32_bf16 v[112:115], v[146:149], v[234:237], v[112:115]
	v_mfma_f32_16x16x32_bf16 v[48:51], v[168:171], v[234:237], v[48:51]
	v_mfma_f32_16x16x32_bf16 v[52:55], v[146:149], v[242:245], v[52:55]
	v_mfma_f32_16x16x32_bf16 v[56:59], v[168:171], v[242:245], v[56:59]
	v_mfma_f32_16x16x32_bf16 v[60:63], v[146:149], v[250:253], v[60:63]
	v_mfma_f32_16x16x32_bf16 v[64:67], v[168:171], v[250:253], v[64:67]
	s_setprio 0
	s_barrier
; #define PG8_STAGE(bufoff, gbase, voff) do { _Pragma("unroll") for (int _i = 0; _i < 2; ++_i) \
;         __builtin_amdgcn_global_load_lds((const unsigned*)((const char*)(gbase) + (voff)[_i]), (LAS unsigned*)(lds + (bufoff) + ldsw + _i * 8192), 16, 0, 0); } while (0)
; #define PG8_LDA(dst, b, h) do { _Pragma("unroll") for (int m = 0; m < 4; ++m) _Pragma("unroll") for (int k = 0; k < 2; ++k) dst[m][k] = *(const LAS bf16x8*)(lds + PG8_SA(b, h) + aoff + m * 2048 + k * 1024); } while (0)
; #define PG8_LDB(dst, b, h) do { _Pragma("unroll") for (int n = 0; n < 2; ++n) _Pragma("unroll") for (int k = 0; k < 2; ++k) dst[n][k] = *(const LAS bf16x8*)(lds + PG8_SB(b, h) + boff + n * 2048 + k * 1024); } while (0)
; #define PG8_MMA(ai, bj, At, Bt) do { __builtin_amdgcn_s_setprio(1); _Pragma("unroll") for (int m = 0; m < 4; ++m) _Pragma("unroll") for (int n = 0; n < 2; ++n) _Pragma("unroll") for (int k = 0; k < 2; ++k) \
;         acc[ai][bj][m][n] = __builtin_amdgcn_mfma_f32_16x16x32_bf16(Bt[n][k], At[m][k], acc[ai][bj][m][n], 0, 0, 0); __builtin_amdgcn_s_setprio(0); } while (0)
; #define PG8_WAIT_V(n) asm volatile("s_waitcnt vmcnt(" #n ")" ::: "memory")
; template <class Epi, class Sched, bool ALIGN_EPI = true, bool SP2 = true>
; __device__ __forceinline__ void gemm_phase(LAS unsigned char* lds, const Gemm g, const Sched& S, const Epi& E) {
;     ...
;             PG8_LDB(B0, 0, 0); PG8_LDB(B1, 0, 1); PG8_SCHED; PG8_LDA(At, 0, 0); PG8_STAGE(PG8_SA(1, 1), a1 + hstepA, voffA);
;             PG8_WAIT_V(8); PG8_WAIT_L(0); PG8_BAR; PG8_MMA(0, 0, At, B0); PG8_MMA(0, 1, At, B1); PG8_BAR; PG8_SCHED;
;             PG8_LDA(At, 0, 1); PG8_STAGE(PG8_SB(0, 0), b2, voffB); PG8_STAGE(PG8_SB(0, 1), b2 + hstepB, voffB); PG8_STAGE(PG8_SA(0, 0), a2, voffA);
;             PG8_WAIT_V(8); PG8_WAIT_L(0); PG8_BAR; PG8_MMA(1, 0, At, B0); PG8_MMA(1, 1, At, B1); PG8_BAR; PG8_SCHED;
;             PG8_LDB(B0, 1, 0); PG8_LDB(B1, 1, 1); PG8_SCHED; PG8_LDA(At, 1, 0); PG8_STAGE(PG8_SA(0, 1), a2 + hstepA, voffA);
;             PG8_WAIT_V(8); PG8_WAIT_L(0); PG8_BAR; PG8_MMA(0, 0, At, B0); PG8_MMA(0, 1, At, B1); PG8_BAR; PG8_SCHED;
;             PG8_LDA(At, 1, 1); PG8_STAGE(PG8_SB(1, 0), b3, voffB); PG8_STAGE(PG8_SB(1, 1), b3 + hstepB, voffB); PG8_STAGE(PG8_SA(1, 0), a3, voffA);
;             PG8_WAIT_V(8); PG8_WAIT_L(0); PG8_BAR; PG8_MMA(1, 0, At, B0); PG8_MMA(1, 1, At, B1); PG8_BAR; PG8_SCHED;
	s_mov_b64 s[64:65], 0x280
	s_mov_b32 m0, s61
	v_lshl_add_u64 v[0:1], v[0:1], 0, s[64:65]
	s_add_u32 s44, s44, 0x18280
	ds_read_b128 v[222:225], v167 offset:49152
	ds_read_b128 v[226:229], v167 offset:50176
	ds_read_b128 v[230:233], v167 offset:51200
	ds_read_b128 v[234:237], v167 offset:52224
	ds_read_b128 v[238:241], v167 offset:53248
	ds_read_b128 v[242:245], v167 offset:54272
	ds_read_b128 v[246:249], v167 offset:55296
	ds_read_b128 v[250:253], v167 offset:56320
	global_load_lds_dwordx4 v[0:1], off
	v_lshl_add_u64 v[0:1], v[2:3], 0, s[64:65]
	s_mov_b32 m0, s43
	s_addc_u32 s45, s45, 0
	global_load_lds_dwordx4 v[0:1], off
	s_mov_b32 m0, s57
	s_nop 0
	global_load_lds_dwordx4 v132, s[44:45]
	v_lshl_add_u64 v[0:1], s[44:45], 0, v[136:137]
	s_mov_b32 m0, s59
	s_nop 0
	global_load_lds_dwordx4 v[0:1], off
	v_lshl_add_u64 v[0:1], v[4:5], 0, s[64:65]
	s_mov_b32 m0, s52
	s_nop 0
	global_load_lds_dwordx4 v[0:1], off
	v_lshl_add_u64 v[0:1], v[6:7], 0, s[64:65]
	s_mov_b32 m0, s53
	s_nop 0
	global_load_lds_dwordx4 v[0:1], off
	s_waitcnt vmcnt(8)
	s_waitcnt lgkmcnt(0)
	s_barrier
	s_setprio 1
	s_waitcnt lgkmcnt(0)
	v_mfma_f32_16x16x32_bf16 v[0:3], v[120:123], v[222:225], v[172:175]
	v_mfma_f32_16x16x32_bf16 v[4:7], v[128:131], v[222:225], v[198:201]
	v_mfma_f32_16x16x32_bf16 v[12:15], v[120:123], v[246:249], v[12:15]
	v_mfma_f32_16x16x32_bf16 v[20:23], v[128:131], v[246:249], v[20:23]
	v_mfma_f32_16x16x32_bf16 v[0:3], v[124:127], v[226:229], v[0:3]
	v_mfma_f32_16x16x32_bf16 v[4:7], v[138:141], v[226:229], v[4:7]
	v_mfma_f32_16x16x32_bf16 v[172:175], v[120:123], v[230:233], v[202:205]
	v_mfma_f32_16x16x32_bf16 v[198:201], v[128:131], v[230:233], v[206:209]
	v_mfma_f32_16x16x32_bf16 v[202:205], v[120:123], v[238:241], v[210:213]
	v_mfma_f32_16x16x32_bf16 v[206:209], v[128:131], v[238:241], v[218:221]
	v_mfma_f32_16x16x32_bf16 v[12:15], v[124:127], v[250:253], v[12:15]
	v_mfma_f32_16x16x32_bf16 v[20:23], v[138:141], v[250:253], v[20:23]
	v_mfma_f32_16x16x32_bf16 v[172:175], v[124:127], v[234:237], v[172:175]
	v_mfma_f32_16x16x32_bf16 v[198:201], v[138:141], v[234:237], v[198:201]
	v_mfma_f32_16x16x32_bf16 v[202:205], v[124:127], v[242:245], v[202:205]
	v_mfma_f32_16x16x32_bf16 v[206:209], v[138:141], v[242:245], v[206:209]
	s_setprio 0
	s_setprio 1
	v_mfma_f32_16x16x32_bf16 v[24:27], v[142:145], v[222:225], v[24:27]
	v_mfma_f32_16x16x32_bf16 v[28:31], v[150:153], v[222:225], v[28:31]
	v_mfma_f32_16x16x32_bf16 v[40:43], v[142:145], v[230:233], v[40:43]
	v_mfma_f32_16x16x32_bf16 v[44:47], v[150:153], v[230:233], v[44:47]
	v_mfma_f32_16x16x32_bf16 v[68:71], v[142:145], v[238:241], v[68:71]
	v_mfma_f32_16x16x32_bf16 v[116:119], v[150:153], v[238:241], v[116:119]
	v_mfma_f32_16x16x32_bf16 v[32:35], v[142:145], v[246:249], v[32:35]
	v_mfma_f32_16x16x32_bf16 v[36:39], v[150:153], v[246:249], v[36:39]
	v_mfma_f32_16x16x32_bf16 v[24:27], v[146:149], v[226:229], v[24:27]
	v_mfma_f32_16x16x32_bf16 v[28:31], v[168:171], v[226:229], v[28:31]
	v_mfma_f32_16x16x32_bf16 v[40:43], v[146:149], v[234:237], v[40:43]
	v_mfma_f32_16x16x32_bf16 v[44:47], v[168:171], v[234:237], v[44:47]
	v_mfma_f32_16x16x32_bf16 v[68:71], v[146:149], v[242:245], v[68:71]
	v_mfma_f32_16x16x32_bf16 v[116:119], v[168:171], v[242:245], v[116:119]
	v_mfma_f32_16x16x32_bf16 v[32:35], v[146:149], v[250:253], v[32:35]
	v_mfma_f32_16x16x32_bf16 v[36:39], v[168:171], v[250:253], v[36:39]
	s_setprio 0
	s_barrier
	ds_read_b128 v[120:123], v8
	ds_read_b128 v[124:127], v8 offset:1024
	ds_read_b128 v[128:131], v8 offset:2048
	ds_read_b128 v[138:141], v8 offset:3072
	ds_read_b128 v[142:145], v9
	ds_read_b128 v[146:149], v9 offset:1024
	ds_read_b128 v[150:153], v9 offset:2048
	ds_read_b128 v[168:171], v9 offset:3072
	s_add_u32 s16, s16, 0x30280
	s_addc_u32 s17, s17, 0
	s_mov_b32 m0, s58
	ds_read_b128 v[210:213], v167
	ds_read_b128 v[218:221], v167 offset:1024
	ds_read_b128 v[222:225], v167 offset:2048
	ds_read_b128 v[226:229], v167 offset:3072
	ds_read_b128 v[230:233], v167 offset:4096
	ds_read_b128 v[234:237], v167 offset:5120
	ds_read_b128 v[238:241], v167 offset:6144
	ds_read_b128 v[242:245], v167 offset:7168
	global_load_lds_dwordx4 v16, s[16:17]
	s_mov_b32 m0, s2
	s_nop 0
	global_load_lds_dwordx4 v134, s[16:17]
	s_waitcnt vmcnt(8)
	s_waitcnt lgkmcnt(0)
	s_barrier
	s_setprio 1
	s_waitcnt lgkmcnt(0)
	v_mfma_f32_16x16x32_bf16 v[96:99], v[120:123], v[238:241], v[96:99]
	v_mfma_f32_16x16x32_bf16 v[72:75], v[120:123], v[210:213], v[72:75]
	v_mfma_f32_16x16x32_bf16 v[76:79], v[128:131], v[210:213], v[76:79]
	v_mfma_f32_16x16x32_bf16 v[80:83], v[120:123], v[222:225], v[80:83]
	v_mfma_f32_16x16x32_bf16 v[84:87], v[128:131], v[222:225], v[84:87]
	v_mfma_f32_16x16x32_bf16 v[88:91], v[120:123], v[230:233], v[88:91]
	v_mfma_f32_16x16x32_bf16 v[92:95], v[128:131], v[230:233], v[92:95]
	v_mfma_f32_16x16x32_bf16 v[246:249], v[124:127], v[242:245], v[96:99]
	v_mfma_f32_16x16x32_bf16 v[96:99], v[128:131], v[238:241], v[100:103]
	v_mfma_f32_16x16x32_bf16 v[72:75], v[124:127], v[218:221], v[72:75]
	v_mfma_f32_16x16x32_bf16 v[76:79], v[138:141], v[218:221], v[76:79]
	v_mfma_f32_16x16x32_bf16 v[80:83], v[124:127], v[226:229], v[80:83]
	v_mfma_f32_16x16x32_bf16 v[84:87], v[138:141], v[226:229], v[84:87]
	v_mfma_f32_16x16x32_bf16 v[88:91], v[124:127], v[234:237], v[88:91]
	v_mfma_f32_16x16x32_bf16 v[92:95], v[138:141], v[234:237], v[92:95]
	v_mfma_f32_16x16x32_bf16 v[100:103], v[138:141], v[242:245], v[96:99]
	s_setprio 0
	s_setprio 1
	v_mfma_f32_16x16x32_bf16 v[96:99], v[142:145], v[210:213], v[104:107]
	v_mfma_f32_16x16x32_bf16 v[104:107], v[146:149], v[218:221], v[96:99]
	v_mfma_f32_16x16x32_bf16 v[96:99], v[150:153], v[210:213], v[108:111]
	v_mfma_f32_16x16x32_bf16 v[48:51], v[150:153], v[222:225], v[48:51]
	v_mfma_f32_16x16x32_bf16 v[52:55], v[142:145], v[230:233], v[52:55]
	v_mfma_f32_16x16x32_bf16 v[56:59], v[150:153], v[230:233], v[56:59]
	v_mfma_f32_16x16x32_bf16 v[60:63], v[142:145], v[238:241], v[60:63]
	v_mfma_f32_16x16x32_bf16 v[64:67], v[150:153], v[238:241], v[64:67]
	v_mfma_f32_16x16x32_bf16 v[210:213], v[168:171], v[218:221], v[96:99]
	v_mfma_f32_16x16x32_bf16 v[96:99], v[142:145], v[222:225], v[112:115]
	v_mfma_f32_16x16x32_bf16 v[48:51], v[168:171], v[226:229], v[48:51]
	v_mfma_f32_16x16x32_bf16 v[52:55], v[146:149], v[234:237], v[52:55]
	v_mfma_f32_16x16x32_bf16 v[56:59], v[168:171], v[234:237], v[56:59]
	v_mfma_f32_16x16x32_bf16 v[60:63], v[146:149], v[242:245], v[60:63]
	v_mfma_f32_16x16x32_bf16 v[64:67], v[168:171], v[242:245], v[64:67]
	v_mfma_f32_16x16x32_bf16 v[218:221], v[146:149], v[226:229], v[96:99]
	s_setprio 0
	s_barrier
; #define PG8_STAGE(bufoff, gbase, voff) do { _Pragma("unroll") for (int _i = 0; _i < 2; ++_i) \
;         __builtin_amdgcn_global_load_lds((const unsigned*)((const char*)(gbase) + (voff)[_i]), (LAS unsigned*)(lds + (bufoff) + ldsw + _i * 8192), 16, 0, 0); } while (0)
; #define PG8_LDA(dst, b, h) do { _Pragma("unroll") for (int m = 0; m < 4; ++m) _Pragma("unroll") for (int k = 0; k < 2; ++k) dst[m][k] = *(const LAS bf16x8*)(lds + PG8_SA(b, h) + aoff + m * 2048 + k * 1024); } while (0)
; #define PG8_LDB(dst, b, h) do { _Pragma("unroll") for (int n = 0; n < 2; ++n) _Pragma("unroll") for (int k = 0; k < 2; ++k) dst[n][k] = *(const LAS bf16x8*)(lds + PG8_SB(b, h) + boff + n * 2048 + k * 1024); } while (0)
; #define PG8_MMA(ai, bj, At, Bt) do { __builtin_amdgcn_s_setprio(1); _Pragma("unroll") for (int m = 0; m < 4; ++m) _Pragma("unroll") for (int n = 0; n < 2; ++n) _Pragma("unroll") for (int k = 0; k < 2; ++k) \
;         acc[ai][bj][m][n] = __builtin_amdgcn_mfma_f32_16x16x32_bf16(Bt[n][k], At[m][k], acc[ai][bj][m][n], 0, 0, 0); __builtin_amdgcn_s_setprio(0); } while (0)
; #define PG8_WAIT_V(n) asm volatile("s_waitcnt vmcnt(" #n ")" ::: "memory")
; #define PG8_WAIT_L(n) asm volatile("s_waitcnt lgkmcnt(" #n ")" ::: "memory")
; #define PG8_BAR __builtin_amdgcn_s_barrier()
; #define PG8_SCHED __builtin_amdgcn_sched_barrier(0)
; template <class Epi, class Sched, bool ALIGN_EPI = true, bool SP2 = true>
; __device__ __forceinline__ void gemm_phase(LAS unsigned char* lds, const Gemm g, const Sched& S, const Epi& E) {
;     ...
;             PG8_LDA(At, 0, 1); PG8_STAGE(PG8_SB(0, 0), b2, voffB); PG8_STAGE(PG8_SB(0, 1), b2 + hstepB, voffB); PG8_STAGE(PG8_SA(0, 0), a2, voffA);
;             PG8_WAIT_V(8); PG8_WAIT_L(0); PG8_BAR; PG8_MMA(1, 0, At, B0); PG8_MMA(1, 1, At, B1); PG8_BAR; PG8_SCHED;
;             PG8_LDB(B0, 1, 0); PG8_LDB(B1, 1, 1); PG8_SCHED; PG8_LDA(At, 1, 0); PG8_STAGE(PG8_SA(0, 1), a2 + hstepA, voffA);
;             PG8_WAIT_V(8); PG8_WAIT_L(0); PG8_BAR; PG8_MMA(0, 0, At, B0); PG8_MMA(0, 1, At, B1); PG8_BAR; PG8_SCHED;
	s_mov_b32 m0, s42
	v_lshl_add_u64 v[176:177], s[34:35], 0, v[132:133]
	s_add_u32 s16, s34, 0x18000
	ds_read_b128 v[96:99], v167 offset:16384
	ds_read_b128 v[108:111], v167 offset:17408
	ds_read_b128 v[112:115], v167 offset:18432
	ds_read_b128 v[222:225], v167 offset:19456
	ds_read_b128 v[226:229], v167 offset:20480
	ds_read_b128 v[230:233], v167 offset:21504
	ds_read_b128 v[234:237], v167 offset:22528
	ds_read_b128 v[238:241], v167 offset:23552
	global_load_lds_dwordx4 v[176:177], off
	v_lshl_add_u64 v[214:215], s[34:35], 0, v[136:137]
	s_mov_b32 m0, s8
	s_addc_u32 s17, s35, 0
	global_load_lds_dwordx4 v[214:215], off
	s_mov_b32 m0, s9
	v_lshl_add_u64 v[182:183], s[46:47], 0, v[16:17]
	global_load_lds_dwordx4 v132, s[16:17]
	s_mov_b32 m0, s30
	v_lshl_add_u64 v[178:179], s[46:47], 0, v[134:135]
	global_load_lds_dwordx4 v136, s[16:17]
	s_mov_b32 m0, s22
	s_nop 0
	global_load_lds_dwordx4 v[182:183], off
	s_mov_b32 m0, s23
	s_nop 0
	global_load_lds_dwordx4 v[178:179], off
	s_waitcnt vmcnt(8)
	s_waitcnt lgkmcnt(0)
	s_barrier
	s_setprio 1
	s_waitcnt lgkmcnt(0)
	v_mfma_f32_16x16x32_bf16 v[0:3], v[120:123], v[96:99], v[0:3]
	v_mfma_f32_16x16x32_bf16 v[4:7], v[128:131], v[96:99], v[4:7]
	v_mfma_f32_16x16x32_bf16 v[12:15], v[120:123], v[234:237], v[12:15]
	v_mfma_f32_16x16x32_bf16 v[20:23], v[128:131], v[234:237], v[20:23]
	v_mfma_f32_16x16x32_bf16 v[0:3], v[124:127], v[108:111], v[0:3]
	v_mfma_f32_16x16x32_bf16 v[4:7], v[138:141], v[108:111], v[4:7]
	v_mfma_f32_16x16x32_bf16 v[172:175], v[120:123], v[112:115], v[172:175]
	v_mfma_f32_16x16x32_bf16 v[198:201], v[128:131], v[112:115], v[198:201]
	v_mfma_f32_16x16x32_bf16 v[202:205], v[120:123], v[226:229], v[202:205]
	v_mfma_f32_16x16x32_bf16 v[206:209], v[128:131], v[226:229], v[206:209]
	v_mfma_f32_16x16x32_bf16 v[12:15], v[124:127], v[238:241], v[12:15]
	v_mfma_f32_16x16x32_bf16 v[20:23], v[138:141], v[238:241], v[20:23]
	v_mfma_f32_16x16x32_bf16 v[172:175], v[124:127], v[222:225], v[172:175]
	v_mfma_f32_16x16x32_bf16 v[198:201], v[138:141], v[222:225], v[198:201]
	v_mfma_f32_16x16x32_bf16 v[202:205], v[124:127], v[230:233], v[202:205]
	v_mfma_f32_16x16x32_bf16 v[206:209], v[138:141], v[230:233], v[206:209]
	s_setprio 0
	s_setprio 1
	v_mfma_f32_16x16x32_bf16 v[28:31], v[150:153], v[96:99], v[28:31]
	v_mfma_f32_16x16x32_bf16 v[138:141], v[168:171], v[108:111], v[28:31]
	v_mfma_f32_16x16x32_bf16 v[28:31], v[142:145], v[112:115], v[40:43]
	v_mfma_f32_16x16x32_bf16 v[40:43], v[146:149], v[222:225], v[28:31]
	v_mfma_f32_16x16x32_bf16 v[28:31], v[150:153], v[112:115], v[44:47]
	v_mfma_f32_16x16x32_bf16 v[222:225], v[168:171], v[222:225], v[28:31]
	v_mfma_f32_16x16x32_bf16 v[28:31], v[142:145], v[226:229], v[68:71]
	v_mfma_f32_16x16x32_bf16 v[242:245], v[146:149], v[230:233], v[28:31]
	v_mfma_f32_16x16x32_bf16 v[28:31], v[150:153], v[226:229], v[116:119]
	v_mfma_f32_16x16x32_bf16 v[24:27], v[142:145], v[96:99], v[24:27]
	v_mfma_f32_16x16x32_bf16 v[226:229], v[168:171], v[230:233], v[28:31]
	v_mfma_f32_16x16x32_bf16 v[28:31], v[142:145], v[234:237], v[32:35]
	v_mfma_f32_16x16x32_bf16 v[24:27], v[146:149], v[108:111], v[24:27]
	v_mfma_f32_16x16x32_bf16 v[142:145], v[146:149], v[238:241], v[28:31]
	v_mfma_f32_16x16x32_bf16 v[28:31], v[150:153], v[234:237], v[36:39]
	v_mfma_f32_16x16x32_bf16 v[146:149], v[168:171], v[238:241], v[28:31]
	s_setprio 0
	s_barrier
	ds_read_b128 v[36:39], v10
	ds_read_b128 v[150:153], v10 offset:1024
	ds_read_b128 v[168:171], v10 offset:2048
	ds_read_b128 v[230:233], v10 offset:3072
	ds_read_b128 v[234:237], v11
	ds_read_b128 v[238:241], v11 offset:1024
	ds_read_b128 v[250:253], v11 offset:2048
	ds_read_b128 v[154:157], v11 offset:3072
	s_add_u32 s8, s46, 0x30000
	s_addc_u32 s9, s47, 0
	s_mov_b32 m0, s24
	ds_read_b128 v[8:11], v167 offset:32768
	ds_read_b128 v[28:31], v167 offset:33792
	ds_read_b128 v[32:35], v167 offset:34816
	ds_read_b128 v[44:47], v167 offset:35840
	ds_read_b128 v[68:71], v167 offset:36864
	ds_read_b128 v[186:189], v167 offset:37888
	ds_read_b128 v[190:193], v167 offset:38912
	ds_read_b128 v[158:161], v167 offset:39936
	global_load_lds_dwordx4 v16, s[8:9]
	v_lshl_add_u64 v[96:97], s[8:9], 0, v[134:135]
	s_mov_b32 m0, s31
	s_nop 0
	global_load_lds_dwordx4 v[96:97], off
	s_waitcnt vmcnt(8)
	s_waitcnt lgkmcnt(0)
	s_barrier
; #define PG8_STAGE(bufoff, gbase, voff) do { _Pragma("unroll") for (int _i = 0; _i < 2; ++_i) \
;         __builtin_amdgcn_global_load_lds((const unsigned*)((const char*)(gbase) + (voff)[_i]), (LAS unsigned*)(lds + (bufoff) + ldsw + _i * 8192), 16, 0, 0); } while (0)
; #define PG8_LDA(dst, b, h) do { _Pragma("unroll") for (int m = 0; m < 4; ++m) _Pragma("unroll") for (int k = 0; k < 2; ++k) dst[m][k] = *(const LAS bf16x8*)(lds + PG8_SA(b, h) + aoff + m * 2048 + k * 1024); } while (0)
; #define PG8_MMA(ai, bj, At, Bt) do { __builtin_amdgcn_s_setprio(1); _Pragma("unroll") for (int m = 0; m < 4; ++m) _Pragma("unroll") for (int n = 0; n < 2; ++n) _Pragma("unroll") for (int k = 0; k < 2; ++k) \
;         acc[ai][bj][m][n] = __builtin_amdgcn_mfma_f32_16x16x32_bf16(Bt[n][k], At[m][k], acc[ai][bj][m][n], 0, 0, 0); __builtin_amdgcn_s_setprio(0); } while (0)
; #define PG8_WAIT_V(n) asm volatile("s_waitcnt vmcnt(" #n ")" ::: "memory")
; #define PG8_WAIT_L(n) asm volatile("s_waitcnt lgkmcnt(" #n ")" ::: "memory")
; #define PG8_BAR __builtin_amdgcn_s_barrier()
; #define PG8_SCHED __builtin_amdgcn_sched_barrier(0)
; template <class Epi, class Sched, bool ALIGN_EPI = true, bool SP2 = true>
; __device__ __forceinline__ void gemm_phase(LAS unsigned char* lds, const Gemm g, const Sched& S, const Epi& E) {
;     ...
;             PG8_WAIT_V(8); PG8_WAIT_L(0); PG8_BAR; PG8_MMA(0, 0, At, B0); PG8_MMA(0, 1, At, B1); PG8_BAR; PG8_SCHED;
;             PG8_LDA(At, 1, 1); PG8_STAGE(PG8_SB(1, 0), b3, voffB); PG8_STAGE(PG8_SB(1, 1), b3 + hstepB, voffB); PG8_STAGE(PG8_SA(1, 0), a3, voffA);
;             PG8_WAIT_V(8); PG8_WAIT_L(0); PG8_BAR; PG8_MMA(1, 0, At, B0); PG8_MMA(1, 1, At, B1); PG8_BAR; PG8_SCHED;
;         }
	s_setprio 1
	s_waitcnt lgkmcnt(0)
	v_mfma_f32_16x16x32_bf16 v[72:75], v[36:39], v[8:11], v[72:75]
	v_mfma_f32_16x16x32_bf16 v[124:127], v[150:153], v[28:31], v[72:75]
	v_mfma_f32_16x16x32_bf16 v[72:75], v[168:171], v[8:11], v[76:79]
	v_mfma_f32_16x16x32_bf16 v[128:131], v[230:233], v[28:31], v[72:75]
	v_mfma_f32_16x16x32_bf16 v[72:75], v[36:39], v[32:35], v[80:83]
	v_mfma_f32_16x16x32_bf16 v[112:115], v[150:153], v[44:47], v[72:75]
	v_mfma_f32_16x16x32_bf16 v[72:75], v[168:171], v[32:35], v[84:87]
	v_mfma_f32_16x16x32_bf16 v[108:111], v[230:233], v[44:47], v[72:75]
	v_mfma_f32_16x16x32_bf16 v[72:75], v[36:39], v[68:71], v[88:91]
	v_mfma_f32_16x16x32_bf16 v[96:99], v[150:153], v[186:189], v[72:75]
	v_mfma_f32_16x16x32_bf16 v[72:75], v[168:171], v[68:71], v[92:95]
	v_mfma_f32_16x16x32_bf16 v[92:95], v[230:233], v[186:189], v[72:75]
	v_mfma_f32_16x16x32_bf16 v[72:75], v[36:39], v[190:193], v[246:249]
	v_mfma_f32_16x16x32_bf16 v[80:83], v[150:153], v[158:161], v[72:75]
	v_mfma_f32_16x16x32_bf16 v[72:75], v[168:171], v[190:193], v[100:103]
	v_mfma_f32_16x16x32_bf16 v[76:79], v[230:233], v[158:161], v[72:75]
	s_setprio 0
	s_setprio 1
	v_mfma_f32_16x16x32_bf16 v[72:75], v[234:237], v[8:11], v[104:107]
	v_mfma_f32_16x16x32_bf16 v[8:11], v[250:253], v[8:11], v[210:213]
	v_mfma_f32_16x16x32_bf16 v[116:119], v[154:157], v[28:31], v[8:11]
	v_mfma_f32_16x16x32_bf16 v[8:11], v[234:237], v[32:35], v[218:221]
	v_mfma_f32_16x16x32_bf16 v[104:107], v[238:241], v[44:47], v[8:11]
	v_mfma_f32_16x16x32_bf16 v[8:11], v[250:253], v[32:35], v[48:51]
	v_mfma_f32_16x16x32_bf16 v[100:103], v[154:157], v[44:47], v[8:11]
	v_mfma_f32_16x16x32_bf16 v[8:11], v[234:237], v[68:71], v[52:55]
	v_mfma_f32_16x16x32_bf16 v[88:91], v[238:241], v[186:189], v[8:11]
	v_mfma_f32_16x16x32_bf16 v[8:11], v[250:253], v[68:71], v[56:59]
	v_mfma_f32_16x16x32_bf16 v[84:87], v[154:157], v[186:189], v[8:11]
	v_mfma_f32_16x16x32_bf16 v[8:11], v[234:237], v[190:193], v[60:63]
	v_mfma_f32_16x16x32_bf16 v[120:123], v[238:241], v[28:31], v[72:75]
	v_mfma_f32_16x16x32_bf16 v[72:75], v[238:241], v[158:161], v[8:11]
	v_mfma_f32_16x16x32_bf16 v[8:11], v[250:253], v[190:193], v[64:67]
	v_mfma_f32_16x16x32_bf16 v[68:71], v[154:157], v[158:161], v[8:11]
	s_setprio 0
	s_barrier
	s_mov_b32 m0, s61
	s_nop 3
	v_lshl_add_u64 v[8:9], v[176:177], 0, s[14:15]
	s_add_u32 s8, s34, 0x18080
	ds_read_b128 v[52:55], v167 offset:49152
	ds_read_b128 v[158:161], v167 offset:50176
	ds_read_b128 v[186:189], v167 offset:51200
	ds_read_b128 v[190:193], v167 offset:52224
	ds_read_b128 v[210:213], v167 offset:53248
	ds_read_b128 v[218:221], v167 offset:54272
	ds_read_b128 v[246:249], v167 offset:55296
	ds_read_b128 v[162:165], v167 offset:56320
	global_load_lds_dwordx4 v[8:9], off
	v_lshl_add_u64 v[8:9], v[214:215], 0, s[14:15]
	s_mov_b32 m0, s43
	s_addc_u32 s9, s35, 0
	global_load_lds_dwordx4 v[8:9], off
	s_mov_b32 m0, s57
	s_nop 0
	global_load_lds_dwordx4 v132, s[8:9]
	v_lshl_add_u64 v[8:9], s[8:9], 0, v[136:137]
	s_mov_b32 m0, s59
	s_nop 0
	global_load_lds_dwordx4 v[8:9], off
	v_lshl_add_u64 v[8:9], v[182:183], 0, s[14:15]
	s_mov_b32 m0, s52
	s_nop 0
	global_load_lds_dwordx4 v[8:9], off
	v_lshl_add_u64 v[8:9], v[178:179], 0, s[14:15]
	s_mov_b32 m0, s53
	s_nop 0
	global_load_lds_dwordx4 v[8:9], off
	s_waitcnt vmcnt(8)
	s_waitcnt lgkmcnt(0)
	s_barrier
	s_setprio 1
	s_waitcnt lgkmcnt(0)
	v_mfma_f32_16x16x32_bf16 v[0:3], v[36:39], v[52:55], v[0:3]
	v_mfma_f32_16x16x32_bf16 v[64:67], v[150:153], v[158:161], v[0:3]
	v_mfma_f32_16x16x32_bf16 v[0:3], v[168:171], v[52:55], v[4:7]
	v_mfma_f32_16x16x32_bf16 v[60:63], v[230:233], v[158:161], v[0:3]
	v_mfma_f32_16x16x32_bf16 v[0:3], v[36:39], v[186:189], v[172:175]
	v_mfma_f32_16x16x32_bf16 v[48:51], v[150:153], v[190:193], v[0:3]
	v_mfma_f32_16x16x32_bf16 v[0:3], v[168:171], v[186:189], v[198:201]
	v_mfma_f32_16x16x32_bf16 v[44:47], v[230:233], v[190:193], v[0:3]
	v_mfma_f32_16x16x32_bf16 v[0:3], v[36:39], v[210:213], v[202:205]
	v_mfma_f32_16x16x32_bf16 v[32:35], v[150:153], v[218:221], v[0:3]
	v_mfma_f32_16x16x32_bf16 v[0:3], v[168:171], v[210:213], v[206:209]
	v_mfma_f32_16x16x32_bf16 v[28:31], v[230:233], v[218:221], v[0:3]
	v_mfma_f32_16x16x32_bf16 v[0:3], v[36:39], v[246:249], v[12:15]
	v_mfma_f32_16x16x32_bf16 v[12:15], v[150:153], v[162:165], v[0:3]
	v_mfma_f32_16x16x32_bf16 v[0:3], v[168:171], v[246:249], v[20:23]
	v_mfma_f32_16x16x32_bf16 v[8:11], v[230:233], v[162:165], v[0:3]
	s_setprio 0
	s_setprio 1
	v_mfma_f32_16x16x32_bf16 v[0:3], v[234:237], v[52:55], v[24:27]
	v_mfma_f32_16x16x32_bf16 v[56:59], v[238:241], v[158:161], v[0:3]
	v_mfma_f32_16x16x32_bf16 v[0:3], v[250:253], v[52:55], v[138:141]
	v_mfma_f32_16x16x32_bf16 v[52:55], v[154:157], v[158:161], v[0:3]
	v_mfma_f32_16x16x32_bf16 v[0:3], v[234:237], v[186:189], v[40:43]
	v_mfma_f32_16x16x32_bf16 v[40:43], v[238:241], v[190:193], v[0:3]
	v_mfma_f32_16x16x32_bf16 v[0:3], v[250:253], v[186:189], v[222:225]
	v_mfma_f32_16x16x32_bf16 v[36:39], v[154:157], v[190:193], v[0:3]
	v_mfma_f32_16x16x32_bf16 v[0:3], v[234:237], v[210:213], v[242:245]
	v_mfma_f32_16x16x32_bf16 v[24:27], v[238:241], v[218:221], v[0:3]
	v_mfma_f32_16x16x32_bf16 v[0:3], v[250:253], v[210:213], v[226:229]
	v_mfma_f32_16x16x32_bf16 v[20:23], v[154:157], v[218:221], v[0:3]
	v_mfma_f32_16x16x32_bf16 v[0:3], v[234:237], v[246:249], v[142:145]
	v_mfma_f32_16x16x32_bf16 v[4:7], v[238:241], v[162:165], v[0:3]
	v_mfma_f32_16x16x32_bf16 v[0:3], v[250:253], v[246:249], v[146:149]
	v_mfma_f32_16x16x32_bf16 v[0:3], v[154:157], v[162:165], v[0:3]
	s_setprio 0
	s_barrier
	s_andn2_b64 vcc, exec, s[62:63]
	s_cbranch_vccnz .LBB0_629
	s_barrier

; #define PG8_STAGE(bufoff, gbase, voff) do { _Pragma("unroll") for (int _i = 0; _i < 2; ++_i) \
;         __builtin_amdgcn_global_load_lds((const unsigned*)((const char*)(gbase) + (voff)[_i]), (LAS unsigned*)(lds + (bufoff) + ldsw + _i * 8192), 16, 0, 0); } while (0)
; #define PG8_WAIT_V(n) asm volatile("s_waitcnt vmcnt(" #n ")" ::: "memory")
; #define PG8_BAR __builtin_amdgcn_s_barrier()
; template <class Epi, class Sched, bool ALIGN_EPI = true, bool SP2 = true>
; __device__ __forceinline__ void gemm_phase(LAS unsigned char* lds, const Gemm g, const Sched& S, const Epi& E) {
;     ...
;     const char* cA = (const char*)g.A + (size_t)cur.pm * tstepA; const char* cB = (const char*)g.Bt + (size_t)cur.pn * tstepB;
;     if constexpr (SP2) {
;         PG8_STAGE(PG8_SB(0, 0), cB, voffB); PG8_STAGE(PG8_SB(0, 1), cB + hstepB, voffB); PG8_STAGE(PG8_SA(0, 0), cA, voffA); PG8_STAGE(PG8_SA(0, 1), cA + hstepA, voffA);
;         if (wr == 1) PG8_BAR;
;         PG8_WAIT_V(2); PG8_BAR;
;         PG8_STAGE(PG8_SB(1, 0), cB + kstep, voffB); PG8_STAGE(PG8_SA(1, 0), cA + kstep, voffA); PG8_STAGE(PG8_SB(1, 1), cB + hstepB + kstep, voffB);
;         PG8_WAIT_V(6); PG8_BAR;
.LBB0_668:
	s_add_u32 s12, s48, 0x26e00000
	s_addc_u32 s13, s49, 0
	s_add_u32 s36, s48, 0x1a0000
	s_addc_u32 s37, s49, 0
	s_lshl_b32 s6, s6, 5
	v_and_b32_e32 v9, 48, v8
	v_lshlrev_b32_e32 v10, 6, v8
	s_movk_i32 s8, 0x3c0
	v_lshlrev_b32_e32 v8, 2, v8
	s_and_b32 s24, s6, 0x60
	v_and_or_b32 v9, v10, s8, v9
	v_and_b32_e32 v8, 32, v8
	s_lshl_b32 s6, s24, 7
	s_add_i32 m0, s39, 0x18000
	v_lshl_add_u64 v[4:5], v[4:5], 0, s[14:15]
	s_sext_i32_i8 s1, s10
	s_lshl_b32 s10, s7, 6
	s_lshl_b32 s7, s7, 13
	v_bitop3_b32 v144, s6, v9, v8 bitop3:0xf6
	s_waitcnt vmcnt(2)
	s_barrier
	global_load_lds_dwordx4 v[4:5], off
	v_lshl_add_u64 v[2:3], v[2:3], 0, s[14:15]
	s_add_i32 m0, s39, 0x1a000
	s_add_i32 s31, s39, 0x8000
	s_add_i32 s6, s39, 0xa000
	global_load_lds_dwordx4 v[2:3], off
	v_lshl_add_u64 v[0:1], v[0:1], 0, s[14:15]
	s_mov_b32 m0, s31
	s_add_u32 s8, s16, 0x10080
	global_load_lds_dwordx4 v[0:1], off
	v_lshl_add_u64 v[0:1], v[6:7], 0, s[14:15]
	s_mov_b32 m0, s6
	s_addc_u32 s9, s17, 0
	global_load_lds_dwordx4 v[0:1], off
	s_add_i32 m0, s39, 0x1c000
	s_nop 0
	global_load_lds_dwordx4 v18, s[8:9]
	s_add_i32 m0, s39, 0x1e000
	v_bitop3_b32 v10, v9, s7, v8 bitop3:0xde
	global_load_lds_dwordx4 v16, s[8:9]
	s_waitcnt vmcnt(6)
	s_cmpk_lt_u32 s2, 0x100
	s_cselect_b64 s[34:35], -1, 0
	s_ashr_i32 s7, s26, 31
	s_mov_b32 s64, 0
	v_add_u32_e32 v145, 0, v10
	s_barrier
	s_branch .LBB0_671

; #define PG8_STAGE(bufoff, gbase, voff) do { _Pragma("unroll") for (int _i = 0; _i < 2; ++_i) \
;         __builtin_amdgcn_global_load_lds((const unsigned*)((const char*)(gbase) + (voff)[_i]), (LAS unsigned*)(lds + (bufoff) + ldsw + _i * 8192), 16, 0, 0); } while (0)
; #define PG8_LDA(dst, b, h) do { _Pragma("unroll") for (int m = 0; m < 4; ++m) _Pragma("unroll") for (int k = 0; k < 2; ++k) dst[m][k] = *(const LAS bf16x8*)(lds + PG8_SA(b, h) + aoff + m * 2048 + k * 1024); } while (0)
; #define PG8_LDB(dst, b, h) do { _Pragma("unroll") for (int n = 0; n < 2; ++n) _Pragma("unroll") for (int k = 0; k < 2; ++k) dst[n][k] = *(const LAS bf16x8*)(lds + PG8_SB(b, h) + boff + n * 2048 + k * 1024); } while (0)
; #define PG8_MMA(ai, bj, At, Bt) do { __builtin_amdgcn_s_setprio(1); _Pragma("unroll") for (int m = 0; m < 4; ++m) _Pragma("unroll") for (int n = 0; n < 2; ++n) _Pragma("unroll") for (int k = 0; k < 2; ++k) \
;         acc[ai][bj][m][n] = __builtin_amdgcn_mfma_f32_16x16x32_bf16(Bt[n][k], At[m][k], acc[ai][bj][m][n], 0, 0, 0); __builtin_amdgcn_s_setprio(0); } while (0)
; #define PG8_WAIT_V(n) asm volatile("s_waitcnt vmcnt(" #n ")" ::: "memory")
; #define PG8_WAIT_L(n) asm volatile("s_waitcnt lgkmcnt(" #n ")" ::: "memory")
; #define PG8_BAR __builtin_amdgcn_s_barrier()
; template <class Epi, class Sched, bool ALIGN_EPI = true, bool SP2 = true>
; __device__ __forceinline__ void gemm_phase(LAS unsigned char* lds, const Gemm g, const Sched& S, const Epi& E) {
;     ...
;         for (int t = 0; t < nt; t += 2) {
;             const bool last = (t == nt - 2);
;             const char* a1 = cA + (size_t)(t + 1) * kstep;
;             const char* a2 = last ? nA : cA + (size_t)(t + 2) * kstep; const char* b2 = last ? nB : cB + (size_t)(t + 2) * kstep;
;             const char* a3 = a2 + kstep; const char* b3 = b2 + kstep;
;             PG8_LDB(B0, 0, 0); PG8_LDB(B1, 0, 1); PG8_SCHED; PG8_LDA(At, 0, 0); PG8_STAGE(PG8_SA(1, 1), a1 + hstepA, voffA);
;             PG8_WAIT_V(8); PG8_WAIT_L(0); PG8_BAR; PG8_MMA(0, 0, At, B0); PG8_MMA(0, 1, At, B1); PG8_BAR; PG8_SCHED;
;             PG8_LDA(At, 0, 1); PG8_STAGE(PG8_SB(0, 0), b2, voffB); PG8_STAGE(PG8_SB(0, 1), b2 + hstepB, voffB); PG8_STAGE(PG8_SA(0, 0), a2, voffA);
;             PG8_WAIT_V(8); PG8_WAIT_L(0); PG8_BAR; PG8_MMA(1, 0, At, B0); PG8_MMA(1, 1, At, B1); PG8_BAR; PG8_SCHED;
.LBB0_676:
	s_add_u32 s22, s50, s9
	s_addc_u32 s23, s51, 0
	s_add_u32 s30, s22, 0x100
	s_addc_u32 s38, s23, 0
	s_and_b64 s[20:21], s[18:19], exec
	s_cselect_b32 s55, s47, s38
	s_cselect_b32 s54, s46, s30
	s_add_u32 s9, s16, s9
	s_addc_u32 s20, s17, 0
	s_add_u32 s9, s9, 0x100
	s_addc_u32 s20, s20, 0
	s_add_i32 s38, 0, 0x10000
	s_and_b64 s[18:19], s[18:19], exec
	s_cselect_b32 s63, s2, s20
	s_cselect_b32 s62, s8, s9
	s_add_i32 s19, 0, 0x14000
	s_add_u32 s22, s22, 0x30080
	s_addc_u32 s23, s23, 0
	s_add_i32 s67, s38, s52
	s_add_i32 m0, s39, 0xc000
	s_add_i32 s28, s39, 0xe000
	s_add_i32 s59, s67, 0x2000
	s_add_u32 vcc_lo, s62, 0x10000
	v_add_u32_e32 v150, s38, v144
	v_add_u32_e32 v166, s19, v144
	s_addc_u32 vcc_hi, s63, 0
	s_add_i32 s66, s19, s52
	ds_read_b128 v[136:139], v150
	ds_read_b128 v[140:143], v150 offset:1024
	ds_read_b128 v[146:149], v150 offset:2048
	ds_read_b128 v[150:153], v150 offset:3072
	ds_read_b128 v[154:157], v166
	ds_read_b128 v[158:161], v166 offset:1024
	ds_read_b128 v[162:165], v166 offset:2048
	ds_read_b128 v[166:169], v166 offset:3072
	s_add_i32 s61, s66, 0x2000
	s_add_i32 s58, 0, 0x18000
	s_add_i32 s45, 0, 0x1c000
	s_add_u32 s20, s54, 0x30000
	s_addc_u32 s21, s55, 0
	s_add_i32 s30, s58, s52
	s_add_i32 s9, s30, 0x2000
	s_add_u32 s18, s62, 0x10080
	s_addc_u32 s19, s63, 0
	s_add_i32 s60, s45, s52
	s_add_i32 s38, s60, 0x2000
	ds_read_b128 v[170:173], v145
	ds_read_b128 v[174:177], v145 offset:1024
	ds_read_b128 v[186:189], v145 offset:2048
	ds_read_b128 v[190:193], v145 offset:3072
	ds_read_b128 v[198:201], v145 offset:4096
	ds_read_b128 v[202:205], v145 offset:5120
	ds_read_b128 v[206:209], v145 offset:6144
	ds_read_b128 v[210:213], v145 offset:7168
	global_load_lds_dwordx4 v134, s[22:23]
	s_mov_b32 m0, s28
	s_nop 0
	global_load_lds_dwordx4 v132, s[22:23]
	s_waitcnt vmcnt(8)
	s_waitcnt lgkmcnt(0)
	s_barrier
	s_setprio 1
	s_waitcnt lgkmcnt(0)
	v_mfma_f32_16x16x32_bf16 v[128:131], v[136:139], v[170:173], v[128:131]
	v_mfma_f32_16x16x32_bf16 v[124:127], v[146:149], v[170:173], v[124:127]
	v_mfma_f32_16x16x32_bf16 v[112:115], v[136:139], v[186:189], v[112:115]
	v_mfma_f32_16x16x32_bf16 v[108:111], v[146:149], v[186:189], v[108:111]
	v_mfma_f32_16x16x32_bf16 v[96:99], v[136:139], v[198:201], v[96:99]
	v_mfma_f32_16x16x32_bf16 v[92:95], v[146:149], v[198:201], v[92:95]
	v_mfma_f32_16x16x32_bf16 v[80:83], v[136:139], v[206:209], v[80:83]
	v_mfma_f32_16x16x32_bf16 v[76:79], v[146:149], v[206:209], v[76:79]
	v_mfma_f32_16x16x32_bf16 v[128:131], v[140:143], v[174:177], v[128:131]
	v_mfma_f32_16x16x32_bf16 v[124:127], v[150:153], v[174:177], v[124:127]
	v_mfma_f32_16x16x32_bf16 v[112:115], v[140:143], v[190:193], v[112:115]
	v_mfma_f32_16x16x32_bf16 v[108:111], v[150:153], v[190:193], v[108:111]
	v_mfma_f32_16x16x32_bf16 v[96:99], v[140:143], v[202:205], v[96:99]
	v_mfma_f32_16x16x32_bf16 v[92:95], v[150:153], v[202:205], v[92:95]
	v_mfma_f32_16x16x32_bf16 v[80:83], v[140:143], v[210:213], v[80:83]
	v_mfma_f32_16x16x32_bf16 v[76:79], v[150:153], v[210:213], v[76:79]
	s_setprio 0
	s_setprio 1
	v_mfma_f32_16x16x32_bf16 v[120:123], v[154:157], v[170:173], v[120:123]
	v_mfma_f32_16x16x32_bf16 v[116:119], v[162:165], v[170:173], v[116:119]
	v_mfma_f32_16x16x32_bf16 v[104:107], v[154:157], v[186:189], v[104:107]
	v_mfma_f32_16x16x32_bf16 v[100:103], v[162:165], v[186:189], v[100:103]
	v_mfma_f32_16x16x32_bf16 v[88:91], v[154:157], v[198:201], v[88:91]
	v_mfma_f32_16x16x32_bf16 v[84:87], v[162:165], v[198:201], v[84:87]
	v_mfma_f32_16x16x32_bf16 v[72:75], v[154:157], v[206:209], v[72:75]
	v_mfma_f32_16x16x32_bf16 v[68:71], v[162:165], v[206:209], v[68:71]
	v_mfma_f32_16x16x32_bf16 v[120:123], v[158:161], v[174:177], v[120:123]
	v_mfma_f32_16x16x32_bf16 v[116:119], v[166:169], v[174:177], v[116:119]
	v_mfma_f32_16x16x32_bf16 v[104:107], v[158:161], v[190:193], v[104:107]
	v_mfma_f32_16x16x32_bf16 v[100:103], v[166:169], v[190:193], v[100:103]
	v_mfma_f32_16x16x32_bf16 v[88:91], v[158:161], v[202:205], v[88:91]
	v_mfma_f32_16x16x32_bf16 v[84:87], v[166:169], v[202:205], v[84:87]
	v_mfma_f32_16x16x32_bf16 v[72:75], v[158:161], v[210:213], v[72:75]
	v_mfma_f32_16x16x32_bf16 v[68:71], v[166:169], v[210:213], v[68:71]
	s_setprio 0
	s_barrier
	s_mov_b32 m0, s67
	v_lshl_add_u64 v[178:179], s[62:63], 0, v[18:19]
	ds_read_b128 v[170:173], v145 offset:16384
	ds_read_b128 v[174:177], v145 offset:17408
	ds_read_b128 v[186:189], v145 offset:18432
	ds_read_b128 v[190:193], v145 offset:19456
	ds_read_b128 v[198:201], v145 offset:20480
	ds_read_b128 v[202:205], v145 offset:21504
	ds_read_b128 v[206:209], v145 offset:22528
	ds_read_b128 v[210:213], v145 offset:23552
	global_load_lds_dwordx4 v[178:179], off
	v_lshl_add_u64 v[182:183], s[62:63], 0, v[16:17]
	s_mov_b32 m0, s59
	v_lshl_add_u64 v[214:215], vcc, 0, v[18:19]
	global_load_lds_dwordx4 v[182:183], off
	s_mov_b32 m0, s66
	v_lshl_add_u64 v[218:219], s[54:55], 0, v[132:133]
	global_load_lds_dwordx4 v[214:215], off
	v_lshl_add_u64 v[214:215], vcc, 0, v[16:17]
	s_mov_b32 m0, s61
	s_nop 0
	global_load_lds_dwordx4 v[214:215], off
	v_lshl_add_u64 v[214:215], s[54:55], 0, v[134:135]
	s_mov_b32 m0, s39
	s_nop 0
	global_load_lds_dwordx4 v[214:215], off
	s_mov_b32 m0, s56
	s_nop 0
	global_load_lds_dwordx4 v[218:219], off
	s_waitcnt vmcnt(8)
	s_waitcnt lgkmcnt(0)
	s_barrier
; #define PG8_STAGE(bufoff, gbase, voff) do { _Pragma("unroll") for (int _i = 0; _i < 2; ++_i) \
;         __builtin_amdgcn_global_load_lds((const unsigned*)((const char*)(gbase) + (voff)[_i]), (LAS unsigned*)(lds + (bufoff) + ldsw + _i * 8192), 16, 0, 0); } while (0)
; #define PG8_LDA(dst, b, h) do { _Pragma("unroll") for (int m = 0; m < 4; ++m) _Pragma("unroll") for (int k = 0; k < 2; ++k) dst[m][k] = *(const LAS bf16x8*)(lds + PG8_SA(b, h) + aoff + m * 2048 + k * 1024); } while (0)
; #define PG8_LDB(dst, b, h) do { _Pragma("unroll") for (int n = 0; n < 2; ++n) _Pragma("unroll") for (int k = 0; k < 2; ++k) dst[n][k] = *(const LAS bf16x8*)(lds + PG8_SB(b, h) + boff + n * 2048 + k * 1024); } while (0)
; #define PG8_MMA(ai, bj, At, Bt) do { __builtin_amdgcn_s_setprio(1); _Pragma("unroll") for (int m = 0; m < 4; ++m) _Pragma("unroll") for (int n = 0; n < 2; ++n) _Pragma("unroll") for (int k = 0; k < 2; ++k) \
;         acc[ai][bj][m][n] = __builtin_amdgcn_mfma_f32_16x16x32_bf16(Bt[n][k], At[m][k], acc[ai][bj][m][n], 0, 0, 0); __builtin_amdgcn_s_setprio(0); } while (0)
; #define PG8_WAIT_V(n) asm volatile("s_waitcnt vmcnt(" #n ")" ::: "memory")
; #define PG8_WAIT_L(n) asm volatile("s_waitcnt lgkmcnt(" #n ")" ::: "memory")
; #define PG8_BAR __builtin_amdgcn_s_barrier()
; #define PG8_SCHED __builtin_amdgcn_sched_barrier(0)
; template <class Epi, class Sched, bool ALIGN_EPI = true, bool SP2 = true>
; __device__ __forceinline__ void gemm_phase(LAS unsigned char* lds, const Gemm g, const Sched& S, const Epi& E) {
;     ...
;             PG8_WAIT_V(8); PG8_WAIT_L(0); PG8_BAR; PG8_MMA(1, 0, At, B0); PG8_MMA(1, 1, At, B1); PG8_BAR; PG8_SCHED;
;             PG8_LDB(B0, 1, 0); PG8_LDB(B1, 1, 1); PG8_SCHED; PG8_LDA(At, 1, 0); PG8_STAGE(PG8_SA(0, 1), a2 + hstepA, voffA);
;             PG8_WAIT_V(8); PG8_WAIT_L(0); PG8_BAR; PG8_MMA(0, 0, At, B0); PG8_MMA(0, 1, At, B1); PG8_BAR; PG8_SCHED;
	s_setprio 1
	s_waitcnt lgkmcnt(0)
	v_mfma_f32_16x16x32_bf16 v[64:67], v[136:139], v[170:173], v[64:67]
	v_mfma_f32_16x16x32_bf16 v[60:63], v[146:149], v[170:173], v[60:63]
	v_mfma_f32_16x16x32_bf16 v[48:51], v[136:139], v[186:189], v[48:51]
	v_mfma_f32_16x16x32_bf16 v[44:47], v[146:149], v[186:189], v[44:47]
	v_mfma_f32_16x16x32_bf16 v[32:35], v[136:139], v[198:201], v[32:35]
	v_mfma_f32_16x16x32_bf16 v[28:31], v[146:149], v[198:201], v[28:31]
	v_mfma_f32_16x16x32_bf16 v[12:15], v[136:139], v[206:209], v[12:15]
	v_mfma_f32_16x16x32_bf16 v[8:11], v[146:149], v[206:209], v[8:11]
	v_mfma_f32_16x16x32_bf16 v[64:67], v[140:143], v[174:177], v[64:67]
	v_mfma_f32_16x16x32_bf16 v[60:63], v[150:153], v[174:177], v[60:63]
	v_mfma_f32_16x16x32_bf16 v[48:51], v[140:143], v[190:193], v[48:51]
	v_mfma_f32_16x16x32_bf16 v[44:47], v[150:153], v[190:193], v[44:47]
	v_mfma_f32_16x16x32_bf16 v[32:35], v[140:143], v[202:205], v[32:35]
	v_mfma_f32_16x16x32_bf16 v[28:31], v[150:153], v[202:205], v[28:31]
	v_mfma_f32_16x16x32_bf16 v[12:15], v[140:143], v[210:213], v[12:15]
	v_mfma_f32_16x16x32_bf16 v[8:11], v[150:153], v[210:213], v[8:11]
	s_setprio 0
	s_setprio 1
	v_mfma_f32_16x16x32_bf16 v[56:59], v[154:157], v[170:173], v[56:59]
	v_mfma_f32_16x16x32_bf16 v[52:55], v[162:165], v[170:173], v[52:55]
	v_mfma_f32_16x16x32_bf16 v[40:43], v[154:157], v[186:189], v[40:43]
	v_mfma_f32_16x16x32_bf16 v[36:39], v[162:165], v[186:189], v[36:39]
	v_mfma_f32_16x16x32_bf16 v[24:27], v[154:157], v[198:201], v[24:27]
	v_mfma_f32_16x16x32_bf16 v[20:23], v[162:165], v[198:201], v[20:23]
	v_mfma_f32_16x16x32_bf16 v[4:7], v[154:157], v[206:209], v[4:7]
	v_mfma_f32_16x16x32_bf16 v[0:3], v[162:165], v[206:209], v[0:3]
	v_mfma_f32_16x16x32_bf16 v[56:59], v[158:161], v[174:177], v[56:59]
	v_mfma_f32_16x16x32_bf16 v[52:55], v[166:169], v[174:177], v[52:55]
	v_mfma_f32_16x16x32_bf16 v[40:43], v[158:161], v[190:193], v[40:43]
	v_mfma_f32_16x16x32_bf16 v[36:39], v[166:169], v[190:193], v[36:39]
	v_mfma_f32_16x16x32_bf16 v[24:27], v[158:161], v[202:205], v[24:27]
	v_mfma_f32_16x16x32_bf16 v[20:23], v[166:169], v[202:205], v[20:23]
	v_mfma_f32_16x16x32_bf16 v[4:7], v[158:161], v[210:213], v[4:7]
	v_mfma_f32_16x16x32_bf16 v[0:3], v[166:169], v[210:213], v[0:3]
	s_setprio 0
	s_barrier
	v_add_u32_e32 v150, s58, v144
	v_add_u32_e32 v166, s45, v144
	ds_read_b128 v[136:139], v150
	ds_read_b128 v[140:143], v150 offset:1024
	ds_read_b128 v[146:149], v150 offset:2048
	ds_read_b128 v[150:153], v150 offset:3072
	ds_read_b128 v[154:157], v166
	ds_read_b128 v[158:161], v166 offset:1024
	ds_read_b128 v[162:165], v166 offset:2048
	ds_read_b128 v[166:169], v166 offset:3072
	s_mov_b32 m0, s57
	ds_read_b128 v[170:173], v145 offset:32768
	ds_read_b128 v[174:177], v145 offset:33792
	ds_read_b128 v[186:189], v145 offset:34816
	ds_read_b128 v[190:193], v145 offset:35840
	ds_read_b128 v[198:201], v145 offset:36864
	ds_read_b128 v[202:205], v145 offset:37888
	ds_read_b128 v[206:209], v145 offset:38912
	ds_read_b128 v[210:213], v145 offset:39936
	global_load_lds_dwordx4 v134, s[20:21]
	v_lshl_add_u64 v[220:221], s[20:21], 0, v[132:133]
	s_mov_b32 m0, s25
	s_nop 0
	global_load_lds_dwordx4 v[220:221], off
	s_waitcnt vmcnt(8)
	s_waitcnt lgkmcnt(0)
	s_barrier
	s_setprio 1
	s_waitcnt lgkmcnt(0)
	v_mfma_f32_16x16x32_bf16 v[128:131], v[136:139], v[170:173], v[128:131]
	v_mfma_f32_16x16x32_bf16 v[124:127], v[146:149], v[170:173], v[124:127]
	v_mfma_f32_16x16x32_bf16 v[112:115], v[136:139], v[186:189], v[112:115]
	v_mfma_f32_16x16x32_bf16 v[108:111], v[146:149], v[186:189], v[108:111]
	v_mfma_f32_16x16x32_bf16 v[96:99], v[136:139], v[198:201], v[96:99]
	v_mfma_f32_16x16x32_bf16 v[92:95], v[146:149], v[198:201], v[92:95]
	v_mfma_f32_16x16x32_bf16 v[80:83], v[136:139], v[206:209], v[80:83]
	v_mfma_f32_16x16x32_bf16 v[76:79], v[146:149], v[206:209], v[76:79]
	v_mfma_f32_16x16x32_bf16 v[128:131], v[140:143], v[174:177], v[128:131]
	v_mfma_f32_16x16x32_bf16 v[124:127], v[150:153], v[174:177], v[124:127]
	v_mfma_f32_16x16x32_bf16 v[112:115], v[140:143], v[190:193], v[112:115]
	v_mfma_f32_16x16x32_bf16 v[108:111], v[150:153], v[190:193], v[108:111]
	v_mfma_f32_16x16x32_bf16 v[96:99], v[140:143], v[202:205], v[96:99]
	v_mfma_f32_16x16x32_bf16 v[92:95], v[150:153], v[202:205], v[92:95]
	v_mfma_f32_16x16x32_bf16 v[80:83], v[140:143], v[210:213], v[80:83]
	v_mfma_f32_16x16x32_bf16 v[76:79], v[150:153], v[210:213], v[76:79]
	s_setprio 0
	s_setprio 1
	v_mfma_f32_16x16x32_bf16 v[120:123], v[154:157], v[170:173], v[120:123]
	v_mfma_f32_16x16x32_bf16 v[116:119], v[162:165], v[170:173], v[116:119]
	v_mfma_f32_16x16x32_bf16 v[104:107], v[154:157], v[186:189], v[104:107]
	v_mfma_f32_16x16x32_bf16 v[100:103], v[162:165], v[186:189], v[100:103]
	v_mfma_f32_16x16x32_bf16 v[88:91], v[154:157], v[198:201], v[88:91]
	v_mfma_f32_16x16x32_bf16 v[84:87], v[162:165], v[198:201], v[84:87]
	v_mfma_f32_16x16x32_bf16 v[72:75], v[154:157], v[206:209], v[72:75]
	v_mfma_f32_16x16x32_bf16 v[68:71], v[162:165], v[206:209], v[68:71]
	v_mfma_f32_16x16x32_bf16 v[120:123], v[158:161], v[174:177], v[120:123]
	v_mfma_f32_16x16x32_bf16 v[116:119], v[166:169], v[174:177], v[116:119]
	v_mfma_f32_16x16x32_bf16 v[104:107], v[158:161], v[190:193], v[104:107]
	v_mfma_f32_16x16x32_bf16 v[100:103], v[166:169], v[190:193], v[100:103]
	v_mfma_f32_16x16x32_bf16 v[88:91], v[158:161], v[202:205], v[88:91]
	v_mfma_f32_16x16x32_bf16 v[84:87], v[166:169], v[202:205], v[84:87]
	v_mfma_f32_16x16x32_bf16 v[72:75], v[158:161], v[210:213], v[72:75]
	v_mfma_f32_16x16x32_bf16 v[68:71], v[166:169], v[210:213], v[68:71]
	s_setprio 0
	s_barrier
; #define PG8_STAGE(bufoff, gbase, voff) do { _Pragma("unroll") for (int _i = 0; _i < 2; ++_i) \
;         __builtin_amdgcn_global_load_lds((const unsigned*)((const char*)(gbase) + (voff)[_i]), (LAS unsigned*)(lds + (bufoff) + ldsw + _i * 8192), 16, 0, 0); } while (0)
; #define PG8_LDA(dst, b, h) do { _Pragma("unroll") for (int m = 0; m < 4; ++m) _Pragma("unroll") for (int k = 0; k < 2; ++k) dst[m][k] = *(const LAS bf16x8*)(lds + PG8_SA(b, h) + aoff + m * 2048 + k * 1024); } while (0)
; #define PG8_MMA(ai, bj, At, Bt) do { __builtin_amdgcn_s_setprio(1); _Pragma("unroll") for (int m = 0; m < 4; ++m) _Pragma("unroll") for (int n = 0; n < 2; ++n) _Pragma("unroll") for (int k = 0; k < 2; ++k) \
;         acc[ai][bj][m][n] = __builtin_amdgcn_mfma_f32_16x16x32_bf16(Bt[n][k], At[m][k], acc[ai][bj][m][n], 0, 0, 0); __builtin_amdgcn_s_setprio(0); } while (0)
; #define PG8_WAIT_V(n) asm volatile("s_waitcnt vmcnt(" #n ")" ::: "memory")
; #define PG8_WAIT_L(n) asm volatile("s_waitcnt lgkmcnt(" #n ")" ::: "memory")
; #define PG8_BAR __builtin_amdgcn_s_barrier()
; #define PG8_SCHED __builtin_amdgcn_sched_barrier(0)
; template <class Epi, class Sched, bool ALIGN_EPI = true, bool SP2 = true>
; __device__ __forceinline__ void gemm_phase(LAS unsigned char* lds, const Gemm g, const Sched& S, const Epi& E) {
;     ...
;             PG8_LDA(At, 1, 1); PG8_STAGE(PG8_SB(1, 0), b3, voffB); PG8_STAGE(PG8_SB(1, 1), b3 + hstepB, voffB); PG8_STAGE(PG8_SA(1, 0), a3, voffA);
;             PG8_WAIT_V(8); PG8_WAIT_L(0); PG8_BAR; PG8_MMA(1, 0, At, B0); PG8_MMA(1, 1, At, B1); PG8_BAR; PG8_SCHED;
;         }
	s_mov_b32 m0, s30
	v_lshl_add_u64 v[178:179], v[178:179], 0, s[14:15]
	ds_read_b128 v[170:173], v145 offset:49152
	ds_read_b128 v[174:177], v145 offset:50176
	ds_read_b128 v[186:189], v145 offset:51200
	ds_read_b128 v[190:193], v145 offset:52224
	ds_read_b128 v[198:201], v145 offset:53248
	ds_read_b128 v[202:205], v145 offset:54272
	ds_read_b128 v[206:209], v145 offset:55296
	ds_read_b128 v[210:213], v145 offset:56320
	global_load_lds_dwordx4 v[178:179], off
	v_lshl_add_u64 v[178:179], v[182:183], 0, s[14:15]
	s_mov_b32 m0, s9
	s_nop 0
	global_load_lds_dwordx4 v[178:179], off
	s_mov_b32 m0, s60
	s_nop 0
	global_load_lds_dwordx4 v18, s[18:19]
	v_lshl_add_u64 v[178:179], s[18:19], 0, v[16:17]
	s_mov_b32 m0, s38
	s_nop 0
	global_load_lds_dwordx4 v[178:179], off
	v_lshl_add_u64 v[178:179], v[214:215], 0, s[14:15]
	s_mov_b32 m0, s31
	s_nop 0
	global_load_lds_dwordx4 v[178:179], off
	v_lshl_add_u64 v[178:179], v[218:219], 0, s[14:15]
	s_mov_b32 m0, s6
	s_nop 0
	global_load_lds_dwordx4 v[178:179], off
	s_waitcnt vmcnt(8)
	s_waitcnt lgkmcnt(0)
	s_barrier
	s_setprio 1
	s_waitcnt lgkmcnt(0)
	v_mfma_f32_16x16x32_bf16 v[64:67], v[136:139], v[170:173], v[64:67]
	v_mfma_f32_16x16x32_bf16 v[60:63], v[146:149], v[170:173], v[60:63]
	v_mfma_f32_16x16x32_bf16 v[48:51], v[136:139], v[186:189], v[48:51]
	v_mfma_f32_16x16x32_bf16 v[44:47], v[146:149], v[186:189], v[44:47]
	v_mfma_f32_16x16x32_bf16 v[32:35], v[136:139], v[198:201], v[32:35]
	v_mfma_f32_16x16x32_bf16 v[28:31], v[146:149], v[198:201], v[28:31]
	v_mfma_f32_16x16x32_bf16 v[12:15], v[136:139], v[206:209], v[12:15]
	v_mfma_f32_16x16x32_bf16 v[8:11], v[146:149], v[206:209], v[8:11]
	v_mfma_f32_16x16x32_bf16 v[64:67], v[140:143], v[174:177], v[64:67]
	v_mfma_f32_16x16x32_bf16 v[60:63], v[150:153], v[174:177], v[60:63]
	v_mfma_f32_16x16x32_bf16 v[48:51], v[140:143], v[190:193], v[48:51]
	v_mfma_f32_16x16x32_bf16 v[44:47], v[150:153], v[190:193], v[44:47]
	v_mfma_f32_16x16x32_bf16 v[32:35], v[140:143], v[202:205], v[32:35]
	v_mfma_f32_16x16x32_bf16 v[28:31], v[150:153], v[202:205], v[28:31]
	v_mfma_f32_16x16x32_bf16 v[12:15], v[140:143], v[210:213], v[12:15]
	v_mfma_f32_16x16x32_bf16 v[8:11], v[150:153], v[210:213], v[8:11]
	s_setprio 0
	s_setprio 1
	v_mfma_f32_16x16x32_bf16 v[56:59], v[154:157], v[170:173], v[56:59]
	v_mfma_f32_16x16x32_bf16 v[52:55], v[162:165], v[170:173], v[52:55]
	v_mfma_f32_16x16x32_bf16 v[40:43], v[154:157], v[186:189], v[40:43]
	v_mfma_f32_16x16x32_bf16 v[36:39], v[162:165], v[186:189], v[36:39]
	v_mfma_f32_16x16x32_bf16 v[24:27], v[154:157], v[198:201], v[24:27]
	v_mfma_f32_16x16x32_bf16 v[20:23], v[162:165], v[198:201], v[20:23]
	v_mfma_f32_16x16x32_bf16 v[4:7], v[154:157], v[206:209], v[4:7]
	v_mfma_f32_16x16x32_bf16 v[0:3], v[162:165], v[206:209], v[0:3]
	v_mfma_f32_16x16x32_bf16 v[56:59], v[158:161], v[174:177], v[56:59]
	v_mfma_f32_16x16x32_bf16 v[52:55], v[166:169], v[174:177], v[52:55]
	v_mfma_f32_16x16x32_bf16 v[40:43], v[158:161], v[190:193], v[40:43]
	v_mfma_f32_16x16x32_bf16 v[36:39], v[166:169], v[190:193], v[36:39]
	v_mfma_f32_16x16x32_bf16 v[24:27], v[158:161], v[202:205], v[24:27]
	v_mfma_f32_16x16x32_bf16 v[20:23], v[166:169], v[202:205], v[20:23]
	v_mfma_f32_16x16x32_bf16 v[4:7], v[158:161], v[210:213], v[4:7]
	v_mfma_f32_16x16x32_bf16 v[0:3], v[166:169], v[210:213], v[0:3]
	s_setprio 0
	s_barrier
	s_movk_i32 s9, 0x100
	s_andn2_b64 vcc, exec, s[42:43]
	s_mov_b64 s[18:19], -1
	s_mov_b64 s[42:43], 0
	s_cbranch_vccz .LBB0_676
	s_and_b64 vcc, exec, s[34:35]
	s_cbranch_vccz .LBB0_679
	s_barrier

; #define PG8_STAGE(bufoff, gbase, voff) do { _Pragma("unroll") for (int _i = 0; _i < 2; ++_i) \
;         __builtin_amdgcn_global_load_lds((const unsigned*)((const char*)(gbase) + (voff)[_i]), (LAS unsigned*)(lds + (bufoff) + ldsw + _i * 8192), 16, 0, 0); } while (0)
; #define PG8_WAIT_V(n) asm volatile("s_waitcnt vmcnt(" #n ")" ::: "memory")
; #define PG8_BAR __builtin_amdgcn_s_barrier()
; template <class Epi, class Sched, bool ALIGN_EPI = true, bool SP2 = true>
; __device__ __forceinline__ void gemm_phase(LAS unsigned char* lds, const Gemm g, const Sched& S, const Epi& E) {
;     ...
;     const char* cA = (const char*)g.A + (size_t)cur.pm * tstepA; const char* cB = (const char*)g.Bt + (size_t)cur.pn * tstepB;
;     if constexpr (SP2) {
;         PG8_STAGE(PG8_SB(0, 0), cB, voffB); PG8_STAGE(PG8_SB(0, 1), cB + hstepB, voffB); PG8_STAGE(PG8_SA(0, 0), cA, voffA); PG8_STAGE(PG8_SA(0, 1), cA + hstepA, voffA);
;         if (wr == 1) PG8_BAR;
;         PG8_WAIT_V(2); PG8_BAR;
;         PG8_STAGE(PG8_SB(1, 0), cB + kstep, voffB); PG8_STAGE(PG8_SA(1, 0), cA + kstep, voffA); PG8_STAGE(PG8_SB(1, 1), cB + hstepB + kstep, voffB);
;         PG8_WAIT_V(6); PG8_BAR;
.LBB0_878:
	s_add_u32 s34, s34, 0x17e00000
	s_addc_u32 s35, s35, 0
	v_and_b32_e32 v15, 48, v14
	v_lshlrev_b32_e32 v20, 6, v14
	s_movk_i32 s9, 0x3c0
	v_lshlrev_b32_e32 v14, 2, v14
	s_lshl_b32 s1, s1, 5
	s_lshl_b32 s0, s8, 6
	s_lshl_b32 s8, s8, 13
	v_and_or_b32 v15, v20, s9, v15
	v_and_b32_e32 v14, 32, v14
	s_and_b32 s1, s1, 0x60
	v_bitop3_b32 v20, v15, s8, v14 bitop3:0xde
	s_lshl_b32 s8, s1, 7
	s_add_i32 m0, s53, 0x18000
	v_lshl_add_u64 v[6:7], v[6:7], 0, s[14:15]
	v_bitop3_b32 v142, s8, v15, v14 bitop3:0xf6
	s_waitcnt vmcnt(2)
	s_barrier
	global_load_lds_dwordx4 v[6:7], off
	v_lshl_add_u64 v[4:5], v[4:5], 0, s[14:15]
	s_add_i32 m0, s53, 0x1a000
	s_add_i32 s8, s53, 0x8000
	s_add_i32 s9, s53, 0xa000
	global_load_lds_dwordx4 v[4:5], off
	v_lshl_add_u64 v[0:1], v[0:1], 0, s[14:15]
	s_mov_b32 m0, s8
	s_add_u32 s22, s18, 0x40080
	global_load_lds_dwordx4 v[0:1], off
	v_lshl_add_u64 v[0:1], v[2:3], 0, s[14:15]
	s_mov_b32 m0, s9
	s_addc_u32 s23, s19, 0
	global_load_lds_dwordx4 v[0:1], off
	s_add_i32 m0, s53, 0x1c000
	s_nop 0
	global_load_lds_dwordx4 v18, s[22:23]
	s_add_i32 m0, s53, 0x1e000
	s_cmpk_lt_u32 s2, 0x100
	global_load_lds_dwordx4 v16, s[22:23]
	v_lshlrev_b32_e32 v0, 14, v12
	v_and_b32_e32 v0, 0xffff8000, v0
	v_lshl_add_u32 v0, v11, 11, v0
	v_and_b32_e32 v1, 1, v12
	v_lshl_or_b32 v0, v1, 6, v0
	v_lshl_add_u32 v136, v13, 1, v0
	v_lshlrev_b32_e32 v0, 14, v8
	v_and_b32_e32 v0, 0xffff8000, v0
	s_waitcnt vmcnt(6)
	v_lshl_add_u32 v0, v9, 11, v0
	v_and_b32_e32 v1, 1, v8
	v_lshl_or_b32 v0, v1, 6, v0
	s_sext_i32_i8 s17, s10
	s_cselect_b64 s[36:37], -1, 0
	s_ashr_i32 s10, s24, 31
	v_mov_b32_e32 v137, v19
	v_lshl_add_u32 v138, v10, 1, v0
	v_mov_b32_e32 v139, v19
	s_mov_b32 s48, 0
	v_add_u32_e32 v143, 0, v20
	s_barrier
	s_waitcnt vmcnt(0)
	s_branch .LBB0_881

; #define PG8_STAGE(bufoff, gbase, voff) do { _Pragma("unroll") for (int _i = 0; _i < 2; ++_i) \
;         __builtin_amdgcn_global_load_lds((const unsigned*)((const char*)(gbase) + (voff)[_i]), (LAS unsigned*)(lds + (bufoff) + ldsw + _i * 8192), 16, 0, 0); } while (0)
; #define PG8_LDA(dst, b, h) do { _Pragma("unroll") for (int m = 0; m < 4; ++m) _Pragma("unroll") for (int k = 0; k < 2; ++k) dst[m][k] = *(const LAS bf16x8*)(lds + PG8_SA(b, h) + aoff + m * 2048 + k * 1024); } while (0)
; #define PG8_LDB(dst, b, h) do { _Pragma("unroll") for (int n = 0; n < 2; ++n) _Pragma("unroll") for (int k = 0; k < 2; ++k) dst[n][k] = *(const LAS bf16x8*)(lds + PG8_SB(b, h) + boff + n * 2048 + k * 1024); } while (0)
; #define PG8_MMA(ai, bj, At, Bt) do { __builtin_amdgcn_s_setprio(1); _Pragma("unroll") for (int m = 0; m < 4; ++m) _Pragma("unroll") for (int n = 0; n < 2; ++n) _Pragma("unroll") for (int k = 0; k < 2; ++k) \
;         acc[ai][bj][m][n] = __builtin_amdgcn_mfma_f32_16x16x32_bf16(Bt[n][k], At[m][k], acc[ai][bj][m][n], 0, 0, 0); __builtin_amdgcn_s_setprio(0); } while (0)
; #define PG8_WAIT_V(n) asm volatile("s_waitcnt vmcnt(" #n ")" ::: "memory")
; #define PG8_WAIT_L(n) asm volatile("s_waitcnt lgkmcnt(" #n ")" ::: "memory")
; #define PG8_BAR __builtin_amdgcn_s_barrier()
; template <class Epi, class Sched, bool ALIGN_EPI = true, bool SP2 = true>
; __device__ __forceinline__ void gemm_phase(LAS unsigned char* lds, const Gemm g, const Sched& S, const Epi& E) {
;     ...
;         for (int t = 0; t < nt; t += 2) {
;             const bool last = (t == nt - 2);
;             const char* a1 = cA + (size_t)(t + 1) * kstep;
;             const char* a2 = last ? nA : cA + (size_t)(t + 2) * kstep; const char* b2 = last ? nB : cB + (size_t)(t + 2) * kstep;
;             const char* a3 = a2 + kstep; const char* b3 = b2 + kstep;
;             PG8_LDB(B0, 0, 0); PG8_LDB(B1, 0, 1); PG8_SCHED; PG8_LDA(At, 0, 0); PG8_STAGE(PG8_SA(1, 1), a1 + hstepA, voffA);
;             PG8_WAIT_V(8); PG8_WAIT_L(0); PG8_BAR; PG8_MMA(0, 0, At, B0); PG8_MMA(0, 1, At, B1); PG8_BAR; PG8_SCHED;
;             PG8_LDA(At, 0, 1); PG8_STAGE(PG8_SB(0, 0), b2, voffB); PG8_STAGE(PG8_SB(0, 1), b2 + hstepB, voffB); PG8_STAGE(PG8_SA(0, 0), a2, voffA);
;             PG8_WAIT_V(8); PG8_WAIT_L(0); PG8_BAR; PG8_MMA(1, 0, At, B0); PG8_MMA(1, 1, At, B1); PG8_BAR; PG8_SCHED;
.LBB0_884:
	s_add_u32 s18, s54, 0xfffc0080
	s_addc_u32 s19, s55, -1
	s_add_i32 s58, 0, 0x10000
	s_cmp_eq_u32 s49, 12
	s_cselect_b32 s21, s22, s19
	s_cselect_b32 s20, s23, s18
	v_add_u32_e32 v140, s58, v142
	s_cselect_b32 s19, s2, s45
	s_cselect_b32 s18, s43, s30
	s_add_i32 s61, 0, 0x14000
	ds_read_b128 v[144:147], v140
	ds_read_b128 v[148:151], v140 offset:1024
	ds_read_b128 v[152:155], v140 offset:2048
	ds_read_b128 v[156:159], v140 offset:3072
	v_add_u32_e32 v140, s61, v142
	ds_read_b128 v[160:163], v140
	ds_read_b128 v[164:167], v140 offset:1024
	ds_read_b128 v[168:171], v140 offset:2048
	ds_read_b128 v[172:175], v140 offset:3072
	s_add_i32 m0, s53, 0xc000
	ds_read_b128 v[186:189], v143
	ds_read_b128 v[190:193], v143 offset:1024
	ds_read_b128 v[198:201], v143 offset:2048
	ds_read_b128 v[202:205], v143 offset:3072
	ds_read_b128 v[206:209], v143 offset:4096
	ds_read_b128 v[210:213], v143 offset:5120
	ds_read_b128 v[218:221], v143 offset:6144
	ds_read_b128 v[222:225], v143 offset:7168
	global_load_lds_dwordx4 v136, s[54:55]
	s_add_i32 m0, s53, 0xe000
	s_nop 0
	global_load_lds_dwordx4 v138, s[54:55]
	s_waitcnt vmcnt(8)
	s_waitcnt lgkmcnt(0)
	s_barrier
	s_setprio 1
	s_waitcnt lgkmcnt(0)
	v_mfma_f32_16x16x32_bf16 v[128:131], v[144:147], v[186:189], v[128:131]
	v_mfma_f32_16x16x32_bf16 v[124:127], v[152:155], v[186:189], v[124:127]
	v_mfma_f32_16x16x32_bf16 v[120:123], v[144:147], v[198:201], v[120:123]
	v_mfma_f32_16x16x32_bf16 v[112:115], v[152:155], v[198:201], v[112:115]
	v_mfma_f32_16x16x32_bf16 v[104:107], v[144:147], v[206:209], v[104:107]
	v_mfma_f32_16x16x32_bf16 v[96:99], v[152:155], v[206:209], v[96:99]
	v_mfma_f32_16x16x32_bf16 v[88:91], v[144:147], v[218:221], v[88:91]
	v_mfma_f32_16x16x32_bf16 v[80:83], v[152:155], v[218:221], v[80:83]
	v_mfma_f32_16x16x32_bf16 v[128:131], v[148:151], v[190:193], v[128:131]
	v_mfma_f32_16x16x32_bf16 v[124:127], v[156:159], v[190:193], v[124:127]
	v_mfma_f32_16x16x32_bf16 v[120:123], v[148:151], v[202:205], v[120:123]
	v_mfma_f32_16x16x32_bf16 v[112:115], v[156:159], v[202:205], v[112:115]
	v_mfma_f32_16x16x32_bf16 v[104:107], v[148:151], v[210:213], v[104:107]
	v_mfma_f32_16x16x32_bf16 v[96:99], v[156:159], v[210:213], v[96:99]
	v_mfma_f32_16x16x32_bf16 v[88:91], v[148:151], v[222:225], v[88:91]
	v_mfma_f32_16x16x32_bf16 v[80:83], v[156:159], v[222:225], v[80:83]
	s_setprio 0
	s_setprio 1
	v_mfma_f32_16x16x32_bf16 v[116:119], v[160:163], v[186:189], v[116:119]
	v_mfma_f32_16x16x32_bf16 v[108:111], v[168:171], v[186:189], v[108:111]
	v_mfma_f32_16x16x32_bf16 v[100:103], v[160:163], v[198:201], v[100:103]
	v_mfma_f32_16x16x32_bf16 v[92:95], v[168:171], v[198:201], v[92:95]
	v_mfma_f32_16x16x32_bf16 v[84:87], v[160:163], v[206:209], v[84:87]
	v_mfma_f32_16x16x32_bf16 v[76:79], v[168:171], v[206:209], v[76:79]
	v_mfma_f32_16x16x32_bf16 v[72:75], v[160:163], v[218:221], v[72:75]
	v_mfma_f32_16x16x32_bf16 v[68:71], v[168:171], v[218:221], v[68:71]
	v_mfma_f32_16x16x32_bf16 v[116:119], v[164:167], v[190:193], v[116:119]
	v_mfma_f32_16x16x32_bf16 v[108:111], v[172:175], v[190:193], v[108:111]
	v_mfma_f32_16x16x32_bf16 v[100:103], v[164:167], v[202:205], v[100:103]
	v_mfma_f32_16x16x32_bf16 v[92:95], v[172:175], v[202:205], v[92:95]
	v_mfma_f32_16x16x32_bf16 v[84:87], v[164:167], v[210:213], v[84:87]
	v_mfma_f32_16x16x32_bf16 v[76:79], v[172:175], v[210:213], v[76:79]
	v_mfma_f32_16x16x32_bf16 v[72:75], v[164:167], v[222:225], v[72:75]
	v_mfma_f32_16x16x32_bf16 v[68:71], v[172:175], v[222:225], v[68:71]
	s_setprio 0
	s_barrier
	s_add_i32 s58, s58, s39
	v_lshl_add_u64 v[140:141], s[18:19], 0, v[18:19]
	s_mov_b32 m0, s58
	ds_read_b128 v[186:189], v143 offset:16384
	ds_read_b128 v[190:193], v143 offset:17408
	ds_read_b128 v[198:201], v143 offset:18432
	ds_read_b128 v[202:205], v143 offset:19456
	ds_read_b128 v[206:209], v143 offset:20480
	ds_read_b128 v[210:213], v143 offset:21504
	ds_read_b128 v[218:221], v143 offset:22528
	ds_read_b128 v[222:225], v143 offset:23552
	global_load_lds_dwordx4 v[140:141], off
	s_add_i32 m0, s58, 0x2000
	s_add_u32 s58, s18, 0x40000
	v_lshl_add_u64 v[176:177], s[18:19], 0, v[16:17]
	s_addc_u32 s59, s19, 0
	s_add_i32 s61, s61, s39
	global_load_lds_dwordx4 v[176:177], off
	s_mov_b32 m0, s61
	v_lshl_add_u64 v[182:183], s[20:21], 0, v[132:133]
	global_load_lds_dwordx4 v18, s[58:59]
	s_add_i32 m0, s61, 0x2000
	s_nop 0
	global_load_lds_dwordx4 v16, s[58:59]
	v_lshl_add_u64 v[178:179], s[20:21], 0, v[134:135]
	s_mov_b32 m0, s53
	s_nop 0
	global_load_lds_dwordx4 v[178:179], off
	s_mov_b32 m0, s56
	s_nop 0
	global_load_lds_dwordx4 v[182:183], off
	s_waitcnt vmcnt(8)
	s_waitcnt lgkmcnt(0)
	s_barrier
; #define PG8_STAGE(bufoff, gbase, voff) do { _Pragma("unroll") for (int _i = 0; _i < 2; ++_i) \
;         __builtin_amdgcn_global_load_lds((const unsigned*)((const char*)(gbase) + (voff)[_i]), (LAS unsigned*)(lds + (bufoff) + ldsw + _i * 8192), 16, 0, 0); } while (0)
; #define PG8_LDA(dst, b, h) do { _Pragma("unroll") for (int m = 0; m < 4; ++m) _Pragma("unroll") for (int k = 0; k < 2; ++k) dst[m][k] = *(const LAS bf16x8*)(lds + PG8_SA(b, h) + aoff + m * 2048 + k * 1024); } while (0)
; #define PG8_LDB(dst, b, h) do { _Pragma("unroll") for (int n = 0; n < 2; ++n) _Pragma("unroll") for (int k = 0; k < 2; ++k) dst[n][k] = *(const LAS bf16x8*)(lds + PG8_SB(b, h) + boff + n * 2048 + k * 1024); } while (0)
; #define PG8_MMA(ai, bj, At, Bt) do { __builtin_amdgcn_s_setprio(1); _Pragma("unroll") for (int m = 0; m < 4; ++m) _Pragma("unroll") for (int n = 0; n < 2; ++n) _Pragma("unroll") for (int k = 0; k < 2; ++k) \
;         acc[ai][bj][m][n] = __builtin_amdgcn_mfma_f32_16x16x32_bf16(Bt[n][k], At[m][k], acc[ai][bj][m][n], 0, 0, 0); __builtin_amdgcn_s_setprio(0); } while (0)
; #define PG8_WAIT_V(n) asm volatile("s_waitcnt vmcnt(" #n ")" ::: "memory")
; #define PG8_WAIT_L(n) asm volatile("s_waitcnt lgkmcnt(" #n ")" ::: "memory")
; #define PG8_BAR __builtin_amdgcn_s_barrier()
; #define PG8_SCHED __builtin_amdgcn_sched_barrier(0)
; template <class Epi, class Sched, bool ALIGN_EPI = true, bool SP2 = true>
; __device__ __forceinline__ void gemm_phase(LAS unsigned char* lds, const Gemm g, const Sched& S, const Epi& E) {
;     ...
;             PG8_WAIT_V(8); PG8_WAIT_L(0); PG8_BAR; PG8_MMA(1, 0, At, B0); PG8_MMA(1, 1, At, B1); PG8_BAR; PG8_SCHED;
;             PG8_LDB(B0, 1, 0); PG8_LDB(B1, 1, 1); PG8_SCHED; PG8_LDA(At, 1, 0); PG8_STAGE(PG8_SA(0, 1), a2 + hstepA, voffA);
;             PG8_WAIT_V(8); PG8_WAIT_L(0); PG8_BAR; PG8_MMA(0, 0, At, B0); PG8_MMA(0, 1, At, B1); PG8_BAR; PG8_SCHED;
	s_setprio 1
	s_waitcnt lgkmcnt(0)
	v_mfma_f32_16x16x32_bf16 v[64:67], v[144:147], v[186:189], v[64:67]
	v_mfma_f32_16x16x32_bf16 v[60:63], v[152:155], v[186:189], v[60:63]
	v_mfma_f32_16x16x32_bf16 v[56:59], v[144:147], v[198:201], v[56:59]
	v_mfma_f32_16x16x32_bf16 v[48:51], v[152:155], v[198:201], v[48:51]
	v_mfma_f32_16x16x32_bf16 v[40:43], v[144:147], v[206:209], v[40:43]
	v_mfma_f32_16x16x32_bf16 v[32:35], v[152:155], v[206:209], v[32:35]
	v_mfma_f32_16x16x32_bf16 v[24:27], v[144:147], v[218:221], v[24:27]
	v_mfma_f32_16x16x32_bf16 v[12:15], v[152:155], v[218:221], v[12:15]
	v_mfma_f32_16x16x32_bf16 v[64:67], v[148:151], v[190:193], v[64:67]
	v_mfma_f32_16x16x32_bf16 v[60:63], v[156:159], v[190:193], v[60:63]
	v_mfma_f32_16x16x32_bf16 v[56:59], v[148:151], v[202:205], v[56:59]
	v_mfma_f32_16x16x32_bf16 v[48:51], v[156:159], v[202:205], v[48:51]
	v_mfma_f32_16x16x32_bf16 v[40:43], v[148:151], v[210:213], v[40:43]
	v_mfma_f32_16x16x32_bf16 v[32:35], v[156:159], v[210:213], v[32:35]
	v_mfma_f32_16x16x32_bf16 v[24:27], v[148:151], v[222:225], v[24:27]
	v_mfma_f32_16x16x32_bf16 v[12:15], v[156:159], v[222:225], v[12:15]
	s_setprio 0
	s_setprio 1
	v_mfma_f32_16x16x32_bf16 v[52:55], v[160:163], v[186:189], v[52:55]
	v_mfma_f32_16x16x32_bf16 v[44:47], v[168:171], v[186:189], v[44:47]
	v_mfma_f32_16x16x32_bf16 v[36:39], v[160:163], v[198:201], v[36:39]
	v_mfma_f32_16x16x32_bf16 v[28:31], v[168:171], v[198:201], v[28:31]
	v_mfma_f32_16x16x32_bf16 v[20:23], v[160:163], v[206:209], v[20:23]
	v_mfma_f32_16x16x32_bf16 v[8:11], v[168:171], v[206:209], v[8:11]
	v_mfma_f32_16x16x32_bf16 v[4:7], v[160:163], v[218:221], v[4:7]
	v_mfma_f32_16x16x32_bf16 v[0:3], v[168:171], v[218:221], v[0:3]
	v_mfma_f32_16x16x32_bf16 v[52:55], v[164:167], v[190:193], v[52:55]
	v_mfma_f32_16x16x32_bf16 v[44:47], v[172:175], v[190:193], v[44:47]
	v_mfma_f32_16x16x32_bf16 v[36:39], v[164:167], v[202:205], v[36:39]
	v_mfma_f32_16x16x32_bf16 v[28:31], v[172:175], v[202:205], v[28:31]
	v_mfma_f32_16x16x32_bf16 v[20:23], v[164:167], v[210:213], v[20:23]
	v_mfma_f32_16x16x32_bf16 v[8:11], v[172:175], v[210:213], v[8:11]
	v_mfma_f32_16x16x32_bf16 v[4:7], v[164:167], v[222:225], v[4:7]
	v_mfma_f32_16x16x32_bf16 v[0:3], v[172:175], v[222:225], v[0:3]
	s_setprio 0
	s_barrier
	s_add_i32 s58, 0, 0x18000
	s_add_i32 s59, 0, 0x1c000
	v_add_u32_e32 v156, s58, v142
	v_add_u32_e32 v172, s59, v142
	ds_read_b128 v[144:147], v156
	ds_read_b128 v[148:151], v156 offset:1024
	ds_read_b128 v[152:155], v156 offset:2048
	ds_read_b128 v[156:159], v156 offset:3072
	ds_read_b128 v[160:163], v172
	ds_read_b128 v[164:167], v172 offset:1024
	ds_read_b128 v[168:171], v172 offset:2048
	ds_read_b128 v[172:175], v172 offset:3072
	s_add_u32 s20, s20, 0x40000
	s_addc_u32 s21, s21, 0
	s_mov_b32 m0, s57
	ds_read_b128 v[186:189], v143 offset:32768
	ds_read_b128 v[190:193], v143 offset:33792
	ds_read_b128 v[198:201], v143 offset:34816
	ds_read_b128 v[202:205], v143 offset:35840
	ds_read_b128 v[206:209], v143 offset:36864
	ds_read_b128 v[210:213], v143 offset:37888
	ds_read_b128 v[218:221], v143 offset:38912
	ds_read_b128 v[222:225], v143 offset:39936
	global_load_lds_dwordx4 v134, s[20:21]
	v_lshl_add_u64 v[214:215], s[20:21], 0, v[132:133]
	s_mov_b32 m0, s60
	s_nop 0
	global_load_lds_dwordx4 v[214:215], off
	s_waitcnt vmcnt(8)
	s_waitcnt lgkmcnt(0)
	s_barrier
	s_setprio 1
	s_waitcnt lgkmcnt(0)
	v_mfma_f32_16x16x32_bf16 v[128:131], v[144:147], v[186:189], v[128:131]
	v_mfma_f32_16x16x32_bf16 v[124:127], v[152:155], v[186:189], v[124:127]
	v_mfma_f32_16x16x32_bf16 v[120:123], v[144:147], v[198:201], v[120:123]
	v_mfma_f32_16x16x32_bf16 v[112:115], v[152:155], v[198:201], v[112:115]
	v_mfma_f32_16x16x32_bf16 v[104:107], v[144:147], v[206:209], v[104:107]
	v_mfma_f32_16x16x32_bf16 v[96:99], v[152:155], v[206:209], v[96:99]
	v_mfma_f32_16x16x32_bf16 v[88:91], v[144:147], v[218:221], v[88:91]
	v_mfma_f32_16x16x32_bf16 v[80:83], v[152:155], v[218:221], v[80:83]
	v_mfma_f32_16x16x32_bf16 v[128:131], v[148:151], v[190:193], v[128:131]
	v_mfma_f32_16x16x32_bf16 v[124:127], v[156:159], v[190:193], v[124:127]
	v_mfma_f32_16x16x32_bf16 v[120:123], v[148:151], v[202:205], v[120:123]
	v_mfma_f32_16x16x32_bf16 v[112:115], v[156:159], v[202:205], v[112:115]
	v_mfma_f32_16x16x32_bf16 v[104:107], v[148:151], v[210:213], v[104:107]
	v_mfma_f32_16x16x32_bf16 v[96:99], v[156:159], v[210:213], v[96:99]
	v_mfma_f32_16x16x32_bf16 v[88:91], v[148:151], v[222:225], v[88:91]
	v_mfma_f32_16x16x32_bf16 v[80:83], v[156:159], v[222:225], v[80:83]
	s_setprio 0
	s_setprio 1
	v_mfma_f32_16x16x32_bf16 v[116:119], v[160:163], v[186:189], v[116:119]
	v_mfma_f32_16x16x32_bf16 v[108:111], v[168:171], v[186:189], v[108:111]
	v_mfma_f32_16x16x32_bf16 v[100:103], v[160:163], v[198:201], v[100:103]
	v_mfma_f32_16x16x32_bf16 v[92:95], v[168:171], v[198:201], v[92:95]
	v_mfma_f32_16x16x32_bf16 v[84:87], v[160:163], v[206:209], v[84:87]
	v_mfma_f32_16x16x32_bf16 v[76:79], v[168:171], v[206:209], v[76:79]
	v_mfma_f32_16x16x32_bf16 v[72:75], v[160:163], v[218:221], v[72:75]
	v_mfma_f32_16x16x32_bf16 v[68:71], v[168:171], v[218:221], v[68:71]
	v_mfma_f32_16x16x32_bf16 v[116:119], v[164:167], v[190:193], v[116:119]
	v_mfma_f32_16x16x32_bf16 v[108:111], v[172:175], v[190:193], v[108:111]
	v_mfma_f32_16x16x32_bf16 v[100:103], v[164:167], v[202:205], v[100:103]
	v_mfma_f32_16x16x32_bf16 v[92:95], v[172:175], v[202:205], v[92:95]
	v_mfma_f32_16x16x32_bf16 v[84:87], v[164:167], v[210:213], v[84:87]
	v_mfma_f32_16x16x32_bf16 v[76:79], v[172:175], v[210:213], v[76:79]
	v_mfma_f32_16x16x32_bf16 v[72:75], v[164:167], v[222:225], v[72:75]
	v_mfma_f32_16x16x32_bf16 v[68:71], v[172:175], v[222:225], v[68:71]
	s_setprio 0
	s_barrier
; #define PG8_STAGE(bufoff, gbase, voff) do { _Pragma("unroll") for (int _i = 0; _i < 2; ++_i) \
;         __builtin_amdgcn_global_load_lds((const unsigned*)((const char*)(gbase) + (voff)[_i]), (LAS unsigned*)(lds + (bufoff) + ldsw + _i * 8192), 16, 0, 0); } while (0)
; #define PG8_LDA(dst, b, h) do { _Pragma("unroll") for (int m = 0; m < 4; ++m) _Pragma("unroll") for (int k = 0; k < 2; ++k) dst[m][k] = *(const LAS bf16x8*)(lds + PG8_SA(b, h) + aoff + m * 2048 + k * 1024); } while (0)
; #define PG8_MMA(ai, bj, At, Bt) do { __builtin_amdgcn_s_setprio(1); _Pragma("unroll") for (int m = 0; m < 4; ++m) _Pragma("unroll") for (int n = 0; n < 2; ++n) _Pragma("unroll") for (int k = 0; k < 2; ++k) \
;         acc[ai][bj][m][n] = __builtin_amdgcn_mfma_f32_16x16x32_bf16(Bt[n][k], At[m][k], acc[ai][bj][m][n], 0, 0, 0); __builtin_amdgcn_s_setprio(0); } while (0)
; #define PG8_WAIT_V(n) asm volatile("s_waitcnt vmcnt(" #n ")" ::: "memory")
; #define PG8_WAIT_L(n) asm volatile("s_waitcnt lgkmcnt(" #n ")" ::: "memory")
; #define PG8_BAR __builtin_amdgcn_s_barrier()
; #define PG8_SCHED __builtin_amdgcn_sched_barrier(0)
; template <class Epi, class Sched, bool ALIGN_EPI = true, bool SP2 = true>
; __device__ __forceinline__ void gemm_phase(LAS unsigned char* lds, const Gemm g, const Sched& S, const Epi& E) {
;     ...
;             PG8_LDA(At, 1, 1); PG8_STAGE(PG8_SB(1, 0), b3, voffB); PG8_STAGE(PG8_SB(1, 1), b3 + hstepB, voffB); PG8_STAGE(PG8_SA(1, 0), a3, voffA);
;             PG8_WAIT_V(8); PG8_WAIT_L(0); PG8_BAR; PG8_MMA(1, 0, At, B0); PG8_MMA(1, 1, At, B1); PG8_BAR; PG8_SCHED;
;         }
	s_add_i32 s20, s58, s39
	v_lshl_add_u64 v[140:141], v[140:141], 0, s[14:15]
	s_mov_b32 m0, s20
	ds_read_b128 v[186:189], v143 offset:49152
	ds_read_b128 v[190:193], v143 offset:50176
	ds_read_b128 v[198:201], v143 offset:51200
	ds_read_b128 v[202:205], v143 offset:52224
	ds_read_b128 v[206:209], v143 offset:53248
	ds_read_b128 v[210:213], v143 offset:54272
	ds_read_b128 v[218:221], v143 offset:55296
	ds_read_b128 v[222:225], v143 offset:56320
	global_load_lds_dwordx4 v[140:141], off
	s_add_i32 m0, s20, 0x2000
	s_add_u32 s18, s18, 0x40080
	v_lshl_add_u64 v[140:141], v[176:177], 0, s[14:15]
	s_addc_u32 s19, s19, 0
	s_add_i32 s20, s59, s39
	global_load_lds_dwordx4 v[140:141], off
	s_mov_b32 m0, s20
	s_nop 0
	global_load_lds_dwordx4 v18, s[18:19]
	v_lshl_add_u64 v[140:141], s[18:19], 0, v[16:17]
	s_add_i32 m0, s20, 0x2000
	s_nop 0
	global_load_lds_dwordx4 v[140:141], off
	v_lshl_add_u64 v[140:141], v[178:179], 0, s[14:15]
	s_mov_b32 m0, s8
	s_nop 0
	global_load_lds_dwordx4 v[140:141], off
	v_lshl_add_u64 v[140:141], v[182:183], 0, s[14:15]
	s_mov_b32 m0, s9
	s_nop 0
	global_load_lds_dwordx4 v[140:141], off
	s_waitcnt vmcnt(8)
	s_waitcnt lgkmcnt(0)
	s_barrier
	s_setprio 1
	s_waitcnt lgkmcnt(0)
	v_mfma_f32_16x16x32_bf16 v[64:67], v[144:147], v[186:189], v[64:67]
	v_mfma_f32_16x16x32_bf16 v[60:63], v[152:155], v[186:189], v[60:63]
	v_mfma_f32_16x16x32_bf16 v[56:59], v[144:147], v[198:201], v[56:59]
	v_mfma_f32_16x16x32_bf16 v[48:51], v[152:155], v[198:201], v[48:51]
	v_mfma_f32_16x16x32_bf16 v[40:43], v[144:147], v[206:209], v[40:43]
	v_mfma_f32_16x16x32_bf16 v[32:35], v[152:155], v[206:209], v[32:35]
	v_mfma_f32_16x16x32_bf16 v[24:27], v[144:147], v[218:221], v[24:27]
	v_mfma_f32_16x16x32_bf16 v[12:15], v[152:155], v[218:221], v[12:15]
	v_mfma_f32_16x16x32_bf16 v[64:67], v[148:151], v[190:193], v[64:67]
	v_mfma_f32_16x16x32_bf16 v[60:63], v[156:159], v[190:193], v[60:63]
	v_mfma_f32_16x16x32_bf16 v[56:59], v[148:151], v[202:205], v[56:59]
	v_mfma_f32_16x16x32_bf16 v[48:51], v[156:159], v[202:205], v[48:51]
	v_mfma_f32_16x16x32_bf16 v[40:43], v[148:151], v[210:213], v[40:43]
	v_mfma_f32_16x16x32_bf16 v[32:35], v[156:159], v[210:213], v[32:35]
	v_mfma_f32_16x16x32_bf16 v[24:27], v[148:151], v[222:225], v[24:27]
	v_mfma_f32_16x16x32_bf16 v[12:15], v[156:159], v[222:225], v[12:15]
	s_setprio 0
	s_setprio 1
	v_mfma_f32_16x16x32_bf16 v[52:55], v[160:163], v[186:189], v[52:55]
	v_mfma_f32_16x16x32_bf16 v[44:47], v[168:171], v[186:189], v[44:47]
	v_mfma_f32_16x16x32_bf16 v[36:39], v[160:163], v[198:201], v[36:39]
	v_mfma_f32_16x16x32_bf16 v[28:31], v[168:171], v[198:201], v[28:31]
	v_mfma_f32_16x16x32_bf16 v[20:23], v[160:163], v[206:209], v[20:23]
	v_mfma_f32_16x16x32_bf16 v[8:11], v[168:171], v[206:209], v[8:11]
	v_mfma_f32_16x16x32_bf16 v[4:7], v[160:163], v[218:221], v[4:7]
	v_mfma_f32_16x16x32_bf16 v[0:3], v[168:171], v[218:221], v[0:3]
	v_mfma_f32_16x16x32_bf16 v[52:55], v[164:167], v[190:193], v[52:55]
	v_mfma_f32_16x16x32_bf16 v[44:47], v[172:175], v[190:193], v[44:47]
	v_mfma_f32_16x16x32_bf16 v[36:39], v[164:167], v[202:205], v[36:39]
	v_mfma_f32_16x16x32_bf16 v[28:31], v[172:175], v[202:205], v[28:31]
	v_mfma_f32_16x16x32_bf16 v[20:23], v[164:167], v[210:213], v[20:23]
	v_mfma_f32_16x16x32_bf16 v[8:11], v[172:175], v[210:213], v[8:11]
	v_mfma_f32_16x16x32_bf16 v[4:7], v[164:167], v[222:225], v[4:7]
	v_mfma_f32_16x16x32_bf16 v[0:3], v[172:175], v[222:225], v[0:3]
	s_setprio 0
	s_barrier
	s_add_i32 s49, s49, 2
	s_add_u32 s54, s54, 0x100
	s_addc_u32 s55, s55, 0
	s_add_u32 s30, s30, 0x100
	s_addc_u32 s45, s45, 0
	s_cmp_gt_u32 s49, 13
	s_cbranch_scc0 .LBB0_884
	s_and_b64 vcc, exec, s[36:37]
	s_cbranch_vccz .LBB0_887
	s_barrier

; #define PG8_STAGE(bufoff, gbase, voff) do { _Pragma("unroll") for (int _i = 0; _i < 2; ++_i) \
;         __builtin_amdgcn_global_load_lds((const unsigned*)((const char*)(gbase) + (voff)[_i]), (LAS unsigned*)(lds + (bufoff) + ldsw + _i * 8192), 16, 0, 0); } while (0)
; #define PG8_WAIT_V(n) asm volatile("s_waitcnt vmcnt(" #n ")" ::: "memory")
; #define PG8_BAR __builtin_amdgcn_s_barrier()
; template <class Epi, class Sched, bool ALIGN_EPI = true, bool SP2 = true>
; __device__ __forceinline__ void gemm_phase(LAS unsigned char* lds, const Gemm g, const Sched& S, const Epi& E) {
;     ...
;     const char* cA = (const char*)g.A + (size_t)cur.pm * tstepA; const char* cB = (const char*)g.Bt + (size_t)cur.pn * tstepB;
;     if constexpr (SP2) {
;         PG8_STAGE(PG8_SB(0, 0), cB, voffB); PG8_STAGE(PG8_SB(0, 1), cB + hstepB, voffB); PG8_STAGE(PG8_SA(0, 0), cA, voffA); PG8_STAGE(PG8_SA(0, 1), cA + hstepA, voffA);
;         if (wr == 1) PG8_BAR;
;         PG8_WAIT_V(2); PG8_BAR;
;         PG8_STAGE(PG8_SB(1, 0), cB + kstep, voffB); PG8_STAGE(PG8_SA(1, 0), cA + kstep, voffA); PG8_STAGE(PG8_SB(1, 1), cB + hstepB + kstep, voffB);
;         PG8_WAIT_V(6); PG8_BAR;
.LBB0_1057:
	s_add_u32 s42, s20, 0x29600000
	s_addc_u32 s43, s21, 0
	v_and_b32_e32 v15, 48, v14
	v_lshlrev_b32_e32 v20, 6, v14
	s_movk_i32 s21, 0x3c0
	v_lshlrev_b32_e32 v14, 2, v14
	s_lshl_b32 s20, s30, 13
	v_and_or_b32 v15, v20, s21, v15
	v_and_b32_e32 v14, 32, v14
	v_bitop3_b32 v20, v15, s20, v14 bitop3:0xde
	s_lshl_b32 s20, s23, 5
	s_and_b32 s48, s20, 0x60
	s_add_i32 m0, s65, 0x18000
	v_lshl_add_u64 v[6:7], v[6:7], 0, s[14:15]
	s_lshl_b32 s9, s30, 6
	s_lshl_b32 s20, s48, 7
	s_waitcnt vmcnt(2)
	s_barrier
	global_load_lds_dwordx4 v[6:7], off
	v_lshl_add_u64 v[4:5], v[4:5], 0, s[14:15]
	s_add_i32 m0, s65, 0x1a000
	s_add_i32 s49, s65, 0x8000
	s_add_i32 s66, s65, 0xa000
	v_bitop3_b32 v144, s20, v15, v14 bitop3:0xf6
	global_load_lds_dwordx4 v[4:5], off
	v_lshl_add_u64 v[0:1], v[0:1], 0, s[14:15]
	s_mov_b32 m0, s49
	s_add_u32 s20, s18, 0x40080
	global_load_lds_dwordx4 v[0:1], off
	v_lshl_add_u64 v[0:1], v[2:3], 0, s[14:15]
	s_mov_b32 m0, s66
	s_addc_u32 s21, s19, 0
	global_load_lds_dwordx4 v[0:1], off
	s_add_i32 m0, s65, 0x1c000
	s_nop 0
	global_load_lds_dwordx4 v18, s[20:21]
	s_add_i32 m0, s65, 0x1e000
	s_cmpk_lt_u32 s2, 0x100
	global_load_lds_dwordx4 v16, s[20:21]
	v_lshlrev_b32_e32 v0, 14, v12
	v_and_b32_e32 v0, 0xffff8000, v0
	v_lshl_add_u32 v0, v11, 11, v0
	v_and_b32_e32 v1, 1, v12
	v_lshl_or_b32 v0, v1, 6, v0
	v_lshl_add_u32 v136, v13, 1, v0
	v_lshlrev_b32_e32 v0, 14, v8
	v_and_b32_e32 v0, 0xffff8000, v0
	s_waitcnt vmcnt(6)
	v_lshl_add_u32 v0, v9, 11, v0
	v_and_b32_e32 v1, 1, v8
	v_lshl_or_b32 v0, v1, 6, v0
	s_sext_i32_i16 s17, s22
	s_cselect_b64 s[44:45], -1, 0
	s_ashr_i32 s67, s24, 31
	v_mov_b32_e32 v137, v19
	v_lshl_add_u32 v138, v10, 1, v0
	v_mov_b32_e32 v139, v19
	s_mov_b32 s61, 0
	v_add_u32_e32 v145, 0, v20
	s_barrier
	s_waitcnt vmcnt(0)
	s_branch .LBB0_1060

; #define PG8_STAGE(bufoff, gbase, voff) do { _Pragma("unroll") for (int _i = 0; _i < 2; ++_i) \
;         __builtin_amdgcn_global_load_lds((const unsigned*)((const char*)(gbase) + (voff)[_i]), (LAS unsigned*)(lds + (bufoff) + ldsw + _i * 8192), 16, 0, 0); } while (0)
; #define PG8_LDA(dst, b, h) do { _Pragma("unroll") for (int m = 0; m < 4; ++m) _Pragma("unroll") for (int k = 0; k < 2; ++k) dst[m][k] = *(const LAS bf16x8*)(lds + PG8_SA(b, h) + aoff + m * 2048 + k * 1024); } while (0)
; #define PG8_LDB(dst, b, h) do { _Pragma("unroll") for (int n = 0; n < 2; ++n) _Pragma("unroll") for (int k = 0; k < 2; ++k) dst[n][k] = *(const LAS bf16x8*)(lds + PG8_SB(b, h) + boff + n * 2048 + k * 1024); } while (0)
; #define PG8_MMA(ai, bj, At, Bt) do { __builtin_amdgcn_s_setprio(1); _Pragma("unroll") for (int m = 0; m < 4; ++m) _Pragma("unroll") for (int n = 0; n < 2; ++n) _Pragma("unroll") for (int k = 0; k < 2; ++k) \
;         acc[ai][bj][m][n] = __builtin_amdgcn_mfma_f32_16x16x32_bf16(Bt[n][k], At[m][k], acc[ai][bj][m][n], 0, 0, 0); __builtin_amdgcn_s_setprio(0); } while (0)
; #define PG8_WAIT_V(n) asm volatile("s_waitcnt vmcnt(" #n ")" ::: "memory")
; #define PG8_WAIT_L(n) asm volatile("s_waitcnt lgkmcnt(" #n ")" ::: "memory")
; #define PG8_BAR __builtin_amdgcn_s_barrier()
; template <class Epi, class Sched, bool ALIGN_EPI = true, bool SP2 = true>
; __device__ __forceinline__ void gemm_phase(LAS unsigned char* lds, const Gemm g, const Sched& S, const Epi& E) {
;     ...
;         for (int t = 0; t < nt; t += 2) {
;             const bool last = (t == nt - 2);
;             const char* a1 = cA + (size_t)(t + 1) * kstep;
;             const char* a2 = last ? nA : cA + (size_t)(t + 2) * kstep; const char* b2 = last ? nB : cB + (size_t)(t + 2) * kstep;
;             const char* a3 = a2 + kstep; const char* b3 = b2 + kstep;
;             PG8_LDB(B0, 0, 0); PG8_LDB(B1, 0, 1); PG8_SCHED; PG8_LDA(At, 0, 0); PG8_STAGE(PG8_SA(1, 1), a1 + hstepA, voffA);
;             PG8_WAIT_V(8); PG8_WAIT_L(0); PG8_BAR; PG8_MMA(0, 0, At, B0); PG8_MMA(0, 1, At, B1); PG8_BAR; PG8_SCHED;
;             PG8_LDA(At, 0, 1); PG8_STAGE(PG8_SB(0, 0), b2, voffB); PG8_STAGE(PG8_SB(0, 1), b2 + hstepB, voffB); PG8_STAGE(PG8_SA(0, 0), a2, voffA);
;             PG8_WAIT_V(8); PG8_WAIT_L(0); PG8_BAR; PG8_MMA(1, 0, At, B0); PG8_MMA(1, 1, At, B1); PG8_BAR; PG8_SCHED;
.LBB0_1063:
	s_add_u32 s18, vcc_lo, 0xfffc0080
	s_addc_u32 s19, vcc_hi, -1
	s_add_i32 s34, 0, 0x10000
	s_cmp_eq_u32 s58, 12
	s_cselect_b32 s23, s51, s19
	s_cselect_b32 s22, s2, s18
	s_cselect_b32 s19, s47, s55
	s_cselect_b32 s18, s30, s54
	s_add_i32 s59, 0, 0x14000
	v_add_u32_e32 v154, s34, v144
	v_add_u32_e32 v170, s59, v144
	ds_read_b128 v[140:143], v154
	ds_read_b128 v[146:149], v154 offset:1024
	ds_read_b128 v[150:153], v154 offset:2048
	ds_read_b128 v[154:157], v154 offset:3072
	ds_read_b128 v[158:161], v170
	ds_read_b128 v[162:165], v170 offset:1024
	ds_read_b128 v[166:169], v170 offset:2048
	ds_read_b128 v[170:173], v170 offset:3072
	v_lshl_add_u64 v[178:179], vcc, 0, v[136:137]
	s_add_i32 m0, s65, 0xc000
	ds_read_b128 v[174:177], v145
	ds_read_b128 v[186:189], v145 offset:1024
	ds_read_b128 v[190:193], v145 offset:2048
	ds_read_b128 v[198:201], v145 offset:3072
	ds_read_b128 v[202:205], v145 offset:4096
	ds_read_b128 v[206:209], v145 offset:5120
	ds_read_b128 v[210:213], v145 offset:6144
	ds_read_b128 v[218:221], v145 offset:7168
	global_load_lds_dwordx4 v[178:179], off
	v_lshl_add_u64 v[178:179], vcc, 0, v[138:139]
	s_add_i32 m0, s65, 0xe000
	s_nop 0
	global_load_lds_dwordx4 v[178:179], off
	s_waitcnt vmcnt(8)
	s_waitcnt lgkmcnt(0)
	s_barrier
	s_setprio 1
	s_waitcnt lgkmcnt(0)
	v_mfma_f32_16x16x32_bf16 v[128:131], v[140:143], v[174:177], v[128:131]
	v_mfma_f32_16x16x32_bf16 v[124:127], v[150:153], v[174:177], v[124:127]
	v_mfma_f32_16x16x32_bf16 v[120:123], v[140:143], v[190:193], v[120:123]
	v_mfma_f32_16x16x32_bf16 v[112:115], v[150:153], v[190:193], v[112:115]
	v_mfma_f32_16x16x32_bf16 v[104:107], v[140:143], v[202:205], v[104:107]
	v_mfma_f32_16x16x32_bf16 v[96:99], v[150:153], v[202:205], v[96:99]
	v_mfma_f32_16x16x32_bf16 v[88:91], v[140:143], v[210:213], v[88:91]
	v_mfma_f32_16x16x32_bf16 v[80:83], v[150:153], v[210:213], v[80:83]
	v_mfma_f32_16x16x32_bf16 v[128:131], v[146:149], v[186:189], v[128:131]
	v_mfma_f32_16x16x32_bf16 v[124:127], v[154:157], v[186:189], v[124:127]
	v_mfma_f32_16x16x32_bf16 v[120:123], v[146:149], v[198:201], v[120:123]
	v_mfma_f32_16x16x32_bf16 v[112:115], v[154:157], v[198:201], v[112:115]
	v_mfma_f32_16x16x32_bf16 v[104:107], v[146:149], v[206:209], v[104:107]
	v_mfma_f32_16x16x32_bf16 v[96:99], v[154:157], v[206:209], v[96:99]
	v_mfma_f32_16x16x32_bf16 v[88:91], v[146:149], v[218:221], v[88:91]
	v_mfma_f32_16x16x32_bf16 v[80:83], v[154:157], v[218:221], v[80:83]
	s_setprio 0
	s_setprio 1
	v_mfma_f32_16x16x32_bf16 v[116:119], v[158:161], v[174:177], v[116:119]
	v_mfma_f32_16x16x32_bf16 v[108:111], v[166:169], v[174:177], v[108:111]
	v_mfma_f32_16x16x32_bf16 v[100:103], v[158:161], v[190:193], v[100:103]
	v_mfma_f32_16x16x32_bf16 v[92:95], v[166:169], v[190:193], v[92:95]
	v_mfma_f32_16x16x32_bf16 v[84:87], v[158:161], v[202:205], v[84:87]
	v_mfma_f32_16x16x32_bf16 v[76:79], v[166:169], v[202:205], v[76:79]
	v_mfma_f32_16x16x32_bf16 v[72:75], v[158:161], v[210:213], v[72:75]
	v_mfma_f32_16x16x32_bf16 v[68:71], v[166:169], v[210:213], v[68:71]
	v_mfma_f32_16x16x32_bf16 v[116:119], v[162:165], v[186:189], v[116:119]
	v_mfma_f32_16x16x32_bf16 v[108:111], v[170:173], v[186:189], v[108:111]
	v_mfma_f32_16x16x32_bf16 v[100:103], v[162:165], v[198:201], v[100:103]
	v_mfma_f32_16x16x32_bf16 v[92:95], v[170:173], v[198:201], v[92:95]
	v_mfma_f32_16x16x32_bf16 v[84:87], v[162:165], v[206:209], v[84:87]
	v_mfma_f32_16x16x32_bf16 v[76:79], v[170:173], v[206:209], v[76:79]
	v_mfma_f32_16x16x32_bf16 v[72:75], v[162:165], v[218:221], v[72:75]
	v_mfma_f32_16x16x32_bf16 v[68:71], v[170:173], v[218:221], v[68:71]
	s_setprio 0
	s_barrier
	s_add_i32 s34, s34, s56
	v_lshl_add_u64 v[178:179], s[18:19], 0, v[18:19]
	s_mov_b32 m0, s34
	ds_read_b128 v[174:177], v145 offset:16384
	ds_read_b128 v[186:189], v145 offset:17408
	ds_read_b128 v[190:193], v145 offset:18432
	ds_read_b128 v[198:201], v145 offset:19456
	ds_read_b128 v[202:205], v145 offset:20480
	ds_read_b128 v[206:209], v145 offset:21504
	ds_read_b128 v[210:213], v145 offset:22528
	ds_read_b128 v[218:221], v145 offset:23552
	global_load_lds_dwordx4 v[178:179], off
	s_add_i32 m0, s34, 0x2000
	s_add_u32 s34, s18, 0x40000
	v_lshl_add_u64 v[182:183], s[18:19], 0, v[16:17]
	s_addc_u32 s35, s19, 0
	s_add_i32 s59, s59, s56
	global_load_lds_dwordx4 v[182:183], off
	s_mov_b32 m0, s59
	v_lshl_add_u64 v[222:223], s[22:23], 0, v[132:133]
	global_load_lds_dwordx4 v18, s[34:35]
	s_add_i32 m0, s59, 0x2000
	s_nop 0
	global_load_lds_dwordx4 v16, s[34:35]
	v_lshl_add_u64 v[214:215], s[22:23], 0, v[134:135]
	s_mov_b32 m0, s65
	s_nop 0
	global_load_lds_dwordx4 v[214:215], off
	s_mov_b32 m0, s0
	s_nop 0
	global_load_lds_dwordx4 v[222:223], off
	s_waitcnt vmcnt(8)
	s_waitcnt lgkmcnt(0)
	s_barrier
; #define PG8_STAGE(bufoff, gbase, voff) do { _Pragma("unroll") for (int _i = 0; _i < 2; ++_i) \
;         __builtin_amdgcn_global_load_lds((const unsigned*)((const char*)(gbase) + (voff)[_i]), (LAS unsigned*)(lds + (bufoff) + ldsw + _i * 8192), 16, 0, 0); } while (0)
; #define PG8_LDA(dst, b, h) do { _Pragma("unroll") for (int m = 0; m < 4; ++m) _Pragma("unroll") for (int k = 0; k < 2; ++k) dst[m][k] = *(const LAS bf16x8*)(lds + PG8_SA(b, h) + aoff + m * 2048 + k * 1024); } while (0)
; #define PG8_LDB(dst, b, h) do { _Pragma("unroll") for (int n = 0; n < 2; ++n) _Pragma("unroll") for (int k = 0; k < 2; ++k) dst[n][k] = *(const LAS bf16x8*)(lds + PG8_SB(b, h) + boff + n * 2048 + k * 1024); } while (0)
; #define PG8_MMA(ai, bj, At, Bt) do { __builtin_amdgcn_s_setprio(1); _Pragma("unroll") for (int m = 0; m < 4; ++m) _Pragma("unroll") for (int n = 0; n < 2; ++n) _Pragma("unroll") for (int k = 0; k < 2; ++k) \
;         acc[ai][bj][m][n] = __builtin_amdgcn_mfma_f32_16x16x32_bf16(Bt[n][k], At[m][k], acc[ai][bj][m][n], 0, 0, 0); __builtin_amdgcn_s_setprio(0); } while (0)
; #define PG8_WAIT_V(n) asm volatile("s_waitcnt vmcnt(" #n ")" ::: "memory")
; #define PG8_WAIT_L(n) asm volatile("s_waitcnt lgkmcnt(" #n ")" ::: "memory")
; #define PG8_BAR __builtin_amdgcn_s_barrier()
; #define PG8_SCHED __builtin_amdgcn_sched_barrier(0)
; template <class Epi, class Sched, bool ALIGN_EPI = true, bool SP2 = true>
; __device__ __forceinline__ void gemm_phase(LAS unsigned char* lds, const Gemm g, const Sched& S, const Epi& E) {
;     ...
;             PG8_WAIT_V(8); PG8_WAIT_L(0); PG8_BAR; PG8_MMA(1, 0, At, B0); PG8_MMA(1, 1, At, B1); PG8_BAR; PG8_SCHED;
;             PG8_LDB(B0, 1, 0); PG8_LDB(B1, 1, 1); PG8_SCHED; PG8_LDA(At, 1, 0); PG8_STAGE(PG8_SA(0, 1), a2 + hstepA, voffA);
;             PG8_WAIT_V(8); PG8_WAIT_L(0); PG8_BAR; PG8_MMA(0, 0, At, B0); PG8_MMA(0, 1, At, B1); PG8_BAR; PG8_SCHED;
	s_setprio 1
	s_waitcnt lgkmcnt(0)
	v_mfma_f32_16x16x32_bf16 v[64:67], v[140:143], v[174:177], v[64:67]
	v_mfma_f32_16x16x32_bf16 v[60:63], v[150:153], v[174:177], v[60:63]
	v_mfma_f32_16x16x32_bf16 v[56:59], v[140:143], v[190:193], v[56:59]
	v_mfma_f32_16x16x32_bf16 v[48:51], v[150:153], v[190:193], v[48:51]
	v_mfma_f32_16x16x32_bf16 v[40:43], v[140:143], v[202:205], v[40:43]
	v_mfma_f32_16x16x32_bf16 v[32:35], v[150:153], v[202:205], v[32:35]
	v_mfma_f32_16x16x32_bf16 v[24:27], v[140:143], v[210:213], v[24:27]
	v_mfma_f32_16x16x32_bf16 v[12:15], v[150:153], v[210:213], v[12:15]
	v_mfma_f32_16x16x32_bf16 v[64:67], v[146:149], v[186:189], v[64:67]
	v_mfma_f32_16x16x32_bf16 v[60:63], v[154:157], v[186:189], v[60:63]
	v_mfma_f32_16x16x32_bf16 v[56:59], v[146:149], v[198:201], v[56:59]
	v_mfma_f32_16x16x32_bf16 v[48:51], v[154:157], v[198:201], v[48:51]
	v_mfma_f32_16x16x32_bf16 v[40:43], v[146:149], v[206:209], v[40:43]
	v_mfma_f32_16x16x32_bf16 v[32:35], v[154:157], v[206:209], v[32:35]
	v_mfma_f32_16x16x32_bf16 v[24:27], v[146:149], v[218:221], v[24:27]
	v_mfma_f32_16x16x32_bf16 v[12:15], v[154:157], v[218:221], v[12:15]
	s_setprio 0
	s_setprio 1
	v_mfma_f32_16x16x32_bf16 v[52:55], v[158:161], v[174:177], v[52:55]
	v_mfma_f32_16x16x32_bf16 v[44:47], v[166:169], v[174:177], v[44:47]
	v_mfma_f32_16x16x32_bf16 v[36:39], v[158:161], v[190:193], v[36:39]
	v_mfma_f32_16x16x32_bf16 v[28:31], v[166:169], v[190:193], v[28:31]
	v_mfma_f32_16x16x32_bf16 v[20:23], v[158:161], v[202:205], v[20:23]
	v_mfma_f32_16x16x32_bf16 v[8:11], v[166:169], v[202:205], v[8:11]
	v_mfma_f32_16x16x32_bf16 v[4:7], v[158:161], v[210:213], v[4:7]
	v_mfma_f32_16x16x32_bf16 v[0:3], v[166:169], v[210:213], v[0:3]
	v_mfma_f32_16x16x32_bf16 v[52:55], v[162:165], v[186:189], v[52:55]
	v_mfma_f32_16x16x32_bf16 v[44:47], v[170:173], v[186:189], v[44:47]
	v_mfma_f32_16x16x32_bf16 v[36:39], v[162:165], v[198:201], v[36:39]
	v_mfma_f32_16x16x32_bf16 v[28:31], v[170:173], v[198:201], v[28:31]
	v_mfma_f32_16x16x32_bf16 v[20:23], v[162:165], v[206:209], v[20:23]
	v_mfma_f32_16x16x32_bf16 v[8:11], v[170:173], v[206:209], v[8:11]
	v_mfma_f32_16x16x32_bf16 v[4:7], v[162:165], v[218:221], v[4:7]
	v_mfma_f32_16x16x32_bf16 v[0:3], v[170:173], v[218:221], v[0:3]
	s_setprio 0
	s_barrier
	s_add_i32 s34, 0, 0x18000
	s_add_i32 s35, 0, 0x1c000
	v_add_u32_e32 v154, s34, v144
	v_add_u32_e32 v170, s35, v144
	ds_read_b128 v[140:143], v154
	ds_read_b128 v[146:149], v154 offset:1024
	ds_read_b128 v[150:153], v154 offset:2048
	ds_read_b128 v[154:157], v154 offset:3072
	ds_read_b128 v[158:161], v170
	ds_read_b128 v[162:165], v170 offset:1024
	ds_read_b128 v[166:169], v170 offset:2048
	ds_read_b128 v[170:173], v170 offset:3072
	s_add_u32 s22, s22, 0x40000
	s_addc_u32 s23, s23, 0
	s_mov_b32 m0, s1
	ds_read_b128 v[174:177], v145 offset:32768
	ds_read_b128 v[186:189], v145 offset:33792
	ds_read_b128 v[190:193], v145 offset:34816
	ds_read_b128 v[198:201], v145 offset:35840
	ds_read_b128 v[202:205], v145 offset:36864
	ds_read_b128 v[206:209], v145 offset:37888
	ds_read_b128 v[210:213], v145 offset:38912
	ds_read_b128 v[218:221], v145 offset:39936
	global_load_lds_dwordx4 v134, s[22:23]
	v_lshl_add_u64 v[224:225], s[22:23], 0, v[132:133]
	s_mov_b32 m0, s8
	s_nop 0
	global_load_lds_dwordx4 v[224:225], off
	s_waitcnt vmcnt(8)
	s_waitcnt lgkmcnt(0)
	s_barrier
	s_setprio 1
	s_waitcnt lgkmcnt(0)
	v_mfma_f32_16x16x32_bf16 v[128:131], v[140:143], v[174:177], v[128:131]
	v_mfma_f32_16x16x32_bf16 v[124:127], v[150:153], v[174:177], v[124:127]
	v_mfma_f32_16x16x32_bf16 v[120:123], v[140:143], v[190:193], v[120:123]
	v_mfma_f32_16x16x32_bf16 v[112:115], v[150:153], v[190:193], v[112:115]
	v_mfma_f32_16x16x32_bf16 v[104:107], v[140:143], v[202:205], v[104:107]
	v_mfma_f32_16x16x32_bf16 v[96:99], v[150:153], v[202:205], v[96:99]
	v_mfma_f32_16x16x32_bf16 v[88:91], v[140:143], v[210:213], v[88:91]
	v_mfma_f32_16x16x32_bf16 v[80:83], v[150:153], v[210:213], v[80:83]
	v_mfma_f32_16x16x32_bf16 v[128:131], v[146:149], v[186:189], v[128:131]
	v_mfma_f32_16x16x32_bf16 v[124:127], v[154:157], v[186:189], v[124:127]
	v_mfma_f32_16x16x32_bf16 v[120:123], v[146:149], v[198:201], v[120:123]
	v_mfma_f32_16x16x32_bf16 v[112:115], v[154:157], v[198:201], v[112:115]
	v_mfma_f32_16x16x32_bf16 v[104:107], v[146:149], v[206:209], v[104:107]
	v_mfma_f32_16x16x32_bf16 v[96:99], v[154:157], v[206:209], v[96:99]
	v_mfma_f32_16x16x32_bf16 v[88:91], v[146:149], v[218:221], v[88:91]
	v_mfma_f32_16x16x32_bf16 v[80:83], v[154:157], v[218:221], v[80:83]
	s_setprio 0
	s_setprio 1
	v_mfma_f32_16x16x32_bf16 v[116:119], v[158:161], v[174:177], v[116:119]
	v_mfma_f32_16x16x32_bf16 v[108:111], v[166:169], v[174:177], v[108:111]
	v_mfma_f32_16x16x32_bf16 v[100:103], v[158:161], v[190:193], v[100:103]
	v_mfma_f32_16x16x32_bf16 v[92:95], v[166:169], v[190:193], v[92:95]
	v_mfma_f32_16x16x32_bf16 v[84:87], v[158:161], v[202:205], v[84:87]
	v_mfma_f32_16x16x32_bf16 v[76:79], v[166:169], v[202:205], v[76:79]
	v_mfma_f32_16x16x32_bf16 v[72:75], v[158:161], v[210:213], v[72:75]
	v_mfma_f32_16x16x32_bf16 v[68:71], v[166:169], v[210:213], v[68:71]
	v_mfma_f32_16x16x32_bf16 v[116:119], v[162:165], v[186:189], v[116:119]
	v_mfma_f32_16x16x32_bf16 v[108:111], v[170:173], v[186:189], v[108:111]
	v_mfma_f32_16x16x32_bf16 v[100:103], v[162:165], v[198:201], v[100:103]
	v_mfma_f32_16x16x32_bf16 v[92:95], v[170:173], v[198:201], v[92:95]
	v_mfma_f32_16x16x32_bf16 v[84:87], v[162:165], v[206:209], v[84:87]
	v_mfma_f32_16x16x32_bf16 v[76:79], v[170:173], v[206:209], v[76:79]
	v_mfma_f32_16x16x32_bf16 v[72:75], v[162:165], v[218:221], v[72:75]
	v_mfma_f32_16x16x32_bf16 v[68:71], v[170:173], v[218:221], v[68:71]
	s_setprio 0
	s_barrier
; #define PG8_STAGE(bufoff, gbase, voff) do { _Pragma("unroll") for (int _i = 0; _i < 2; ++_i) \
;         __builtin_amdgcn_global_load_lds((const unsigned*)((const char*)(gbase) + (voff)[_i]), (LAS unsigned*)(lds + (bufoff) + ldsw + _i * 8192), 16, 0, 0); } while (0)
; #define PG8_LDA(dst, b, h) do { _Pragma("unroll") for (int m = 0; m < 4; ++m) _Pragma("unroll") for (int k = 0; k < 2; ++k) dst[m][k] = *(const LAS bf16x8*)(lds + PG8_SA(b, h) + aoff + m * 2048 + k * 1024); } while (0)
; #define PG8_MMA(ai, bj, At, Bt) do { __builtin_amdgcn_s_setprio(1); _Pragma("unroll") for (int m = 0; m < 4; ++m) _Pragma("unroll") for (int n = 0; n < 2; ++n) _Pragma("unroll") for (int k = 0; k < 2; ++k) \
;         acc[ai][bj][m][n] = __builtin_amdgcn_mfma_f32_16x16x32_bf16(Bt[n][k], At[m][k], acc[ai][bj][m][n], 0, 0, 0); __builtin_amdgcn_s_setprio(0); } while (0)
; #define PG8_WAIT_V(n) asm volatile("s_waitcnt vmcnt(" #n ")" ::: "memory")
; #define PG8_WAIT_L(n) asm volatile("s_waitcnt lgkmcnt(" #n ")" ::: "memory")
; #define PG8_BAR __builtin_amdgcn_s_barrier()
; #define PG8_SCHED __builtin_amdgcn_sched_barrier(0)
; template <class Epi, class Sched, bool ALIGN_EPI = true, bool SP2 = true>
; __device__ __forceinline__ void gemm_phase(LAS unsigned char* lds, const Gemm g, const Sched& S, const Epi& E) {
;     ...
;             PG8_LDA(At, 1, 1); PG8_STAGE(PG8_SB(1, 0), b3, voffB); PG8_STAGE(PG8_SB(1, 1), b3 + hstepB, voffB); PG8_STAGE(PG8_SA(1, 0), a3, voffA);
;             PG8_WAIT_V(8); PG8_WAIT_L(0); PG8_BAR; PG8_MMA(1, 0, At, B0); PG8_MMA(1, 1, At, B1); PG8_BAR; PG8_SCHED;
;         }
	s_add_i32 s22, s34, s56
	v_lshl_add_u64 v[178:179], v[178:179], 0, s[14:15]
	s_mov_b32 m0, s22
	ds_read_b128 v[174:177], v145 offset:49152
	ds_read_b128 v[186:189], v145 offset:50176
	ds_read_b128 v[190:193], v145 offset:51200
	ds_read_b128 v[198:201], v145 offset:52224
	ds_read_b128 v[202:205], v145 offset:53248
	ds_read_b128 v[206:209], v145 offset:54272
	ds_read_b128 v[210:213], v145 offset:55296
	ds_read_b128 v[218:221], v145 offset:56320
	global_load_lds_dwordx4 v[178:179], off
	s_add_i32 m0, s22, 0x2000
	s_add_u32 s18, s18, 0x40080
	v_lshl_add_u64 v[178:179], v[182:183], 0, s[14:15]
	s_addc_u32 s19, s19, 0
	s_add_i32 s22, s35, s56
	global_load_lds_dwordx4 v[178:179], off
	s_mov_b32 m0, s22
	s_nop 0
	global_load_lds_dwordx4 v18, s[18:19]
	v_lshl_add_u64 v[178:179], s[18:19], 0, v[16:17]
	s_add_i32 m0, s22, 0x2000
	s_nop 0
	global_load_lds_dwordx4 v[178:179], off
	v_lshl_add_u64 v[178:179], v[214:215], 0, s[14:15]
	s_mov_b32 m0, s49
	s_nop 0
	global_load_lds_dwordx4 v[178:179], off
	v_lshl_add_u64 v[178:179], v[222:223], 0, s[14:15]
	s_mov_b32 m0, s66
	s_nop 0
	global_load_lds_dwordx4 v[178:179], off
	s_waitcnt vmcnt(8)
	s_waitcnt lgkmcnt(0)
	s_barrier
	s_setprio 1
	s_waitcnt lgkmcnt(0)
	v_mfma_f32_16x16x32_bf16 v[64:67], v[140:143], v[174:177], v[64:67]
	v_mfma_f32_16x16x32_bf16 v[60:63], v[150:153], v[174:177], v[60:63]
	v_mfma_f32_16x16x32_bf16 v[56:59], v[140:143], v[190:193], v[56:59]
	v_mfma_f32_16x16x32_bf16 v[48:51], v[150:153], v[190:193], v[48:51]
	v_mfma_f32_16x16x32_bf16 v[40:43], v[140:143], v[202:205], v[40:43]
	v_mfma_f32_16x16x32_bf16 v[32:35], v[150:153], v[202:205], v[32:35]
	v_mfma_f32_16x16x32_bf16 v[24:27], v[140:143], v[210:213], v[24:27]
	v_mfma_f32_16x16x32_bf16 v[12:15], v[150:153], v[210:213], v[12:15]
	v_mfma_f32_16x16x32_bf16 v[64:67], v[146:149], v[186:189], v[64:67]
	v_mfma_f32_16x16x32_bf16 v[60:63], v[154:157], v[186:189], v[60:63]
	v_mfma_f32_16x16x32_bf16 v[56:59], v[146:149], v[198:201], v[56:59]
	v_mfma_f32_16x16x32_bf16 v[48:51], v[154:157], v[198:201], v[48:51]
	v_mfma_f32_16x16x32_bf16 v[40:43], v[146:149], v[206:209], v[40:43]
	v_mfma_f32_16x16x32_bf16 v[32:35], v[154:157], v[206:209], v[32:35]
	v_mfma_f32_16x16x32_bf16 v[24:27], v[146:149], v[218:221], v[24:27]
	v_mfma_f32_16x16x32_bf16 v[12:15], v[154:157], v[218:221], v[12:15]
	s_setprio 0
	s_setprio 1
	v_mfma_f32_16x16x32_bf16 v[52:55], v[158:161], v[174:177], v[52:55]
	v_mfma_f32_16x16x32_bf16 v[44:47], v[166:169], v[174:177], v[44:47]
	v_mfma_f32_16x16x32_bf16 v[36:39], v[158:161], v[190:193], v[36:39]
	v_mfma_f32_16x16x32_bf16 v[28:31], v[166:169], v[190:193], v[28:31]
	v_mfma_f32_16x16x32_bf16 v[20:23], v[158:161], v[202:205], v[20:23]
	v_mfma_f32_16x16x32_bf16 v[8:11], v[166:169], v[202:205], v[8:11]
	v_mfma_f32_16x16x32_bf16 v[4:7], v[158:161], v[210:213], v[4:7]
	v_mfma_f32_16x16x32_bf16 v[0:3], v[166:169], v[210:213], v[0:3]
	v_mfma_f32_16x16x32_bf16 v[52:55], v[162:165], v[186:189], v[52:55]
	v_mfma_f32_16x16x32_bf16 v[44:47], v[170:173], v[186:189], v[44:47]
	v_mfma_f32_16x16x32_bf16 v[36:39], v[162:165], v[198:201], v[36:39]
	v_mfma_f32_16x16x32_bf16 v[28:31], v[170:173], v[198:201], v[28:31]
	v_mfma_f32_16x16x32_bf16 v[20:23], v[162:165], v[206:209], v[20:23]
	v_mfma_f32_16x16x32_bf16 v[8:11], v[170:173], v[206:209], v[8:11]
	v_mfma_f32_16x16x32_bf16 v[4:7], v[162:165], v[218:221], v[4:7]
	v_mfma_f32_16x16x32_bf16 v[0:3], v[170:173], v[218:221], v[0:3]
	s_setprio 0
	s_barrier
	s_add_i32 s58, s58, 2
	s_add_u32 vcc_lo, vcc_lo, 0x100
	s_addc_u32 vcc_hi, vcc_hi, 0
	s_add_u32 s54, s54, 0x100
	s_addc_u32 s55, s55, 0
	s_cmp_gt_u32 s58, 13
	s_cbranch_scc0 .LBB0_1063
	s_and_b64 vcc, exec, s[44:45]
	s_cbranch_vccz .LBB0_1066
	s_barrier

; #define PG8_STAGE(bufoff, gbase, voff) do { _Pragma("unroll") for (int _i = 0; _i < 2; ++_i) \
;         __builtin_amdgcn_global_load_lds((const unsigned*)((const char*)(gbase) + (voff)[_i]), (LAS unsigned*)(lds + (bufoff) + ldsw + _i * 8192), 16, 0, 0); } while (0)
; #define PG8_WAIT_V(n) asm volatile("s_waitcnt vmcnt(" #n ")" ::: "memory")
; #define PG8_BAR __builtin_amdgcn_s_barrier()
; template <class Epi, class Sched, bool ALIGN_EPI = true, bool SP2 = true>
; __device__ __forceinline__ void gemm_phase(LAS unsigned char* lds, const Gemm g, const Sched& S, const Epi& E) {
;     ...
;     const char* cA = (const char*)g.A + (size_t)cur.pm * tstepA; const char* cB = (const char*)g.Bt + (size_t)cur.pn * tstepB;
;     if constexpr (SP2) {
;         PG8_STAGE(PG8_SB(0, 0), cB, voffB); PG8_STAGE(PG8_SB(0, 1), cB + hstepB, voffB); PG8_STAGE(PG8_SA(0, 0), cA, voffA); PG8_STAGE(PG8_SA(0, 1), cA + hstepA, voffA);
;         if (wr == 1) PG8_BAR;
;         PG8_WAIT_V(2); PG8_BAR;
;         PG8_STAGE(PG8_SB(1, 0), cB + kstep, voffB); PG8_STAGE(PG8_SA(1, 0), cA + kstep, voffA); PG8_STAGE(PG8_SB(1, 1), cB + hstepB + kstep, voffB);
;         PG8_WAIT_V(6); PG8_BAR;
.LBB0_1219:
	s_add_u32 s34, s20, 0x29600000
	s_addc_u32 s35, s21, 0
	v_and_b32_e32 v21, 48, v20
	v_lshlrev_b32_e32 v22, 6, v20
	s_movk_i32 s9, 0x3c0
	v_lshlrev_b32_e32 v20, 2, v20
	s_lshl_b32 s1, s1, 5
	s_sext_i32_i8 s55, s0
	s_lshl_b32 s0, s8, 6
	s_lshl_b32 s8, s8, 13
	v_and_or_b32 v21, v22, s9, v21
	v_and_b32_e32 v20, 32, v20
	s_and_b32 s1, s1, 0x60
	v_bitop3_b32 v22, v21, s8, v20 bitop3:0xde
	s_lshl_b32 s8, s1, 7
	s_add_i32 m0, s46, 0x18000
	v_lshl_add_u64 v[6:7], v[6:7], 0, s[14:15]
	v_bitop3_b32 v142, s8, v21, v20 bitop3:0xf6
	s_waitcnt vmcnt(2)
	s_barrier
	global_load_lds_dwordx4 v[6:7], off
	v_lshl_add_u64 v[4:5], v[4:5], 0, s[14:15]
	s_add_i32 m0, s46, 0x1a000
	s_add_i32 s8, s46, 0x8000
	s_add_i32 s9, s46, 0xa000
	global_load_lds_dwordx4 v[4:5], off
	v_lshl_add_u64 v[0:1], v[0:1], 0, s[14:15]
	s_mov_b32 m0, s8
	s_add_u32 s20, s18, 0xb0080
	global_load_lds_dwordx4 v[0:1], off
	v_lshl_add_u64 v[0:1], v[2:3], 0, s[14:15]
	s_mov_b32 m0, s9
	s_addc_u32 s21, s19, 0
	global_load_lds_dwordx4 v[0:1], off
	s_add_i32 m0, s46, 0x1c000
	s_nop 0
	global_load_lds_dwordx4 v18, s[20:21]
	v_lshl_add_u64 v[0:1], s[20:21], 0, v[16:17]
	s_add_i32 m0, s46, 0x1e000
	s_cmpk_lt_u32 s2, 0x100
	global_load_lds_dwordx4 v[0:1], off
	s_movk_i32 s2, 0xb00
	v_lshrrev_b32_e32 v1, 1, v13
	v_mul_lo_u32 v0, v12, s2
	s_mov_b32 s22, 0xb000
	v_mad_u64_u32 v[0:1], s[20:21], v1, s22, v[0:1]
	v_or_b32_e32 v0, v0, v14
	v_add_lshl_u32 v0, v0, v15, 1
	v_mov_b32_e32 v1, v19
	s_mov_b64 s[40:41], 0xb0080
	v_lshl_add_u64 v[136:137], v[0:1], 0, s[40:41]
	v_lshrrev_b32_e32 v1, 1, v8
	v_mul_lo_u32 v0, v9, s2
	v_mad_u64_u32 v[0:1], s[20:21], v1, s22, v[0:1]
	s_waitcnt vmcnt(6)
	v_or_b32_e32 v0, v0, v10
	v_add_lshl_u32 v0, v0, v11, 1
	v_mov_b32_e32 v1, v19
	s_cselect_b64 s[36:37], -1, 0
	s_ashr_i32 s48, s24, 31
	v_lshl_add_u64 v[138:139], v[0:1], 0, s[40:41]
	s_mov_b32 s49, 0
	v_add_u32_e32 v143, 0, v22
	s_barrier
	s_waitcnt vmcnt(0)
	s_branch .LBB0_1222

; #define PG8_STAGE(bufoff, gbase, voff) do { _Pragma("unroll") for (int _i = 0; _i < 2; ++_i) \
;         __builtin_amdgcn_global_load_lds((const unsigned*)((const char*)(gbase) + (voff)[_i]), (LAS unsigned*)(lds + (bufoff) + ldsw + _i * 8192), 16, 0, 0); } while (0)
; #define PG8_LDA(dst, b, h) do { _Pragma("unroll") for (int m = 0; m < 4; ++m) _Pragma("unroll") for (int k = 0; k < 2; ++k) dst[m][k] = *(const LAS bf16x8*)(lds + PG8_SA(b, h) + aoff + m * 2048 + k * 1024); } while (0)
; #define PG8_LDB(dst, b, h) do { _Pragma("unroll") for (int n = 0; n < 2; ++n) _Pragma("unroll") for (int k = 0; k < 2; ++k) dst[n][k] = *(const LAS bf16x8*)(lds + PG8_SB(b, h) + boff + n * 2048 + k * 1024); } while (0)
; #define PG8_MMA(ai, bj, At, Bt) do { __builtin_amdgcn_s_setprio(1); _Pragma("unroll") for (int m = 0; m < 4; ++m) _Pragma("unroll") for (int n = 0; n < 2; ++n) _Pragma("unroll") for (int k = 0; k < 2; ++k) \
;         acc[ai][bj][m][n] = __builtin_amdgcn_mfma_f32_16x16x32_bf16(Bt[n][k], At[m][k], acc[ai][bj][m][n], 0, 0, 0); __builtin_amdgcn_s_setprio(0); } while (0)
; #define PG8_WAIT_V(n) asm volatile("s_waitcnt vmcnt(" #n ")" ::: "memory")
; #define PG8_WAIT_L(n) asm volatile("s_waitcnt lgkmcnt(" #n ")" ::: "memory")
; #define PG8_BAR __builtin_amdgcn_s_barrier()
; template <class Epi, class Sched, bool ALIGN_EPI = true, bool SP2 = true>
; __device__ __forceinline__ void gemm_phase(LAS unsigned char* lds, const Gemm g, const Sched& S, const Epi& E) {
;     ...
;         for (int t = 0; t < nt; t += 2) {
;             const bool last = (t == nt - 2);
;             const char* a1 = cA + (size_t)(t + 1) * kstep;
;             const char* a2 = last ? nA : cA + (size_t)(t + 2) * kstep; const char* b2 = last ? nB : cB + (size_t)(t + 2) * kstep;
;             const char* a3 = a2 + kstep; const char* b3 = b2 + kstep;
;             PG8_LDB(B0, 0, 0); PG8_LDB(B1, 0, 1); PG8_SCHED; PG8_LDA(At, 0, 0); PG8_STAGE(PG8_SA(1, 1), a1 + hstepA, voffA);
;             PG8_WAIT_V(8); PG8_WAIT_L(0); PG8_BAR; PG8_MMA(0, 0, At, B0); PG8_MMA(0, 1, At, B1); PG8_BAR; PG8_SCHED;
;             PG8_LDA(At, 0, 1); PG8_STAGE(PG8_SB(0, 0), b2, voffB); PG8_STAGE(PG8_SB(0, 1), b2 + hstepB, voffB); PG8_STAGE(PG8_SA(0, 0), a2, voffA);
;             PG8_WAIT_V(8); PG8_WAIT_L(0); PG8_BAR; PG8_MMA(1, 0, At, B0); PG8_MMA(1, 1, At, B1); PG8_BAR; PG8_SCHED;
.LBB0_1229:
	s_add_u32 s18, s16, 0x100
	s_addc_u32 s19, s17, 0
	s_add_i32 s57, 0, 0x10000
	s_cmp_eq_u32 s56, 40
	s_cselect_b32 s23, s43, s19
	s_cselect_b32 s22, s42, s18
	v_add_u32_e32 v140, s57, v142
	s_cselect_b32 s21, s45, s30
	s_cselect_b32 s20, s44, s2
	s_add_i32 s58, 0, 0x14000
	ds_read_b128 v[144:147], v140
	ds_read_b128 v[148:151], v140 offset:1024
	ds_read_b128 v[152:155], v140 offset:2048
	ds_read_b128 v[156:159], v140 offset:3072
	v_add_u32_e32 v140, s58, v142
	ds_read_b128 v[160:163], v140
	ds_read_b128 v[164:167], v140 offset:1024
	ds_read_b128 v[168:171], v140 offset:2048
	ds_read_b128 v[172:175], v140 offset:3072
	s_add_i32 m0, s46, 0xc000
	ds_read_b128 v[186:189], v143
	ds_read_b128 v[190:193], v143 offset:1024
	ds_read_b128 v[198:201], v143 offset:2048
	ds_read_b128 v[202:205], v143 offset:3072
	ds_read_b128 v[206:209], v143 offset:4096
	ds_read_b128 v[210:213], v143 offset:5120
	ds_read_b128 v[218:221], v143 offset:6144
	ds_read_b128 v[222:225], v143 offset:7168
	global_load_lds_dwordx4 v136, s[16:17]
	s_add_i32 m0, s46, 0xe000
	s_nop 0
	global_load_lds_dwordx4 v138, s[16:17]
	s_waitcnt vmcnt(8)
	s_waitcnt lgkmcnt(0)
	s_barrier
	s_setprio 1
	s_waitcnt lgkmcnt(0)
	v_mfma_f32_16x16x32_bf16 v[128:131], v[144:147], v[186:189], v[128:131]
	v_mfma_f32_16x16x32_bf16 v[124:127], v[152:155], v[186:189], v[124:127]
	v_mfma_f32_16x16x32_bf16 v[120:123], v[144:147], v[198:201], v[120:123]
	v_mfma_f32_16x16x32_bf16 v[112:115], v[152:155], v[198:201], v[112:115]
	v_mfma_f32_16x16x32_bf16 v[104:107], v[144:147], v[206:209], v[104:107]
	v_mfma_f32_16x16x32_bf16 v[96:99], v[152:155], v[206:209], v[96:99]
	v_mfma_f32_16x16x32_bf16 v[88:91], v[144:147], v[218:221], v[88:91]
	v_mfma_f32_16x16x32_bf16 v[80:83], v[152:155], v[218:221], v[80:83]
	v_mfma_f32_16x16x32_bf16 v[128:131], v[148:151], v[190:193], v[128:131]
	v_mfma_f32_16x16x32_bf16 v[124:127], v[156:159], v[190:193], v[124:127]
	v_mfma_f32_16x16x32_bf16 v[120:123], v[148:151], v[202:205], v[120:123]
	v_mfma_f32_16x16x32_bf16 v[112:115], v[156:159], v[202:205], v[112:115]
	v_mfma_f32_16x16x32_bf16 v[104:107], v[148:151], v[210:213], v[104:107]
	v_mfma_f32_16x16x32_bf16 v[96:99], v[156:159], v[210:213], v[96:99]
	v_mfma_f32_16x16x32_bf16 v[88:91], v[148:151], v[222:225], v[88:91]
	v_mfma_f32_16x16x32_bf16 v[80:83], v[156:159], v[222:225], v[80:83]
	s_setprio 0
	s_setprio 1
	v_mfma_f32_16x16x32_bf16 v[116:119], v[160:163], v[186:189], v[116:119]
	v_mfma_f32_16x16x32_bf16 v[108:111], v[168:171], v[186:189], v[108:111]
	v_mfma_f32_16x16x32_bf16 v[100:103], v[160:163], v[198:201], v[100:103]
	v_mfma_f32_16x16x32_bf16 v[92:95], v[168:171], v[198:201], v[92:95]
	v_mfma_f32_16x16x32_bf16 v[84:87], v[160:163], v[206:209], v[84:87]
	v_mfma_f32_16x16x32_bf16 v[76:79], v[168:171], v[206:209], v[76:79]
	v_mfma_f32_16x16x32_bf16 v[72:75], v[160:163], v[218:221], v[72:75]
	v_mfma_f32_16x16x32_bf16 v[68:71], v[168:171], v[218:221], v[68:71]
	v_mfma_f32_16x16x32_bf16 v[116:119], v[164:167], v[190:193], v[116:119]
	v_mfma_f32_16x16x32_bf16 v[108:111], v[172:175], v[190:193], v[108:111]
	v_mfma_f32_16x16x32_bf16 v[100:103], v[164:167], v[202:205], v[100:103]
	v_mfma_f32_16x16x32_bf16 v[92:95], v[172:175], v[202:205], v[92:95]
	v_mfma_f32_16x16x32_bf16 v[84:87], v[164:167], v[210:213], v[84:87]
	v_mfma_f32_16x16x32_bf16 v[76:79], v[172:175], v[210:213], v[76:79]
	v_mfma_f32_16x16x32_bf16 v[72:75], v[164:167], v[222:225], v[72:75]
	v_mfma_f32_16x16x32_bf16 v[68:71], v[172:175], v[222:225], v[68:71]
	s_setprio 0
	s_barrier
	s_add_i32 s16, s57, s38
	v_lshl_add_u64 v[140:141], s[20:21], 0, v[18:19]
	s_mov_b32 m0, s16
	ds_read_b128 v[186:189], v143 offset:16384
	ds_read_b128 v[190:193], v143 offset:17408
	ds_read_b128 v[198:201], v143 offset:18432
	ds_read_b128 v[202:205], v143 offset:19456
	ds_read_b128 v[206:209], v143 offset:20480
	ds_read_b128 v[210:213], v143 offset:21504
	ds_read_b128 v[218:221], v143 offset:22528
	ds_read_b128 v[222:225], v143 offset:23552
	global_load_lds_dwordx4 v[140:141], off
	s_add_i32 m0, s16, 0x2000
	s_add_u32 s16, s20, 0xb0000
	v_lshl_add_u64 v[176:177], s[20:21], 0, v[16:17]
	s_addc_u32 s17, s21, 0
	s_add_i32 s57, s58, s38
	global_load_lds_dwordx4 v[176:177], off
	s_mov_b32 m0, s57
	v_lshl_add_u64 v[182:183], s[22:23], 0, v[132:133]
	global_load_lds_dwordx4 v18, s[16:17]
	s_add_i32 m0, s57, 0x2000
	s_nop 0
	global_load_lds_dwordx4 v16, s[16:17]
	v_lshl_add_u64 v[178:179], s[22:23], 0, v[134:135]
	s_mov_b32 m0, s46
	s_nop 0
	global_load_lds_dwordx4 v[178:179], off
	s_mov_b32 m0, s47
	s_nop 0
	global_load_lds_dwordx4 v[182:183], off
	s_waitcnt vmcnt(8)
	s_waitcnt lgkmcnt(0)
	s_barrier
; #define PG8_STAGE(bufoff, gbase, voff) do { _Pragma("unroll") for (int _i = 0; _i < 2; ++_i) \
;         __builtin_amdgcn_global_load_lds((const unsigned*)((const char*)(gbase) + (voff)[_i]), (LAS unsigned*)(lds + (bufoff) + ldsw + _i * 8192), 16, 0, 0); } while (0)
; #define PG8_LDA(dst, b, h) do { _Pragma("unroll") for (int m = 0; m < 4; ++m) _Pragma("unroll") for (int k = 0; k < 2; ++k) dst[m][k] = *(const LAS bf16x8*)(lds + PG8_SA(b, h) + aoff + m * 2048 + k * 1024); } while (0)
; #define PG8_LDB(dst, b, h) do { _Pragma("unroll") for (int n = 0; n < 2; ++n) _Pragma("unroll") for (int k = 0; k < 2; ++k) dst[n][k] = *(const LAS bf16x8*)(lds + PG8_SB(b, h) + boff + n * 2048 + k * 1024); } while (0)
; #define PG8_MMA(ai, bj, At, Bt) do { __builtin_amdgcn_s_setprio(1); _Pragma("unroll") for (int m = 0; m < 4; ++m) _Pragma("unroll") for (int n = 0; n < 2; ++n) _Pragma("unroll") for (int k = 0; k < 2; ++k) \
;         acc[ai][bj][m][n] = __builtin_amdgcn_mfma_f32_16x16x32_bf16(Bt[n][k], At[m][k], acc[ai][bj][m][n], 0, 0, 0); __builtin_amdgcn_s_setprio(0); } while (0)
; #define PG8_WAIT_V(n) asm volatile("s_waitcnt vmcnt(" #n ")" ::: "memory")
; #define PG8_WAIT_L(n) asm volatile("s_waitcnt lgkmcnt(" #n ")" ::: "memory")
; #define PG8_BAR __builtin_amdgcn_s_barrier()
; #define PG8_SCHED __builtin_amdgcn_sched_barrier(0)
; template <class Epi, class Sched, bool ALIGN_EPI = true, bool SP2 = true>
; __device__ __forceinline__ void gemm_phase(LAS unsigned char* lds, const Gemm g, const Sched& S, const Epi& E) {
;     ...
;             PG8_WAIT_V(8); PG8_WAIT_L(0); PG8_BAR; PG8_MMA(1, 0, At, B0); PG8_MMA(1, 1, At, B1); PG8_BAR; PG8_SCHED;
;             PG8_LDB(B0, 1, 0); PG8_LDB(B1, 1, 1); PG8_SCHED; PG8_LDA(At, 1, 0); PG8_STAGE(PG8_SA(0, 1), a2 + hstepA, voffA);
;             PG8_WAIT_V(8); PG8_WAIT_L(0); PG8_BAR; PG8_MMA(0, 0, At, B0); PG8_MMA(0, 1, At, B1); PG8_BAR; PG8_SCHED;
	s_setprio 1
	s_waitcnt lgkmcnt(0)
	v_mfma_f32_16x16x32_bf16 v[64:67], v[144:147], v[186:189], v[64:67]
	v_mfma_f32_16x16x32_bf16 v[60:63], v[152:155], v[186:189], v[60:63]
	v_mfma_f32_16x16x32_bf16 v[56:59], v[144:147], v[198:201], v[56:59]
	v_mfma_f32_16x16x32_bf16 v[48:51], v[152:155], v[198:201], v[48:51]
	v_mfma_f32_16x16x32_bf16 v[40:43], v[144:147], v[206:209], v[40:43]
	v_mfma_f32_16x16x32_bf16 v[32:35], v[152:155], v[206:209], v[32:35]
	v_mfma_f32_16x16x32_bf16 v[24:27], v[144:147], v[218:221], v[24:27]
	v_mfma_f32_16x16x32_bf16 v[12:15], v[152:155], v[218:221], v[12:15]
	v_mfma_f32_16x16x32_bf16 v[64:67], v[148:151], v[190:193], v[64:67]
	v_mfma_f32_16x16x32_bf16 v[60:63], v[156:159], v[190:193], v[60:63]
	v_mfma_f32_16x16x32_bf16 v[56:59], v[148:151], v[202:205], v[56:59]
	v_mfma_f32_16x16x32_bf16 v[48:51], v[156:159], v[202:205], v[48:51]
	v_mfma_f32_16x16x32_bf16 v[40:43], v[148:151], v[210:213], v[40:43]
	v_mfma_f32_16x16x32_bf16 v[32:35], v[156:159], v[210:213], v[32:35]
	v_mfma_f32_16x16x32_bf16 v[24:27], v[148:151], v[222:225], v[24:27]
	v_mfma_f32_16x16x32_bf16 v[12:15], v[156:159], v[222:225], v[12:15]
	s_setprio 0
	s_setprio 1
	v_mfma_f32_16x16x32_bf16 v[52:55], v[160:163], v[186:189], v[52:55]
	v_mfma_f32_16x16x32_bf16 v[44:47], v[168:171], v[186:189], v[44:47]
	v_mfma_f32_16x16x32_bf16 v[36:39], v[160:163], v[198:201], v[36:39]
	v_mfma_f32_16x16x32_bf16 v[28:31], v[168:171], v[198:201], v[28:31]
	v_mfma_f32_16x16x32_bf16 v[20:23], v[160:163], v[206:209], v[20:23]
	v_mfma_f32_16x16x32_bf16 v[8:11], v[168:171], v[206:209], v[8:11]
	v_mfma_f32_16x16x32_bf16 v[4:7], v[160:163], v[218:221], v[4:7]
	v_mfma_f32_16x16x32_bf16 v[0:3], v[168:171], v[218:221], v[0:3]
	v_mfma_f32_16x16x32_bf16 v[52:55], v[164:167], v[190:193], v[52:55]
	v_mfma_f32_16x16x32_bf16 v[44:47], v[172:175], v[190:193], v[44:47]
	v_mfma_f32_16x16x32_bf16 v[36:39], v[164:167], v[202:205], v[36:39]
	v_mfma_f32_16x16x32_bf16 v[28:31], v[172:175], v[202:205], v[28:31]
	v_mfma_f32_16x16x32_bf16 v[20:23], v[164:167], v[210:213], v[20:23]
	v_mfma_f32_16x16x32_bf16 v[8:11], v[172:175], v[210:213], v[8:11]
	v_mfma_f32_16x16x32_bf16 v[4:7], v[164:167], v[222:225], v[4:7]
	v_mfma_f32_16x16x32_bf16 v[0:3], v[172:175], v[222:225], v[0:3]
	s_setprio 0
	s_barrier
	s_add_i32 s57, 0, 0x18000
	s_add_i32 s58, 0, 0x1c000
	v_add_u32_e32 v156, s57, v142
	v_add_u32_e32 v172, s58, v142
	ds_read_b128 v[144:147], v156
	ds_read_b128 v[148:151], v156 offset:1024
	ds_read_b128 v[152:155], v156 offset:2048
	ds_read_b128 v[156:159], v156 offset:3072
	ds_read_b128 v[160:163], v172
	ds_read_b128 v[164:167], v172 offset:1024
	ds_read_b128 v[168:171], v172 offset:2048
	ds_read_b128 v[172:175], v172 offset:3072
	s_add_u32 s16, s22, 0xb0000
	s_addc_u32 s17, s23, 0
	s_mov_b32 m0, s50
	ds_read_b128 v[186:189], v143 offset:32768
	ds_read_b128 v[190:193], v143 offset:33792
	ds_read_b128 v[198:201], v143 offset:34816
	ds_read_b128 v[202:205], v143 offset:35840
	ds_read_b128 v[206:209], v143 offset:36864
	ds_read_b128 v[210:213], v143 offset:37888
	ds_read_b128 v[218:221], v143 offset:38912
	ds_read_b128 v[222:225], v143 offset:39936
	global_load_lds_dwordx4 v134, s[16:17]
	v_lshl_add_u64 v[214:215], s[16:17], 0, v[132:133]
	s_mov_b32 m0, s51
	s_nop 0
	global_load_lds_dwordx4 v[214:215], off
	s_waitcnt vmcnt(8)
	s_waitcnt lgkmcnt(0)
	s_barrier
	s_setprio 1
	s_waitcnt lgkmcnt(0)
	v_mfma_f32_16x16x32_bf16 v[128:131], v[144:147], v[186:189], v[128:131]
	v_mfma_f32_16x16x32_bf16 v[124:127], v[152:155], v[186:189], v[124:127]
	v_mfma_f32_16x16x32_bf16 v[120:123], v[144:147], v[198:201], v[120:123]
	v_mfma_f32_16x16x32_bf16 v[112:115], v[152:155], v[198:201], v[112:115]
	v_mfma_f32_16x16x32_bf16 v[104:107], v[144:147], v[206:209], v[104:107]
	v_mfma_f32_16x16x32_bf16 v[96:99], v[152:155], v[206:209], v[96:99]
	v_mfma_f32_16x16x32_bf16 v[88:91], v[144:147], v[218:221], v[88:91]
	v_mfma_f32_16x16x32_bf16 v[80:83], v[152:155], v[218:221], v[80:83]
	v_mfma_f32_16x16x32_bf16 v[128:131], v[148:151], v[190:193], v[128:131]
	v_mfma_f32_16x16x32_bf16 v[124:127], v[156:159], v[190:193], v[124:127]
	v_mfma_f32_16x16x32_bf16 v[120:123], v[148:151], v[202:205], v[120:123]
	v_mfma_f32_16x16x32_bf16 v[112:115], v[156:159], v[202:205], v[112:115]
	v_mfma_f32_16x16x32_bf16 v[104:107], v[148:151], v[210:213], v[104:107]
	v_mfma_f32_16x16x32_bf16 v[96:99], v[156:159], v[210:213], v[96:99]
	v_mfma_f32_16x16x32_bf16 v[88:91], v[148:151], v[222:225], v[88:91]
	v_mfma_f32_16x16x32_bf16 v[80:83], v[156:159], v[222:225], v[80:83]
	s_setprio 0
	s_setprio 1
	v_mfma_f32_16x16x32_bf16 v[116:119], v[160:163], v[186:189], v[116:119]
	v_mfma_f32_16x16x32_bf16 v[108:111], v[168:171], v[186:189], v[108:111]
	v_mfma_f32_16x16x32_bf16 v[100:103], v[160:163], v[198:201], v[100:103]
	v_mfma_f32_16x16x32_bf16 v[92:95], v[168:171], v[198:201], v[92:95]
	v_mfma_f32_16x16x32_bf16 v[84:87], v[160:163], v[206:209], v[84:87]
	v_mfma_f32_16x16x32_bf16 v[76:79], v[168:171], v[206:209], v[76:79]
	v_mfma_f32_16x16x32_bf16 v[72:75], v[160:163], v[218:221], v[72:75]
	v_mfma_f32_16x16x32_bf16 v[68:71], v[168:171], v[218:221], v[68:71]
	v_mfma_f32_16x16x32_bf16 v[116:119], v[164:167], v[190:193], v[116:119]
	v_mfma_f32_16x16x32_bf16 v[108:111], v[172:175], v[190:193], v[108:111]
	v_mfma_f32_16x16x32_bf16 v[100:103], v[164:167], v[202:205], v[100:103]
	v_mfma_f32_16x16x32_bf16 v[92:95], v[172:175], v[202:205], v[92:95]
	v_mfma_f32_16x16x32_bf16 v[84:87], v[164:167], v[210:213], v[84:87]
	v_mfma_f32_16x16x32_bf16 v[76:79], v[172:175], v[210:213], v[76:79]
	v_mfma_f32_16x16x32_bf16 v[72:75], v[164:167], v[222:225], v[72:75]
	v_mfma_f32_16x16x32_bf16 v[68:71], v[172:175], v[222:225], v[68:71]
	s_setprio 0
	s_barrier
; #define PG8_STAGE(bufoff, gbase, voff) do { _Pragma("unroll") for (int _i = 0; _i < 2; ++_i) \
;         __builtin_amdgcn_global_load_lds((const unsigned*)((const char*)(gbase) + (voff)[_i]), (LAS unsigned*)(lds + (bufoff) + ldsw + _i * 8192), 16, 0, 0); } while (0)
; #define PG8_LDA(dst, b, h) do { _Pragma("unroll") for (int m = 0; m < 4; ++m) _Pragma("unroll") for (int k = 0; k < 2; ++k) dst[m][k] = *(const LAS bf16x8*)(lds + PG8_SA(b, h) + aoff + m * 2048 + k * 1024); } while (0)
; #define PG8_MMA(ai, bj, At, Bt) do { __builtin_amdgcn_s_setprio(1); _Pragma("unroll") for (int m = 0; m < 4; ++m) _Pragma("unroll") for (int n = 0; n < 2; ++n) _Pragma("unroll") for (int k = 0; k < 2; ++k) \
;         acc[ai][bj][m][n] = __builtin_amdgcn_mfma_f32_16x16x32_bf16(Bt[n][k], At[m][k], acc[ai][bj][m][n], 0, 0, 0); __builtin_amdgcn_s_setprio(0); } while (0)
; #define PG8_WAIT_V(n) asm volatile("s_waitcnt vmcnt(" #n ")" ::: "memory")
; #define PG8_WAIT_L(n) asm volatile("s_waitcnt lgkmcnt(" #n ")" ::: "memory")
; #define PG8_BAR __builtin_amdgcn_s_barrier()
; #define PG8_SCHED __builtin_amdgcn_sched_barrier(0)
; template <class Epi, class Sched, bool ALIGN_EPI = true, bool SP2 = true>
; __device__ __forceinline__ void gemm_phase(LAS unsigned char* lds, const Gemm g, const Sched& S, const Epi& E) {
;     ...
;             PG8_LDA(At, 1, 1); PG8_STAGE(PG8_SB(1, 0), b3, voffB); PG8_STAGE(PG8_SB(1, 1), b3 + hstepB, voffB); PG8_STAGE(PG8_SA(1, 0), a3, voffA);
;             PG8_WAIT_V(8); PG8_WAIT_L(0); PG8_BAR; PG8_MMA(1, 0, At, B0); PG8_MMA(1, 1, At, B1); PG8_BAR; PG8_SCHED;
;         }
	s_add_i32 s16, s57, s38
	v_lshl_add_u64 v[140:141], v[140:141], 0, s[14:15]
	s_mov_b32 m0, s16
	ds_read_b128 v[186:189], v143 offset:49152
	ds_read_b128 v[190:193], v143 offset:50176
	ds_read_b128 v[198:201], v143 offset:51200
	ds_read_b128 v[202:205], v143 offset:52224
	ds_read_b128 v[206:209], v143 offset:53248
	ds_read_b128 v[210:213], v143 offset:54272
	ds_read_b128 v[218:221], v143 offset:55296
	ds_read_b128 v[222:225], v143 offset:56320
	global_load_lds_dwordx4 v[140:141], off
	s_add_i32 m0, s16, 0x2000
	s_add_u32 s16, s20, 0xb0080
	v_lshl_add_u64 v[140:141], v[176:177], 0, s[14:15]
	s_addc_u32 s17, s21, 0
	s_add_i32 s20, s58, s38
	global_load_lds_dwordx4 v[140:141], off
	s_mov_b32 m0, s20
	s_nop 0
	global_load_lds_dwordx4 v18, s[16:17]
	v_lshl_add_u64 v[140:141], s[16:17], 0, v[16:17]
	s_add_i32 m0, s20, 0x2000
	s_nop 0
	global_load_lds_dwordx4 v[140:141], off
	v_lshl_add_u64 v[140:141], v[178:179], 0, s[14:15]
	s_mov_b32 m0, s8
	s_nop 0
	global_load_lds_dwordx4 v[140:141], off
	v_lshl_add_u64 v[140:141], v[182:183], 0, s[14:15]
	s_mov_b32 m0, s9
	s_nop 0
	global_load_lds_dwordx4 v[140:141], off
	s_waitcnt vmcnt(8)
	s_waitcnt lgkmcnt(0)
	s_barrier
	s_setprio 1
	s_waitcnt lgkmcnt(0)
	v_mfma_f32_16x16x32_bf16 v[64:67], v[144:147], v[186:189], v[64:67]
	v_mfma_f32_16x16x32_bf16 v[60:63], v[152:155], v[186:189], v[60:63]
	v_mfma_f32_16x16x32_bf16 v[56:59], v[144:147], v[198:201], v[56:59]
	v_mfma_f32_16x16x32_bf16 v[48:51], v[152:155], v[198:201], v[48:51]
	v_mfma_f32_16x16x32_bf16 v[40:43], v[144:147], v[206:209], v[40:43]
	v_mfma_f32_16x16x32_bf16 v[32:35], v[152:155], v[206:209], v[32:35]
	v_mfma_f32_16x16x32_bf16 v[24:27], v[144:147], v[218:221], v[24:27]
	v_mfma_f32_16x16x32_bf16 v[12:15], v[152:155], v[218:221], v[12:15]
	v_mfma_f32_16x16x32_bf16 v[64:67], v[148:151], v[190:193], v[64:67]
	v_mfma_f32_16x16x32_bf16 v[60:63], v[156:159], v[190:193], v[60:63]
	v_mfma_f32_16x16x32_bf16 v[56:59], v[148:151], v[202:205], v[56:59]
	v_mfma_f32_16x16x32_bf16 v[48:51], v[156:159], v[202:205], v[48:51]
	v_mfma_f32_16x16x32_bf16 v[40:43], v[148:151], v[210:213], v[40:43]
	v_mfma_f32_16x16x32_bf16 v[32:35], v[156:159], v[210:213], v[32:35]
	v_mfma_f32_16x16x32_bf16 v[24:27], v[148:151], v[222:225], v[24:27]
	v_mfma_f32_16x16x32_bf16 v[12:15], v[156:159], v[222:225], v[12:15]
	s_setprio 0
	s_setprio 1
	v_mfma_f32_16x16x32_bf16 v[52:55], v[160:163], v[186:189], v[52:55]
	v_mfma_f32_16x16x32_bf16 v[44:47], v[168:171], v[186:189], v[44:47]
	v_mfma_f32_16x16x32_bf16 v[36:39], v[160:163], v[198:201], v[36:39]
	v_mfma_f32_16x16x32_bf16 v[28:31], v[168:171], v[198:201], v[28:31]
	v_mfma_f32_16x16x32_bf16 v[20:23], v[160:163], v[206:209], v[20:23]
	v_mfma_f32_16x16x32_bf16 v[8:11], v[168:171], v[206:209], v[8:11]
	v_mfma_f32_16x16x32_bf16 v[4:7], v[160:163], v[218:221], v[4:7]
	v_mfma_f32_16x16x32_bf16 v[0:3], v[168:171], v[218:221], v[0:3]
	v_mfma_f32_16x16x32_bf16 v[52:55], v[164:167], v[190:193], v[52:55]
	v_mfma_f32_16x16x32_bf16 v[44:47], v[172:175], v[190:193], v[44:47]
	v_mfma_f32_16x16x32_bf16 v[36:39], v[164:167], v[202:205], v[36:39]
	v_mfma_f32_16x16x32_bf16 v[28:31], v[172:175], v[202:205], v[28:31]
	v_mfma_f32_16x16x32_bf16 v[20:23], v[164:167], v[210:213], v[20:23]
	v_mfma_f32_16x16x32_bf16 v[8:11], v[172:175], v[210:213], v[8:11]
	v_mfma_f32_16x16x32_bf16 v[4:7], v[164:167], v[222:225], v[4:7]
	v_mfma_f32_16x16x32_bf16 v[0:3], v[172:175], v[222:225], v[0:3]
	s_setprio 0
	s_barrier
	s_add_i32 s56, s56, 2
	s_add_u32 s2, s2, 0x100
	s_addc_u32 s30, s30, 0
	s_cmp_gt_u32 s56, 41
	s_mov_b64 s[16:17], s[18:19]
	s_cbranch_scc0 .LBB0_1229
	s_and_b64 vcc, exec, s[36:37]
	s_cbranch_vccz .LBB0_1232
	s_barrier
